# back-edge rotation: loop-carried scalar and address work hoisted in front of each step barrier in both attention loops (on top of the wait cleanup)
# baseline (speedup 1.0000x reference)
; #define WAIT_BAR(N) asm volatile("s_waitcnt vmcnt(" #N ") lgkmcnt(0)\n\ts_barrier":::"memory")
;   #define RESC() do{ if(resc){ asm volatile("s_waitcnt lgkmcnt(0)":::"memory"); \
;       _Pragma("unroll") for(int d_=0;d_<2;++d_) _Pragma("unroll") for(int r=0;r<16;++r)o[d_][r]*=wsf[crow(r,hi)]; } }while(0)
;   #define ROT() do{sl_prev=sl_cur;sl_cur=sl_next;sl_next=(sl_next==(NSLOT-1)*SLOTB)?0:sl_next+SLOTB;}while(0)
; #define WAIT_BAR(N) asm volatile("s_waitcnt vmcnt(" #N ") lgkmcnt(0)\n\ts_barrier":::"memory")
;   #define RESC() do{ if(resc){ asm volatile("s_waitcnt lgkmcnt(0)":::"memory"); \
;       _Pragma("unroll") for(int d_=0;d_<4;++d_) _Pragma("unroll") for(int r=0;r<16;++r)o[d_][r]*=wsf[crow(r,hi)]; } }while(0)
;   #define ROT() do{sl_prev=sl_cur;sl_cur=sl_next;sl_next=(sl_next==(NSLOT-1)*SLOTB)?0:sl_next+SLOTB;}while(0)
; #define WAIT_BAR(N) asm volatile("s_waitcnt vmcnt(" #N ") lgkmcnt(0)\n\ts_barrier":::"memory")
;   #define RESC() do{ if(resc){ asm volatile("s_waitcnt lgkmcnt(0)":::"memory"); \
;       _Pragma("unroll") for(int d_=0;d_<2;++d_) _Pragma("unroll") for(int r=0;r<16;++r)o[d_][r]*=wsf[crow(r,hi)]; } }while(0)
;   #define ROT() do{sl_prev=sl_cur;sl_cur=sl_next;sl_next=(sl_next==(NSLOT-1)*SLOTB)?0:sl_next+SLOTB;}while(0)
; template<int THRL,bool FIXED> __device__ __forceinline__ void attn_unit(int qb,const bf16*Qp,const unsigned char*__restrict__ K8h,const bf16*__restrict__ Vh,bf16*Op,int PO,char*shm){
;     ...
;   for(;t+5<NT;t+=2){
;     STEP(pB0,pB1,pA0,pA1,t,true,true,true);     WAIT_BAR(3); RESC(); ROT();
;     STEP(pA0,pA1,pB0,pB1,t+1,true,true,true);   WAIT_BAR(3); RESC(); ROT();
.LBB0_543:
	s_add_i32 s22, s10, 0x8000
	s_and_b32 s22, s22, 0x6000
	v_add_u32_e32 v116, s22, v166
	ds_read_b64_tr_b16 v[120:121], v116 offset:24576
	ds_read_b64_tr_b16 v[122:123], v116 offset:25088
	s_add_i32 s23, s10, 0x2000
	v_add_f32_e32 v96, v64, v65
	v_add_f32_e32 v96, v66, v96
	v_add_f32_e32 v96, v67, v96
	v_add_f32_e32 v96, v68, v96
	v_add_f32_e32 v117, v69, v96
	v_cvt_pk_bf16_f32 v148, v64, v65
	v_cvt_pk_bf16_f32 v149, v66, v67
	v_mfma_scale_f32_32x32x64_f8f6f4 v[96:111], v[88:95], v[128:135], v[32:47], v242, v241 op_sel_hi:[0,0,0]
	ds_read_b64_tr_b16 v[64:65], v116 offset:28672
	ds_read_b64_tr_b16 v[66:67], v116 offset:29184
	v_add_f32_e32 v88, v70, v117
	v_add_f32_e32 v88, v71, v88
	v_add_f32_e32 v88, v72, v88
	v_add_f32_e32 v117, v73, v88
	v_mfma_scale_f32_32x32x64_f8f6f4 v[80:95], v[80:87], v[128:135], v[32:47], v242, v241 op_sel_hi:[0,0,0]
	v_cvt_pk_bf16_f32 v150, v68, v69
	v_cvt_pk_bf16_f32 v151, v70, v71
	ds_read_b64_tr_b16 v[68:69], v116 offset:25600
	ds_read_b64_tr_b16 v[70:71], v116 offset:26112
	v_add_f32_e32 v117, v74, v117
	v_add_f32_e32 v117, v75, v117
	v_add_f32_e32 v117, v76, v117
	v_add_f32_e32 v117, v77, v117
	v_cvt_pk_bf16_f32 v144, v72, v73
	v_cvt_pk_bf16_f32 v145, v74, v75
	ds_read_b64_tr_b16 v[72:73], v116 offset:29696
	ds_read_b64_tr_b16 v[74:75], v116 offset:30208
	v_add_f32_e32 v117, v78, v117
	v_add_f32_e32 v117, v79, v117
	v_add_f32_e32 v117, v48, v117
	v_add_f32_e32 v117, v49, v117
	v_cvt_pk_bf16_f32 v146, v76, v77
	v_cvt_pk_bf16_f32 v147, v78, v79
	ds_read_b64_tr_b16 v[76:77], v116 offset:26624
	ds_read_b64_tr_b16 v[78:79], v116 offset:27136
	v_add_f32_e32 v117, v50, v117
	v_add_f32_e32 v117, v51, v117
	v_add_f32_e32 v117, v52, v117
	v_add_f32_e32 v117, v53, v117
	v_cvt_pk_bf16_f32 v140, v48, v49
	v_cvt_pk_bf16_f32 v141, v50, v51
	ds_read_b64_tr_b16 v[124:125], v116 offset:30720
	ds_read_b64_tr_b16 v[126:127], v116 offset:31232
	v_add_f32_e32 v48, v54, v117
	v_add_f32_e32 v48, v55, v48
	v_add_f32_e32 v48, v56, v48
	v_add_f32_e32 v48, v57, v48
	v_cvt_pk_bf16_f32 v142, v52, v53
	v_cvt_pk_bf16_f32 v143, v54, v55
	ds_read_b64_tr_b16 v[168:169], v116 offset:27648
	ds_read_b64_tr_b16 v[170:171], v116 offset:28160
	v_add_f32_e32 v48, v58, v48
	v_add_f32_e32 v48, v59, v48
	v_add_f32_e32 v48, v60, v48
	v_add_f32_e32 v48, v61, v48
	v_cvt_pk_bf16_f32 v136, v56, v57
	v_cvt_pk_bf16_f32 v137, v58, v59
	ds_read_b64_tr_b16 v[172:173], v116 offset:31744
	ds_read_b64_tr_b16 v[174:175], v116 offset:32256
	v_add_f32_e32 v48, v62, v48
	v_add_f32_e32 v48, v63, v48
	v_add_f32_e32 v119, 0, v48
	v_cvt_pk_bf16_f32 v138, v60, v61
	v_cvt_pk_bf16_f32 v139, v62, v63
	v_lshl_add_u64 v[116:117], v[114:115], 0, s[10:11]
	s_add_i32 s50, s50, s29
	s_mov_b32 m0, s50
	v_lshl_add_u64 v[48:49], v[116:117], 0, s[60:61]
	global_load_lds_dwordx4 v[48:49], off
	s_add_i32 s50, s10, 0x6000
	s_and_b32 s50, s50, 0x6000
	s_add_i32 s50, s50, s44
	s_mov_b32 m0, s50
	v_lshl_add_u64 v[48:49], v[112:113], 0, s[36:37]
	global_load_lds_dwordx4 v[48:49], off
	s_waitcnt lgkmcnt(8)
	v_mfma_f32_32x32x16_bf16 v[0:15], v[148:151], v[120:123], v[0:15]
	v_exp_f32_e32 v96, v96
	v_exp_f32_e32 v97, v97
	v_exp_f32_e32 v98, v98
	v_exp_f32_e32 v99, v99
	v_mfma_f32_32x32x16_bf16 v[16:31], v[148:151], v[64:67], v[16:31]
	v_exp_f32_e32 v100, v100
	v_exp_f32_e32 v101, v101
	v_exp_f32_e32 v102, v102
	v_exp_f32_e32 v103, v103
	v_add_u32_e32 v60, s13, v165
	ds_read_b128 v[48:51], v60
	v_mfma_f32_32x32x16_bf16 v[0:15], v[144:147], v[68:71], v[0:15]
	v_exp_f32_e32 v104, v104
	v_exp_f32_e32 v105, v105
	v_exp_f32_e32 v106, v106
	v_exp_f32_e32 v107, v107
	ds_read_b128 v[52:55], v60 offset:1024
	v_mfma_f32_32x32x16_bf16 v[16:31], v[144:147], v[72:75], v[16:31]
	v_exp_f32_e32 v108, v108
	v_exp_f32_e32 v109, v109
	v_exp_f32_e32 v110, v110
	v_exp_f32_e32 v111, v111
	ds_read_b128 v[56:59], v60 offset:512
	s_waitcnt lgkmcnt(3)
	v_mfma_f32_32x32x16_bf16 v[0:15], v[140:143], v[76:79], v[0:15]
	v_exp_f32_e32 v80, v80
	v_exp_f32_e32 v81, v81
	v_exp_f32_e32 v82, v82
	v_exp_f32_e32 v83, v83
	ds_read_b128 v[60:63], v60 offset:1536
	v_mfma_f32_32x32x16_bf16 v[16:31], v[140:143], v[124:127], v[16:31]
	v_exp_f32_e32 v84, v84
	v_exp_f32_e32 v85, v85
	v_exp_f32_e32 v86, v86
	v_exp_f32_e32 v87, v87
	v_mfma_f32_32x32x16_bf16 v[0:15], v[136:139], v[168:171], v[0:15]
	v_exp_f32_e32 v88, v88
	v_exp_f32_e32 v89, v89
	v_exp_f32_e32 v90, v90
	v_exp_f32_e32 v91, v91
	v_mfma_f32_32x32x16_bf16 v[16:31], v[136:139], v[172:175], v[16:31]
	v_exp_f32_e32 v92, v92
	v_exp_f32_e32 v93, v93
	v_exp_f32_e32 v94, v94
	v_exp_f32_e32 v95, v95
	s_add_i32 s50, s13, 0x2000
	s_cmpk_lg_i32 s13, 0x4000
	s_cselect_b32 s50, s50, 0
	s_and_b32 s23, s23, 0x6000
	v_add_u32_e32 v160, s23, v166
	s_waitcnt vmcnt(3) lgkmcnt(0)
	s_barrier
; #define WAIT_BAR(N) asm volatile("s_waitcnt vmcnt(" #N ") lgkmcnt(0)\n\ts_barrier":::"memory")
;   #define RESC() do{ if(resc){ asm volatile("s_waitcnt lgkmcnt(0)":::"memory"); \
;       _Pragma("unroll") for(int d_=0;d_<2;++d_) _Pragma("unroll") for(int r=0;r<16;++r)o[d_][r]*=wsf[crow(r,hi)]; } }while(0)
;   #define ROT() do{sl_prev=sl_cur;sl_cur=sl_next;sl_next=(sl_next==(NSLOT-1)*SLOTB)?0:sl_next+SLOTB;}while(0)
; #define WAIT_BAR(N) asm volatile("s_waitcnt vmcnt(" #N ") lgkmcnt(0)\n\ts_barrier":::"memory")
;   #define RESC() do{ if(resc){ asm volatile("s_waitcnt lgkmcnt(0)":::"memory"); \
;       _Pragma("unroll") for(int d_=0;d_<4;++d_) _Pragma("unroll") for(int r=0;r<16;++r)o[d_][r]*=wsf[crow(r,hi)]; } }while(0)
;   #define ROT() do{sl_prev=sl_cur;sl_cur=sl_next;sl_next=(sl_next==(NSLOT-1)*SLOTB)?0:sl_next+SLOTB;}while(0)
; #define WAIT_BAR(N) asm volatile("s_waitcnt vmcnt(" #N ") lgkmcnt(0)\n\ts_barrier":::"memory")
;   #define RESC() do{ if(resc){ asm volatile("s_waitcnt lgkmcnt(0)":::"memory"); \
;       _Pragma("unroll") for(int d_=0;d_<2;++d_) _Pragma("unroll") for(int r=0;r<16;++r)o[d_][r]*=wsf[crow(r,hi)]; } }while(0)
;   #define ROT() do{sl_prev=sl_cur;sl_cur=sl_next;sl_next=(sl_next==(NSLOT-1)*SLOTB)?0:sl_next+SLOTB;}while(0)
; template<int THRL,bool FIXED> __device__ __forceinline__ void attn_unit(int qb,const bf16*Qp,const unsigned char*__restrict__ K8h,const bf16*__restrict__ Vh,bf16*Op,int PO,char*shm){
;     ...
;   for(;t+5<NT;t+=2){
;     STEP(pB0,pB1,pA0,pA1,t,true,true,true);     WAIT_BAR(3); RESC(); ROT();
;     STEP(pA0,pA1,pB0,pB1,t+1,true,true,true);   WAIT_BAR(3); RESC(); ROT();
	ds_read_b64_tr_b16 v[120:121], v160 offset:24576
	ds_read_b64_tr_b16 v[122:123], v160 offset:25088
	v_add_f32_e32 v64, v96, v97
	v_add_f32_e32 v64, v98, v64
	v_add_f32_e32 v64, v99, v64
	v_add_f32_e32 v64, v100, v64
	v_add_f32_e32 v124, v101, v64
	v_mfma_scale_f32_32x32x64_f8f6f4 v[64:79], v[48:55], v[128:135], v[32:47], v242, v241 op_sel_hi:[0,0,0]
	v_cvt_pk_bf16_f32 v148, v96, v97
	v_cvt_pk_bf16_f32 v149, v98, v99
	ds_read_b64_tr_b16 v[96:97], v160 offset:28672
	ds_read_b64_tr_b16 v[98:99], v160 offset:29184
	v_add_f32_e32 v48, v102, v124
	v_add_f32_e32 v48, v103, v48
	v_add_f32_e32 v48, v104, v48
	v_add_f32_e32 v124, v105, v48
	v_mfma_scale_f32_32x32x64_f8f6f4 v[48:63], v[56:63], v[128:135], v[32:47], v242, v241 op_sel_hi:[0,0,0]
	v_cvt_pk_bf16_f32 v150, v100, v101
	v_cvt_pk_bf16_f32 v151, v102, v103
	ds_read_b64_tr_b16 v[100:101], v160 offset:25600
	ds_read_b64_tr_b16 v[102:103], v160 offset:26112
	v_add_f32_e32 v124, v106, v124
	v_add_f32_e32 v124, v107, v124
	v_add_f32_e32 v124, v108, v124
	v_add_f32_e32 v124, v109, v124
	v_cvt_pk_bf16_f32 v144, v104, v105
	v_cvt_pk_bf16_f32 v145, v106, v107
	ds_read_b64_tr_b16 v[104:105], v160 offset:29696
	ds_read_b64_tr_b16 v[106:107], v160 offset:30208
	v_add_f32_e32 v124, v110, v124
	v_add_f32_e32 v124, v111, v124
	v_add_f32_e32 v124, v80, v124
	v_add_f32_e32 v124, v81, v124
	v_cvt_pk_bf16_f32 v146, v108, v109
	v_cvt_pk_bf16_f32 v147, v110, v111
	ds_read_b64_tr_b16 v[108:109], v160 offset:26624
	ds_read_b64_tr_b16 v[110:111], v160 offset:27136
	v_add_f32_e32 v124, v82, v124
	v_add_f32_e32 v124, v83, v124
	v_add_f32_e32 v124, v84, v124
	v_add_f32_e32 v136, v85, v124
	v_cvt_pk_bf16_f32 v140, v80, v81
	v_cvt_pk_bf16_f32 v141, v82, v83
	ds_read_b64_tr_b16 v[124:125], v160 offset:30720
	ds_read_b64_tr_b16 v[126:127], v160 offset:31232
	v_add_f32_e32 v80, v86, v136
	v_add_f32_e32 v80, v87, v80
	v_add_f32_e32 v80, v88, v80
	v_add_f32_e32 v80, v89, v80
	v_cvt_pk_bf16_f32 v142, v84, v85
	v_cvt_pk_bf16_f32 v143, v86, v87
	ds_read_b64_tr_b16 v[168:169], v160 offset:27648
	ds_read_b64_tr_b16 v[170:171], v160 offset:28160
	v_add_f32_e32 v80, v90, v80
	v_add_f32_e32 v80, v91, v80
	v_add_f32_e32 v80, v92, v80
	v_add_f32_e32 v80, v93, v80
	v_cvt_pk_bf16_f32 v136, v88, v89
	v_cvt_pk_bf16_f32 v137, v90, v91
	ds_read_b64_tr_b16 v[172:173], v160 offset:31744
	ds_read_b64_tr_b16 v[174:175], v160 offset:32256
	v_add_f32_e32 v80, v94, v80
	v_add_f32_e32 v80, v95, v80
	v_add_f32_e32 v160, 0, v80
	v_cvt_pk_bf16_f32 v138, v92, v93
	v_cvt_pk_bf16_f32 v139, v94, v95
	s_add_i32 s13, s13, s29
	s_mov_b32 m0, s13
	v_lshl_add_u64 v[80:81], v[116:117], 0, s[56:57]
	global_load_lds_dwordx4 v[80:81], off
	s_add_i32 s13, s22, s44
	s_mov_b32 m0, s13
	s_nop 0
	global_load_lds_dwordx4 v[112:113], off
	s_waitcnt lgkmcnt(8)
	v_mfma_f32_32x32x16_bf16 v[0:15], v[148:151], v[120:123], v[0:15]
	v_exp_f32_e32 v64, v64
	v_exp_f32_e32 v65, v65
	v_exp_f32_e32 v66, v66
	v_exp_f32_e32 v67, v67
	v_mfma_f32_32x32x16_bf16 v[16:31], v[148:151], v[96:99], v[16:31]
	v_exp_f32_e32 v68, v68
	v_exp_f32_e32 v69, v69
	v_exp_f32_e32 v70, v70
	v_exp_f32_e32 v71, v71
	v_add_u32_e32 v84, s50, v165
	ds_read_b128 v[88:91], v84
	v_mfma_f32_32x32x16_bf16 v[0:15], v[144:147], v[100:103], v[0:15]
	v_exp_f32_e32 v72, v72
	v_exp_f32_e32 v73, v73
	v_exp_f32_e32 v74, v74
	v_exp_f32_e32 v75, v75
	ds_read_b128 v[92:95], v84 offset:1024
	v_mfma_f32_32x32x16_bf16 v[16:31], v[144:147], v[104:107], v[16:31]
	v_exp_f32_e32 v76, v76
	v_exp_f32_e32 v77, v77
	v_exp_f32_e32 v78, v78
	v_exp_f32_e32 v79, v79
	ds_read_b128 v[80:83], v84 offset:512
	s_waitcnt lgkmcnt(3)
	v_mfma_f32_32x32x16_bf16 v[0:15], v[140:143], v[108:111], v[0:15]
	v_exp_f32_e32 v48, v48
	v_exp_f32_e32 v49, v49
	v_exp_f32_e32 v50, v50
	v_exp_f32_e32 v51, v51
	ds_read_b128 v[84:87], v84 offset:1536
	v_mfma_f32_32x32x16_bf16 v[16:31], v[140:143], v[124:127], v[16:31]
	v_exp_f32_e32 v52, v52
	v_exp_f32_e32 v53, v53
	v_exp_f32_e32 v54, v54
	v_exp_f32_e32 v55, v55
	v_mfma_f32_32x32x16_bf16 v[0:15], v[136:139], v[168:171], v[0:15]
	v_exp_f32_e32 v56, v56
	v_exp_f32_e32 v57, v57
	v_exp_f32_e32 v58, v58
	v_exp_f32_e32 v59, v59
	v_mfma_f32_32x32x16_bf16 v[16:31], v[136:139], v[172:175], v[16:31]
	v_exp_f32_e32 v60, v60
	v_exp_f32_e32 v61, v61
	v_exp_f32_e32 v62, v62
	v_exp_f32_e32 v63, v63
	s_add_i32 s13, s50, 0x2000
	s_cmpk_lg_i32 s50, 0x4000
	s_cselect_b32 s13, s13, 0
	s_add_i32 s12, s12, 2
	s_add_u32 s10, s10, 0x4000
	v_add_f32_e32 v96, v118, v119
	s_addc_u32 s11, s11, 0
	v_lshl_add_u64 v[112:113], v[112:113], 0, s[40:41]
	s_cmpk_gt_u32 s12, 0xf8
	v_add_f32_e32 v118, v96, v160
	s_waitcnt vmcnt(3) lgkmcnt(0)
	s_barrier
	s_cbranch_scc0 .LBB0_543
;   #define RESC() do{ if(resc){ asm volatile("s_waitcnt lgkmcnt(0)":::"memory"); \
;       _Pragma("unroll") for(int d_=0;d_<2;++d_) _Pragma("unroll") for(int r=0;r<16;++r)o[d_][r]*=wsf[crow(r,hi)]; } }while(0)
;   #define ROT() do{sl_prev=sl_cur;sl_cur=sl_next;sl_next=(sl_next==(NSLOT-1)*SLOTB)?0:sl_next+SLOTB;}while(0)
;   #define ENDW(tt) do{ if((tt)+3<NT){WAIT_BAR(3);} else if((tt)+2<NT){WAIT_BAR(2);} else {WAIT_BAR(0);} }while(0)
;   #define RESC() do{ if(resc){ asm volatile("s_waitcnt lgkmcnt(0)":::"memory"); \
;       _Pragma("unroll") for(int d_=0;d_<4;++d_) _Pragma("unroll") for(int r=0;r<16;++r)o[d_][r]*=wsf[crow(r,hi)]; } }while(0)
;   #define ROT() do{sl_prev=sl_cur;sl_cur=sl_next;sl_next=(sl_next==(NSLOT-1)*SLOTB)?0:sl_next+SLOTB;}while(0)
;   #define ENDW(tt) do{ if((tt)+3<NT){WAIT_BAR(5);} else if((tt)+2<NT){WAIT_BAR(4);} else {WAIT_BAR(0);} }while(0)
;   #define RESC() do{ if(resc){ asm volatile("s_waitcnt lgkmcnt(0)":::"memory"); \
;       _Pragma("unroll") for(int d_=0;d_<2;++d_) _Pragma("unroll") for(int r=0;r<16;++r)o[d_][r]*=wsf[crow(r,hi)]; } }while(0)
;   #define ROT() do{sl_prev=sl_cur;sl_cur=sl_next;sl_next=(sl_next==(NSLOT-1)*SLOTB)?0:sl_next+SLOTB;}while(0)
;   #define ENDW(tt) do{ if((tt)+3<NT){WAIT_BAR(3);} else if((tt)+2<NT){WAIT_BAR(2);} else {WAIT_BAR(0);} }while(0)
; template<int THRL,bool FIXED> __device__ __forceinline__ void attn_unit(int qb,const bf16*Qp,const unsigned char*__restrict__ K8h,const bf16*__restrict__ Vh,bf16*Op,int PO,char*shm){
;     ...
;   for(;t+1<NT;t+=2){
;     STEP(pB0,pB1,pA0,pA1,t,(t+3<NT),(t+2<NT),(t+1<NT));       ENDW(t);   RESC(); ROT();
;     STEP(pA0,pA1,pB0,pB1,t+1,(t+4<NT),(t+3<NT),(t+2<NT));     ENDW(t+1); RESC(); ROT();
	s_mov_b32 m0, s101
	s_and_b32 s10, s34, 0x3fffffc0
	s_lshl_b32 s10, s10, 2
	s_add_i32 s12, s10, 0
	ds_read_b64_tr_b16 v[112:113], v166 offset:40960
	ds_read_b64_tr_b16 v[114:115], v166 offset:41472
	v_add_f32_e32 v96, v64, v65
	v_add_f32_e32 v96, v66, v96
	v_add_f32_e32 v96, v67, v96
	v_add_f32_e32 v96, v68, v96
	v_add_f32_e32 v116, v69, v96
	v_cvt_pk_bf16_f32 v148, v64, v65
	v_cvt_pk_bf16_f32 v149, v66, v67
	s_waitcnt lgkmcnt(4)
	v_mfma_scale_f32_32x32x64_f8f6f4 v[96:111], v[88:95], v[128:135], v[32:47], v242, v241 op_sel_hi:[0,0,0]
	ds_read_b64_tr_b16 v[64:65], v166 offset:45056
	ds_read_b64_tr_b16 v[66:67], v166 offset:45568
	v_add_f32_e32 v88, v70, v116
	v_add_f32_e32 v88, v71, v88
	v_add_f32_e32 v88, v72, v88
	v_add_f32_e32 v116, v73, v88
	v_cvt_pk_bf16_f32 v150, v68, v69
	v_cvt_pk_bf16_f32 v151, v70, v71
	s_waitcnt lgkmcnt(4)
	v_mfma_scale_f32_32x32x64_f8f6f4 v[80:95], v[80:87], v[128:135], v[32:47], v242, v241 op_sel_hi:[0,0,0]
	ds_read_b64_tr_b16 v[68:69], v166 offset:41984
	ds_read_b64_tr_b16 v[70:71], v166 offset:42496
	v_add_f32_e32 v116, v74, v116
	v_add_f32_e32 v116, v75, v116
	v_add_f32_e32 v116, v76, v116
	v_add_f32_e32 v116, v77, v116
	v_cvt_pk_bf16_f32 v144, v72, v73
	v_cvt_pk_bf16_f32 v145, v74, v75
	ds_read_b64_tr_b16 v[72:73], v166 offset:46080
	ds_read_b64_tr_b16 v[74:75], v166 offset:46592
	v_add_f32_e32 v116, v78, v116
	v_add_f32_e32 v116, v79, v116
	v_add_f32_e32 v116, v48, v116
	v_add_f32_e32 v116, v49, v116
	v_cvt_pk_bf16_f32 v146, v76, v77
	v_cvt_pk_bf16_f32 v147, v78, v79
	ds_read_b64_tr_b16 v[76:77], v166 offset:43008
	ds_read_b64_tr_b16 v[78:79], v166 offset:43520
	v_add_f32_e32 v116, v50, v116
	v_add_f32_e32 v116, v51, v116
	v_add_f32_e32 v116, v52, v116
	v_add_f32_e32 v116, v53, v116
	v_cvt_pk_bf16_f32 v140, v48, v49
	v_cvt_pk_bf16_f32 v141, v50, v51
	ds_read_b64_tr_b16 v[120:121], v166 offset:47104
	ds_read_b64_tr_b16 v[122:123], v166 offset:47616
	v_add_f32_e32 v48, v54, v116
	v_add_f32_e32 v48, v55, v48
	v_add_f32_e32 v48, v56, v48
	v_add_f32_e32 v48, v57, v48
	v_cvt_pk_bf16_f32 v142, v52, v53
	v_cvt_pk_bf16_f32 v143, v54, v55
	ds_read_b64_tr_b16 v[124:125], v166 offset:44032
	ds_read_b64_tr_b16 v[126:127], v166 offset:44544
	v_add_f32_e32 v48, v58, v48
	v_add_f32_e32 v48, v59, v48
	v_add_f32_e32 v48, v60, v48
	v_add_f32_e32 v48, v61, v48
	v_cvt_pk_bf16_f32 v136, v56, v57
	v_cvt_pk_bf16_f32 v137, v58, v59
	ds_read_b64_tr_b16 v[168:169], v166 offset:48128
	ds_read_b64_tr_b16 v[170:171], v166 offset:48640
	v_add_f32_e32 v48, v62, v48
	v_add_f32_e32 v48, v63, v48
	v_add_f32_e32 v48, 0, v48
	v_cvt_pk_bf16_f32 v138, v60, v61
	v_cvt_pk_bf16_f32 v139, v62, v63
	s_mov_b64 s[22:23], 0x1fc000
	v_add_f32_e32 v160, v118, v48
	s_add_i32 s10, s50, s29
	v_lshl_add_u64 v[48:49], v[154:155], 0, s[22:23]
	s_mov_b32 s11, m0
	s_mov_b32 m0, s10
	s_nop 0
	global_load_lds_dwordx4 v[48:49], off
	s_mov_b32 m0, s11
	s_mov_b64 s[10:11], 0x4728000
	s_cmp_lg_u32 0, -1
	v_lshl_add_u64 v[48:49], v[152:153], 0, s[10:11]
	s_cselect_b32 s10, 0, 0
	s_add_i32 s11, s10, s28
	s_add_i32 s22, s11, 0x8000
	s_mov_b32 s23, m0
	s_mov_b32 m0, s22
	s_nop 0
	global_load_lds_dwordx4 v[48:49], off
	s_mov_b32 m0, s23
	s_waitcnt lgkmcnt(14)
	v_mfma_f32_32x32x16_bf16 v[0:15], v[148:151], v[112:115], v[0:15]
	v_exp_f32_e32 v96, v96
	v_exp_f32_e32 v97, v97
	v_exp_f32_e32 v98, v98
	v_exp_f32_e32 v99, v99
	s_waitcnt lgkmcnt(12)
	v_mfma_f32_32x32x16_bf16 v[16:31], v[148:151], v[64:67], v[16:31]
	v_exp_f32_e32 v100, v100
	v_exp_f32_e32 v101, v101
	v_exp_f32_e32 v102, v102
	v_exp_f32_e32 v103, v103
	v_add_u32_e32 v60, s13, v165
	ds_read_b128 v[48:51], v60
	s_waitcnt lgkmcnt(11)
	v_mfma_f32_32x32x16_bf16 v[0:15], v[144:147], v[68:71], v[0:15]
	v_exp_f32_e32 v104, v104
	v_exp_f32_e32 v105, v105
	v_exp_f32_e32 v106, v106
	v_exp_f32_e32 v107, v107
	ds_read_b128 v[52:55], v60 offset:1024
	s_waitcnt lgkmcnt(10)
	v_mfma_f32_32x32x16_bf16 v[16:31], v[144:147], v[72:75], v[16:31]
	v_exp_f32_e32 v108, v108
	v_exp_f32_e32 v109, v109
	v_exp_f32_e32 v110, v110
	v_exp_f32_e32 v111, v111
	ds_read_b128 v[56:59], v60 offset:512
	s_waitcnt lgkmcnt(9)
	v_mfma_f32_32x32x16_bf16 v[0:15], v[140:143], v[76:79], v[0:15]
	v_exp_f32_e32 v80, v80
	v_exp_f32_e32 v81, v81
	v_exp_f32_e32 v82, v82
	v_exp_f32_e32 v83, v83
	ds_read_b128 v[60:63], v60 offset:1536
	s_waitcnt lgkmcnt(8)
	v_mfma_f32_32x32x16_bf16 v[16:31], v[140:143], v[120:123], v[16:31]
	v_exp_f32_e32 v84, v84
	v_exp_f32_e32 v85, v85
	v_exp_f32_e32 v86, v86
	v_exp_f32_e32 v87, v87
	s_waitcnt lgkmcnt(6)
	v_mfma_f32_32x32x16_bf16 v[0:15], v[136:139], v[124:127], v[0:15]
	v_exp_f32_e32 v88, v88
	v_exp_f32_e32 v89, v89
	v_exp_f32_e32 v90, v90
	v_exp_f32_e32 v91, v91
	s_waitcnt lgkmcnt(4)
	v_mfma_f32_32x32x16_bf16 v[16:31], v[136:139], v[168:171], v[16:31]
	v_exp_f32_e32 v92, v92
	v_exp_f32_e32 v93, v93
	v_exp_f32_e32 v94, v94
	v_exp_f32_e32 v95, v95
	s_waitcnt vmcnt(3) lgkmcnt(0)
	s_barrier
;   #define RESC() do{ if(resc){ asm volatile("s_waitcnt lgkmcnt(0)":::"memory"); \
;       _Pragma("unroll") for(int d_=0;d_<2;++d_) _Pragma("unroll") for(int r=0;r<16;++r)o[d_][r]*=wsf[crow(r,hi)]; } }while(0)
;   #define ROT() do{sl_prev=sl_cur;sl_cur=sl_next;sl_next=(sl_next==(NSLOT-1)*SLOTB)?0:sl_next+SLOTB;}while(0)
;   #define ENDW(tt) do{ if((tt)+3<NT){WAIT_BAR(3);} else if((tt)+2<NT){WAIT_BAR(2);} else {WAIT_BAR(0);} }while(0)
;   #define RESC() do{ if(resc){ asm volatile("s_waitcnt lgkmcnt(0)":::"memory"); \
;       _Pragma("unroll") for(int d_=0;d_<4;++d_) _Pragma("unroll") for(int r=0;r<16;++r)o[d_][r]*=wsf[crow(r,hi)]; } }while(0)
;   #define ROT() do{sl_prev=sl_cur;sl_cur=sl_next;sl_next=(sl_next==(NSLOT-1)*SLOTB)?0:sl_next+SLOTB;}while(0)
;   #define ENDW(tt) do{ if((tt)+3<NT){WAIT_BAR(5);} else if((tt)+2<NT){WAIT_BAR(4);} else {WAIT_BAR(0);} }while(0)
;   #define RESC() do{ if(resc){ asm volatile("s_waitcnt lgkmcnt(0)":::"memory"); \
;       _Pragma("unroll") for(int d_=0;d_<2;++d_) _Pragma("unroll") for(int r=0;r<16;++r)o[d_][r]*=wsf[crow(r,hi)]; } }while(0)
;   #define ROT() do{sl_prev=sl_cur;sl_cur=sl_next;sl_next=(sl_next==(NSLOT-1)*SLOTB)?0:sl_next+SLOTB;}while(0)
;   #define ENDW(tt) do{ if((tt)+3<NT){WAIT_BAR(3);} else if((tt)+2<NT){WAIT_BAR(2);} else {WAIT_BAR(0);} }while(0)
; template<int THRL,bool FIXED> __device__ __forceinline__ void attn_unit(int qb,const bf16*Qp,const unsigned char*__restrict__ K8h,const bf16*__restrict__ Vh,bf16*Op,int PO,char*shm){
;     ...
;   for(;t+1<NT;t+=2){
;     STEP(pB0,pB1,pA0,pA1,t,(t+3<NT),(t+2<NT),(t+1<NT));       ENDW(t);   RESC(); ROT();
;     STEP(pA0,pA1,pB0,pB1,t+1,(t+4<NT),(t+3<NT),(t+2<NT));     ENDW(t+1); RESC(); ROT();
	s_add_i32 s22, s13, 0x2000
	s_cmpk_lg_i32 s13, 0x4000
	s_cselect_b32 s22, s22, 0
	ds_read_b64_tr_b16 v[64:65], v166 offset:49152
	ds_read_b64_tr_b16 v[66:67], v166 offset:49664
	v_add_f32_e32 v68, v96, v97
	v_add_f32_e32 v68, v98, v68
	v_add_f32_e32 v68, v99, v68
	v_add_f32_e32 v68, v100, v68
	v_add_f32_e32 v72, v101, v68
	v_cvt_pk_bf16_f32 v148, v96, v97
	v_cvt_pk_bf16_f32 v149, v98, v99
	s_waitcnt lgkmcnt(4)
	v_mfma_scale_f32_32x32x64_f8f6f4 v[112:127], v[48:55], v[128:135], v[32:47], v242, v241 op_sel_hi:[0,0,0]
	ds_read_b64_tr_b16 v[68:69], v166 offset:53248
	ds_read_b64_tr_b16 v[70:71], v166 offset:53760
	v_add_f32_e32 v48, v102, v72
	v_add_f32_e32 v48, v103, v48
	v_add_f32_e32 v48, v104, v48
	v_add_f32_e32 v76, v105, v48
	s_waitcnt lgkmcnt(4)
	v_mfma_scale_f32_32x32x64_f8f6f4 v[48:63], v[56:63], v[128:135], v[32:47], v242, v241 op_sel_hi:[0,0,0]
	v_cvt_pk_bf16_f32 v150, v100, v101
	v_cvt_pk_bf16_f32 v151, v102, v103
	ds_read_b64_tr_b16 v[72:73], v166 offset:50176
	ds_read_b64_tr_b16 v[74:75], v166 offset:50688
	v_add_f32_e32 v76, v106, v76
	v_add_f32_e32 v76, v107, v76
	v_add_f32_e32 v76, v108, v76
	v_add_f32_e32 v96, v109, v76
	v_cvt_pk_bf16_f32 v144, v104, v105
	v_cvt_pk_bf16_f32 v145, v106, v107
	ds_read_b64_tr_b16 v[76:77], v166 offset:54272
	ds_read_b64_tr_b16 v[78:79], v166 offset:54784
	v_add_f32_e32 v96, v110, v96
	v_add_f32_e32 v96, v111, v96
	v_add_f32_e32 v96, v80, v96
	v_add_f32_e32 v100, v81, v96
	v_cvt_pk_bf16_f32 v146, v108, v109
	v_cvt_pk_bf16_f32 v147, v110, v111
	ds_read_b64_tr_b16 v[96:97], v166 offset:51200
	ds_read_b64_tr_b16 v[98:99], v166 offset:51712
	v_add_f32_e32 v100, v82, v100
	v_add_f32_e32 v100, v83, v100
	v_add_f32_e32 v100, v84, v100
	v_add_f32_e32 v100, v85, v100
	v_cvt_pk_bf16_f32 v140, v80, v81
	v_cvt_pk_bf16_f32 v141, v82, v83
	ds_read_b64_tr_b16 v[80:81], v166 offset:55296
	ds_read_b64_tr_b16 v[82:83], v166 offset:55808
	v_add_f32_e32 v100, v86, v100
	v_add_f32_e32 v100, v87, v100
	v_add_f32_e32 v100, v88, v100
	v_add_f32_e32 v100, v89, v100
	v_cvt_pk_bf16_f32 v142, v84, v85
	v_cvt_pk_bf16_f32 v143, v86, v87
	ds_read_b64_tr_b16 v[84:85], v166 offset:52224
	ds_read_b64_tr_b16 v[86:87], v166 offset:52736
	v_add_f32_e32 v100, v90, v100
	v_add_f32_e32 v100, v91, v100
	v_add_f32_e32 v100, v92, v100
	v_add_f32_e32 v100, v93, v100
	v_cvt_pk_bf16_f32 v136, v88, v89
	v_cvt_pk_bf16_f32 v137, v90, v91
	ds_read_b64_tr_b16 v[88:89], v166 offset:56320
	ds_read_b64_tr_b16 v[90:91], v166 offset:56832
	v_add_f32_e32 v100, v94, v100
	v_add_f32_e32 v100, v95, v100
	v_add_f32_e32 v100, 0, v100
	v_cvt_pk_bf16_f32 v138, v92, v93
	v_cvt_pk_bf16_f32 v139, v94, v95
	s_mov_b64 s[50:51], 0x1fe000
	s_add_i32 s13, s13, s29
	v_lshl_add_u64 v[92:93], v[154:155], 0, s[50:51]
	s_mov_b32 s23, m0
	s_mov_b32 m0, s13
	s_nop 0
	global_load_lds_dwordx4 v[92:93], off
	s_mov_b32 m0, s23
	v_lshl_add_u64 v[92:93], v[152:153], 0, s[42:43]
	s_add_i32 s11, s11, 0xa000
	s_mov_b32 s13, m0
	s_mov_b32 m0, s11
	s_nop 0
	global_load_lds_dwordx4 v[92:93], off
	s_mov_b32 m0, s13
	v_add_f32_e32 v160, v160, v100
	s_waitcnt lgkmcnt(14)
	v_mfma_f32_32x32x16_bf16 v[0:15], v[148:151], v[64:67], v[0:15]
	v_exp_f32_e32 v112, v112
	v_exp_f32_e32 v113, v113
	v_exp_f32_e32 v114, v114
	v_exp_f32_e32 v115, v115
	s_waitcnt lgkmcnt(12)
	v_mfma_f32_32x32x16_bf16 v[16:31], v[148:151], v[68:71], v[16:31]
	v_exp_f32_e32 v116, v116
	v_exp_f32_e32 v117, v117
	v_exp_f32_e32 v118, v118
	v_exp_f32_e32 v119, v119
	v_add_u32_e32 v92, s22, v165
	ds_read_b128 v[64:67], v92
	s_waitcnt lgkmcnt(11)
	v_mfma_f32_32x32x16_bf16 v[0:15], v[144:147], v[72:75], v[0:15]
	v_exp_f32_e32 v120, v120
	v_exp_f32_e32 v121, v121
	v_exp_f32_e32 v122, v122
	v_exp_f32_e32 v123, v123
	ds_read_b128 v[68:71], v92 offset:1024
	s_waitcnt lgkmcnt(10)
	v_mfma_f32_32x32x16_bf16 v[16:31], v[144:147], v[76:79], v[16:31]
	v_exp_f32_e32 v124, v124
	v_exp_f32_e32 v125, v125
	v_exp_f32_e32 v126, v126
	v_exp_f32_e32 v127, v127
	ds_read_b128 v[72:75], v92 offset:512
	s_waitcnt lgkmcnt(9)
	v_mfma_f32_32x32x16_bf16 v[0:15], v[140:143], v[96:99], v[0:15]
	v_exp_f32_e32 v48, v48
	v_exp_f32_e32 v49, v49
	v_exp_f32_e32 v50, v50
	v_exp_f32_e32 v51, v51
	ds_read_b128 v[76:79], v92 offset:1536
	s_waitcnt lgkmcnt(8)
	v_mfma_f32_32x32x16_bf16 v[16:31], v[140:143], v[80:83], v[16:31]
	v_exp_f32_e32 v52, v52
	v_exp_f32_e32 v53, v53
	v_exp_f32_e32 v54, v54
	v_exp_f32_e32 v55, v55
	s_waitcnt lgkmcnt(6)
	v_mfma_f32_32x32x16_bf16 v[0:15], v[136:139], v[84:87], v[0:15]
	v_exp_f32_e32 v56, v56
	v_exp_f32_e32 v57, v57
	v_exp_f32_e32 v58, v58
	v_exp_f32_e32 v59, v59
	s_waitcnt lgkmcnt(4)
	v_mfma_f32_32x32x16_bf16 v[16:31], v[136:139], v[88:91], v[16:31]
	v_exp_f32_e32 v60, v60
	v_exp_f32_e32 v61, v61
	v_exp_f32_e32 v62, v62
	v_exp_f32_e32 v63, v63
	s_waitcnt vmcnt(3) lgkmcnt(0)
	s_barrier
;   #define RESC() do{ if(resc){ asm volatile("s_waitcnt lgkmcnt(0)":::"memory"); \
;       _Pragma("unroll") for(int d_=0;d_<2;++d_) _Pragma("unroll") for(int r=0;r<16;++r)o[d_][r]*=wsf[crow(r,hi)]; } }while(0)
;   #define ROT() do{sl_prev=sl_cur;sl_cur=sl_next;sl_next=(sl_next==(NSLOT-1)*SLOTB)?0:sl_next+SLOTB;}while(0)
;   #define ENDW(tt) do{ if((tt)+3<NT){WAIT_BAR(3);} else if((tt)+2<NT){WAIT_BAR(2);} else {WAIT_BAR(0);} }while(0)
;   #define RESC() do{ if(resc){ asm volatile("s_waitcnt lgkmcnt(0)":::"memory"); \
;       _Pragma("unroll") for(int d_=0;d_<4;++d_) _Pragma("unroll") for(int r=0;r<16;++r)o[d_][r]*=wsf[crow(r,hi)]; } }while(0)
;   #define ROT() do{sl_prev=sl_cur;sl_cur=sl_next;sl_next=(sl_next==(NSLOT-1)*SLOTB)?0:sl_next+SLOTB;}while(0)
;   #define ENDW(tt) do{ if((tt)+3<NT){WAIT_BAR(5);} else if((tt)+2<NT){WAIT_BAR(4);} else {WAIT_BAR(0);} }while(0)
;   #define RESC() do{ if(resc){ asm volatile("s_waitcnt lgkmcnt(0)":::"memory"); \
;       _Pragma("unroll") for(int d_=0;d_<2;++d_) _Pragma("unroll") for(int r=0;r<16;++r)o[d_][r]*=wsf[crow(r,hi)]; } }while(0)
;   #define ROT() do{sl_prev=sl_cur;sl_cur=sl_next;sl_next=(sl_next==(NSLOT-1)*SLOTB)?0:sl_next+SLOTB;}while(0)
;   #define ENDW(tt) do{ if((tt)+3<NT){WAIT_BAR(3);} else if((tt)+2<NT){WAIT_BAR(2);} else {WAIT_BAR(0);} }while(0)
; template<int THRL,bool FIXED> __device__ __forceinline__ void attn_unit(int qb,const bf16*Qp,const unsigned char*__restrict__ K8h,const bf16*__restrict__ Vh,bf16*Op,int PO,char*shm){
;     ...
;   for(;t+1<NT;t+=2){
;     STEP(pB0,pB1,pA0,pA1,t,(t+3<NT),(t+2<NT),(t+1<NT));       ENDW(t);   RESC(); ROT();
;     STEP(pA0,pA1,pB0,pB1,t+1,(t+4<NT),(t+3<NT),(t+2<NT));     ENDW(t+1); RESC(); ROT();
	s_add_i32 s11, s22, 0x2000
	s_cmpk_lg_i32 s22, 0x4000
	s_cselect_b32 s11, s11, 0
	ds_read_b64_tr_b16 v[80:81], v166 offset:24576
	ds_read_b64_tr_b16 v[82:83], v166 offset:25088
	v_add_f32_e32 v84, v112, v113
	v_add_f32_e32 v84, v114, v84
	v_add_f32_e32 v84, v115, v84
	v_add_f32_e32 v84, v116, v84
	v_add_f32_e32 v88, v117, v84
	v_cvt_pk_bf16_f32 v148, v112, v113
	v_cvt_pk_bf16_f32 v149, v114, v115
	s_waitcnt lgkmcnt(4)
	v_mfma_scale_f32_32x32x64_f8f6f4 v[96:111], v[64:71], v[128:135], v[32:47], v242, v241 op_sel_hi:[0,0,0]
	ds_read_b64_tr_b16 v[84:85], v166 offset:28672
	ds_read_b64_tr_b16 v[86:87], v166 offset:29184
	v_add_f32_e32 v64, v118, v88
	v_add_f32_e32 v64, v119, v64
	v_add_f32_e32 v64, v120, v64
	v_add_f32_e32 v92, v121, v64
	v_cvt_pk_bf16_f32 v150, v116, v117
	v_cvt_pk_bf16_f32 v151, v118, v119
	s_waitcnt lgkmcnt(4)
	v_mfma_scale_f32_32x32x64_f8f6f4 v[64:79], v[72:79], v[128:135], v[32:47], v242, v241 op_sel_hi:[0,0,0]
	ds_read_b64_tr_b16 v[88:89], v166 offset:25600
	ds_read_b64_tr_b16 v[90:91], v166 offset:26112
	v_add_f32_e32 v92, v122, v92
	v_add_f32_e32 v92, v123, v92
	v_add_f32_e32 v92, v124, v92
	v_add_f32_e32 v112, v125, v92
	v_cvt_pk_bf16_f32 v144, v120, v121
	v_cvt_pk_bf16_f32 v145, v122, v123
	ds_read_b64_tr_b16 v[92:93], v166 offset:29696
	ds_read_b64_tr_b16 v[94:95], v166 offset:30208
	v_add_f32_e32 v112, v126, v112
	v_add_f32_e32 v112, v127, v112
	v_add_f32_e32 v112, v48, v112
	v_add_f32_e32 v116, v49, v112
	v_cvt_pk_bf16_f32 v146, v124, v125
	v_cvt_pk_bf16_f32 v147, v126, v127
	ds_read_b64_tr_b16 v[112:113], v166 offset:26624
	ds_read_b64_tr_b16 v[114:115], v166 offset:27136
	v_add_f32_e32 v116, v50, v116
	v_add_f32_e32 v116, v51, v116
	v_add_f32_e32 v116, v52, v116
	v_add_f32_e32 v120, v53, v116
	v_cvt_pk_bf16_f32 v140, v48, v49
	v_cvt_pk_bf16_f32 v141, v50, v51
	ds_read_b64_tr_b16 v[116:117], v166 offset:30720
	ds_read_b64_tr_b16 v[118:119], v166 offset:31232
	v_add_f32_e32 v48, v54, v120
	v_add_f32_e32 v48, v55, v48
	v_add_f32_e32 v48, v56, v48
	v_add_f32_e32 v48, v57, v48
	v_cvt_pk_bf16_f32 v142, v52, v53
	v_cvt_pk_bf16_f32 v143, v54, v55
	ds_read_b64_tr_b16 v[120:121], v166 offset:27648
	ds_read_b64_tr_b16 v[122:123], v166 offset:28160
	v_add_f32_e32 v48, v58, v48
	v_add_f32_e32 v48, v59, v48
	v_add_f32_e32 v48, v60, v48
	v_add_f32_e32 v48, v61, v48
	v_cvt_pk_bf16_f32 v136, v56, v57
	v_cvt_pk_bf16_f32 v137, v58, v59
	ds_read_b64_tr_b16 v[124:125], v166 offset:31744
	ds_read_b64_tr_b16 v[126:127], v166 offset:32256
	v_add_f32_e32 v48, v62, v48
	v_add_f32_e32 v48, v63, v48
	v_add_f32_e32 v48, 0, v48
	v_cvt_pk_bf16_f32 v138, v60, v61
	v_cvt_pk_bf16_f32 v139, v62, v63
	s_add_i32 s10, s10, 0xc000
	v_add_f32_e32 v160, v160, v48
	v_lshl_add_u64 v[48:49], v[152:153], 0, s[46:47]
	s_add_i32 s28, s28, s10
	s_mov_b32 s13, m0
	s_mov_b32 m0, s28
	s_nop 0
	global_load_lds_dwordx4 v[48:49], off
	s_mov_b32 m0, s13
	s_waitcnt lgkmcnt(14)
	v_mfma_f32_32x32x16_bf16 v[0:15], v[148:151], v[80:83], v[0:15]
	v_exp_f32_e32 v96, v96
	v_exp_f32_e32 v97, v97
	v_exp_f32_e32 v98, v98
	v_exp_f32_e32 v99, v99
	s_waitcnt lgkmcnt(12)
	v_mfma_f32_32x32x16_bf16 v[16:31], v[148:151], v[84:87], v[16:31]
	v_exp_f32_e32 v100, v100
	v_exp_f32_e32 v101, v101
	v_exp_f32_e32 v102, v102
	v_exp_f32_e32 v103, v103
	v_add_u32_e32 v60, s11, v165
	ds_read_b128 v[48:51], v60
	s_waitcnt lgkmcnt(11)
	v_mfma_f32_32x32x16_bf16 v[0:15], v[144:147], v[88:91], v[0:15]
	v_exp_f32_e32 v104, v104
	v_exp_f32_e32 v105, v105
	v_exp_f32_e32 v106, v106
	v_exp_f32_e32 v107, v107
	ds_read_b128 v[52:55], v60 offset:1024
	s_waitcnt lgkmcnt(10)
	v_mfma_f32_32x32x16_bf16 v[16:31], v[144:147], v[92:95], v[16:31]
	v_exp_f32_e32 v108, v108
	v_exp_f32_e32 v109, v109
	v_exp_f32_e32 v110, v110
	v_exp_f32_e32 v111, v111
	ds_read_b128 v[56:59], v60 offset:512
	s_waitcnt lgkmcnt(9)
	v_mfma_f32_32x32x16_bf16 v[0:15], v[140:143], v[112:115], v[0:15]
	v_exp_f32_e32 v64, v64
	v_exp_f32_e32 v65, v65
	v_exp_f32_e32 v66, v66
	v_exp_f32_e32 v67, v67
	ds_read_b128 v[60:63], v60 offset:1536
	s_waitcnt lgkmcnt(8)
	v_mfma_f32_32x32x16_bf16 v[16:31], v[140:143], v[116:119], v[16:31]
	v_exp_f32_e32 v68, v68
	v_exp_f32_e32 v69, v69
	v_exp_f32_e32 v70, v70
	v_exp_f32_e32 v71, v71
	s_waitcnt lgkmcnt(6)
	v_mfma_f32_32x32x16_bf16 v[0:15], v[136:139], v[120:123], v[0:15]
	v_exp_f32_e32 v72, v72
	v_exp_f32_e32 v73, v73
	v_exp_f32_e32 v74, v74
	v_exp_f32_e32 v75, v75
	s_waitcnt lgkmcnt(4)
	v_mfma_f32_32x32x16_bf16 v[16:31], v[136:139], v[124:127], v[16:31]
	v_exp_f32_e32 v76, v76
	v_exp_f32_e32 v77, v77
	v_exp_f32_e32 v78, v78
	v_exp_f32_e32 v79, v79
	s_waitcnt vmcnt(2) lgkmcnt(0)
	s_barrier
;   #define RESC() do{ if(resc){ asm volatile("s_waitcnt lgkmcnt(0)":::"memory"); \
;       _Pragma("unroll") for(int d_=0;d_<2;++d_) _Pragma("unroll") for(int r=0;r<16;++r)o[d_][r]*=wsf[crow(r,hi)]; } }while(0)
;   #define ROT() do{sl_prev=sl_cur;sl_cur=sl_next;sl_next=(sl_next==(NSLOT-1)*SLOTB)?0:sl_next+SLOTB;}while(0)
;   #define ENDW(tt) do{ if((tt)+3<NT){WAIT_BAR(3);} else if((tt)+2<NT){WAIT_BAR(2);} else {WAIT_BAR(0);} }while(0)
;   #define RESC() do{ if(resc){ asm volatile("s_waitcnt lgkmcnt(0)":::"memory"); \
;       _Pragma("unroll") for(int d_=0;d_<4;++d_) _Pragma("unroll") for(int r=0;r<16;++r)o[d_][r]*=wsf[crow(r,hi)]; } }while(0)
;   #define ROT() do{sl_prev=sl_cur;sl_cur=sl_next;sl_next=(sl_next==(NSLOT-1)*SLOTB)?0:sl_next+SLOTB;}while(0)
;   #define ENDW(tt) do{ if((tt)+3<NT){WAIT_BAR(5);} else if((tt)+2<NT){WAIT_BAR(4);} else {WAIT_BAR(0);} }while(0)
;   #define RESC() do{ if(resc){ asm volatile("s_waitcnt lgkmcnt(0)":::"memory"); \
;       _Pragma("unroll") for(int d_=0;d_<2;++d_) _Pragma("unroll") for(int r=0;r<16;++r)o[d_][r]*=wsf[crow(r,hi)]; } }while(0)
;   #define ROT() do{sl_prev=sl_cur;sl_cur=sl_next;sl_next=(sl_next==(NSLOT-1)*SLOTB)?0:sl_next+SLOTB;}while(0)
;   #define ENDW(tt) do{ if((tt)+3<NT){WAIT_BAR(3);} else if((tt)+2<NT){WAIT_BAR(2);} else {WAIT_BAR(0);} }while(0)
; template<int THRL,bool FIXED> __device__ __forceinline__ void attn_unit(int qb,const bf16*Qp,const unsigned char*__restrict__ K8h,const bf16*__restrict__ Vh,bf16*Op,int PO,char*shm){
;     ...
;   for(;t+1<NT;t+=2){
;     STEP(pB0,pB1,pA0,pA1,t,(t+3<NT),(t+2<NT),(t+1<NT));       ENDW(t);   RESC(); ROT();
;     STEP(pA0,pA1,pB0,pB1,t+1,(t+4<NT),(t+3<NT),(t+2<NT));     ENDW(t+1); RESC(); ROT();
	s_add_i32 s13, s11, 0x2000
	s_cmpk_lg_i32 s11, 0x4000
	s_cselect_b32 s11, s13, 0
	ds_read_b64_tr_b16 v[112:113], v166 offset:32768
	ds_read_b64_tr_b16 v[114:115], v166 offset:33280
	v_add_f32_e32 v80, v96, v97
	v_add_f32_e32 v80, v98, v80
	v_add_f32_e32 v80, v99, v80
	v_add_f32_e32 v80, v100, v80
	v_add_f32_e32 v116, v101, v80
	v_cvt_pk_bf16_f32 v148, v96, v97
	v_cvt_pk_bf16_f32 v149, v98, v99
	s_waitcnt lgkmcnt(4)
	v_mfma_scale_f32_32x32x64_f8f6f4 v[80:95], v[48:55], v[128:135], v[32:47], v242, v241 op_sel_hi:[0,0,0]
	ds_read_b64_tr_b16 v[96:97], v166 offset:36864
	ds_read_b64_tr_b16 v[98:99], v166 offset:37376
	v_add_f32_e32 v48, v102, v116
	v_add_f32_e32 v48, v103, v48
	v_add_f32_e32 v48, v104, v48
	v_add_f32_e32 v116, v105, v48
	s_waitcnt lgkmcnt(4)
	v_mfma_scale_f32_32x32x64_f8f6f4 v[48:63], v[56:63], v[128:135], v[32:47], v242, v241 op_sel_hi:[0,0,0]
	v_cvt_pk_bf16_f32 v150, v100, v101
	v_cvt_pk_bf16_f32 v151, v102, v103
	ds_read_b64_tr_b16 v[100:101], v166 offset:33792
	ds_read_b64_tr_b16 v[102:103], v166 offset:34304
	v_add_f32_e32 v116, v106, v116
	v_add_f32_e32 v116, v107, v116
	v_add_f32_e32 v116, v108, v116
	v_add_f32_e32 v120, v109, v116
	v_cvt_pk_bf16_f32 v144, v104, v105
	v_cvt_pk_bf16_f32 v145, v106, v107
	ds_read_b64_tr_b16 v[116:117], v166 offset:37888
	ds_read_b64_tr_b16 v[118:119], v166 offset:38400
	v_add_f32_e32 v104, v110, v120
	v_add_f32_e32 v104, v111, v104
	v_add_f32_e32 v104, v64, v104
	v_add_f32_e32 v104, v65, v104
	v_cvt_pk_bf16_f32 v146, v108, v109
	v_cvt_pk_bf16_f32 v147, v110, v111
	ds_read_b64_tr_b16 v[120:121], v166 offset:34816
	ds_read_b64_tr_b16 v[122:123], v166 offset:35328
	v_add_f32_e32 v104, v66, v104
	v_add_f32_e32 v104, v67, v104
	v_add_f32_e32 v104, v68, v104
	v_add_f32_e32 v104, v69, v104
	v_cvt_pk_bf16_f32 v140, v64, v65
	v_cvt_pk_bf16_f32 v141, v66, v67
	ds_read_b64_tr_b16 v[124:125], v166 offset:38912
	ds_read_b64_tr_b16 v[126:127], v166 offset:39424
	v_add_f32_e32 v64, v70, v104
	v_add_f32_e32 v64, v71, v64
	v_add_f32_e32 v64, v72, v64
	v_add_f32_e32 v64, v73, v64
	v_cvt_pk_bf16_f32 v142, v68, v69
	v_cvt_pk_bf16_f32 v143, v70, v71
	ds_read_b64_tr_b16 v[152:153], v166 offset:35840
	ds_read_b64_tr_b16 v[154:155], v166 offset:36352
	v_add_f32_e32 v64, v74, v64
	v_add_f32_e32 v64, v75, v64
	v_add_f32_e32 v64, v76, v64
	v_add_f32_e32 v64, v77, v64
	v_cvt_pk_bf16_f32 v136, v72, v73
	v_cvt_pk_bf16_f32 v137, v74, v75
	ds_read_b64_tr_b16 v[72:73], v166 offset:39936
	ds_read_b64_tr_b16 v[74:75], v166 offset:40448
	v_add_f32_e32 v64, v78, v64
	v_add_f32_e32 v64, v79, v64
	v_add_f32_e32 v64, 0, v64
	v_cvt_pk_bf16_f32 v138, v76, v77
	v_cvt_pk_bf16_f32 v139, v78, v79
	s_nop 0
	v_add_f32_e32 v104, v160, v64
	s_waitcnt lgkmcnt(14)
	v_mfma_f32_32x32x16_bf16 v[0:15], v[148:151], v[112:115], v[0:15]
	v_exp_f32_e32 v80, v80
	v_exp_f32_e32 v81, v81
	v_exp_f32_e32 v82, v82
	v_exp_f32_e32 v83, v83
	s_waitcnt lgkmcnt(12)
	v_mfma_f32_32x32x16_bf16 v[16:31], v[148:151], v[96:99], v[16:31]
	v_exp_f32_e32 v84, v84
	v_exp_f32_e32 v85, v85
	v_exp_f32_e32 v86, v86
	v_exp_f32_e32 v87, v87
	v_add_u32_e32 v76, s11, v165
	ds_read_b128 v[64:67], v76
	s_waitcnt lgkmcnt(11)
	v_mfma_f32_32x32x16_bf16 v[0:15], v[144:147], v[100:103], v[0:15]
	v_exp_f32_e32 v88, v88
	v_exp_f32_e32 v89, v89
	v_exp_f32_e32 v90, v90
	v_exp_f32_e32 v91, v91
	ds_read_b128 v[68:71], v76 offset:1024
	s_waitcnt lgkmcnt(10)
	v_mfma_f32_32x32x16_bf16 v[16:31], v[144:147], v[116:119], v[16:31]
	v_exp_f32_e32 v92, v92
	v_exp_f32_e32 v93, v93
	v_exp_f32_e32 v94, v94
	v_exp_f32_e32 v95, v95
	ds_read_b128 v[106:109], v76 offset:512
	s_waitcnt lgkmcnt(9)
	v_mfma_f32_32x32x16_bf16 v[0:15], v[140:143], v[120:123], v[0:15]
	v_exp_f32_e32 v48, v48
	v_exp_f32_e32 v49, v49
	v_exp_f32_e32 v50, v50
	v_exp_f32_e32 v51, v51
	ds_read_b128 v[110:113], v76 offset:1536
	s_waitcnt lgkmcnt(8)
	v_mfma_f32_32x32x16_bf16 v[16:31], v[140:143], v[124:127], v[16:31]
	v_exp_f32_e32 v52, v52
	v_exp_f32_e32 v53, v53
	v_exp_f32_e32 v54, v54
	v_exp_f32_e32 v55, v55
	s_waitcnt lgkmcnt(6)
	v_mfma_f32_32x32x16_bf16 v[0:15], v[136:139], v[152:155], v[0:15]
	v_exp_f32_e32 v56, v56
	v_exp_f32_e32 v57, v57
	v_exp_f32_e32 v58, v58
	v_exp_f32_e32 v59, v59
	s_waitcnt lgkmcnt(4)
	v_mfma_f32_32x32x16_bf16 v[16:31], v[136:139], v[72:75], v[16:31]
	v_exp_f32_e32 v60, v60
	v_exp_f32_e32 v61, v61
	v_exp_f32_e32 v62, v62
	v_exp_f32_e32 v63, v63
	s_waitcnt vmcnt(0) lgkmcnt(0)
	s_barrier
; #define SBAR() __builtin_amdgcn_sched_barrier(0)
;   #define RESC() do{ if(resc){ asm volatile("s_waitcnt lgkmcnt(0)":::"memory"); \
;       _Pragma("unroll") for(int d_=0;d_<2;++d_) _Pragma("unroll") for(int r=0;r<16;++r)o[d_][r]*=wsf[crow(r,hi)]; } }while(0)
;   #define PKW(P,B) cvtpk_s(P[B],P[B+1])
; #define SBAR() __builtin_amdgcn_sched_barrier(0)
;   #define RESC() do{ if(resc){ asm volatile("s_waitcnt lgkmcnt(0)":::"memory"); \
;       _Pragma("unroll") for(int d_=0;d_<4;++d_) _Pragma("unroll") for(int r=0;r<16;++r)o[d_][r]*=wsf[crow(r,hi)]; } }while(0)
;   #define PKW(P,B) cvtpk_s(P[B],P[B+1])
; #define SBAR() __builtin_amdgcn_sched_barrier(0)
;   #define PKW(P,B) cvtpk_s(P[B],P[B+1])
; __device__ __forceinline__ void pv(f32x16*o,int vb,bf16x8 pa0,bf16x8 pa1,bf16x8 pa2,bf16x8 pa3){
;   #pragma unroll
;   for(int d0=0;d0<4;++d0){s16x4 lo[4],hi[4];
;     #pragma unroll
;     for(int ks=0;ks<4;++ks){
;       asm volatile("ds_read_b64_tr_b16 %0,%1 offset:%c2":"=&v"(lo[ks]):"v"(vb),"i"(d0*4096+ks*1024):"memory");
;       asm volatile("ds_read_b64_tr_b16 %0,%1 offset:%c2":"=&v"(hi[ks]):"v"(vb),"i"(d0*4096+ks*1024+512):"memory");}
;     asm volatile("s_waitcnt lgkmcnt(0)":::"memory");SBAR();
;     ...
;     o[d0]=__builtin_amdgcn_mfma_f32_32x32x16_bf16(pa0,PK(0),o[d0],0,0,0);
;     o[d0]=__builtin_amdgcn_mfma_f32_32x32x16_bf16(pa1,PK(1),o[d0],0,0,0);
;     o[d0]=__builtin_amdgcn_mfma_f32_32x32x16_bf16(pa2,PK(2),o[d0],0,0,0);
;     o[d0]=__builtin_amdgcn_mfma_f32_32x32x16_bf16(pa3,PK(3),o[d0],0,0,0);
;     ...
;   }
; template<int THRL,bool FIXED> __device__ __forceinline__ void attn_unit(int qb,const bf16*Qp,const unsigned char*__restrict__ K8h,const bf16*__restrict__ Vh,bf16*Op,int PO,char*shm){
;     ...
;   STEP(pB0,pB1,pA0,pA1,NT-1,false,false,false); RESC();
;   { float sacc=pB0[0]+pB0[1]; _Pragma("unroll") for(int r=2;r<16;++r)sacc+=pB0[r]; _Pragma("unroll") for(int r=0;r<16;++r)sacc+=pB1[r]; l_reg+=sacc;
;     pw0=(u32x4){PKW(pB0,0),PKW(pB0,2),PKW(pB0,4),PKW(pB0,6)};pw1=(u32x4){PKW(pB0,8),PKW(pB0,10),PKW(pB0,12),PKW(pB0,14)};pw2=(u32x4){PKW(pB1,0),PKW(pB1,2),PKW(pB1,4),PKW(pB1,6)};pw3=(u32x4){PKW(pB1,8),PKW(pB1,10),PKW(pB1,12),PKW(pB1,14)};
;     SBAR(); pv(o,vb0+VSL(NT-1),PAF(0),PAF(1),PAF(2),PAF(3)); }
;     ...
;   {auto rr=__builtin_amdgcn_permlane32_swap(__float_as_uint(l_reg),__float_as_uint(l_reg),false,false);l_reg=__uint_as_float(rr[0])+__uint_as_float(rr[1]);}
	ds_read_b64_tr_b16 v[96:97], v166 offset:40960
	ds_read_b64_tr_b16 v[98:99], v166 offset:41472
	v_add_f32_e32 v72, v80, v81
	v_add_f32_e32 v72, v82, v72
	v_add_f32_e32 v72, v83, v72
	v_add_f32_e32 v72, v84, v72
	v_add_f32_e32 v100, v85, v72
	v_cvt_pk_bf16_f32 v148, v80, v81
	v_cvt_pk_bf16_f32 v149, v82, v83
	s_waitcnt lgkmcnt(4)
	v_mfma_scale_f32_32x32x64_f8f6f4 v[64:79], v[64:71], v[128:135], v[32:47], v242, v241 op_sel_hi:[0,0,0]
	ds_read_b64_tr_b16 v[80:81], v166 offset:45056
	ds_read_b64_tr_b16 v[82:83], v166 offset:45568
	s_waitcnt lgkmcnt(4)
	v_mfma_scale_f32_32x32x64_f8f6f4 v[32:47], v[106:113], v[128:135], v[32:47], v242, v241 op_sel_hi:[0,0,0]
	v_add_f32_e32 v100, v86, v100
	v_add_f32_e32 v100, v87, v100
	v_add_f32_e32 v100, v88, v100
	v_add_f32_e32 v105, v89, v100
	v_cvt_pk_bf16_f32 v150, v84, v85
	v_cvt_pk_bf16_f32 v151, v86, v87
	ds_read_b64_tr_b16 v[100:101], v166 offset:41984
	ds_read_b64_tr_b16 v[102:103], v166 offset:42496
	v_add_f32_e32 v84, v90, v105
	v_add_f32_e32 v84, v91, v84
	v_add_f32_e32 v84, v92, v84
	v_add_f32_e32 v105, v93, v84
	v_cvt_pk_bf16_f32 v144, v88, v89
	v_cvt_pk_bf16_f32 v145, v90, v91
	ds_read_b64_tr_b16 v[84:85], v166 offset:46080
	ds_read_b64_tr_b16 v[86:87], v166 offset:46592
	v_add_f32_e32 v88, v94, v105
	v_add_f32_e32 v88, v95, v88
	v_add_f32_e32 v88, v48, v88
	v_add_f32_e32 v105, v49, v88
	v_cvt_pk_bf16_f32 v146, v92, v93
	v_cvt_pk_bf16_f32 v147, v94, v95
	ds_read_b64_tr_b16 v[88:89], v166 offset:43008
	ds_read_b64_tr_b16 v[90:91], v166 offset:43520
	v_add_f32_e32 v92, v50, v105
	v_add_f32_e32 v92, v51, v92
	v_add_f32_e32 v92, v52, v92
	v_add_f32_e32 v92, v53, v92
	v_cvt_pk_bf16_f32 v140, v48, v49
	v_cvt_pk_bf16_f32 v141, v50, v51
	ds_read_b64_tr_b16 v[48:49], v166 offset:47104
	ds_read_b64_tr_b16 v[50:51], v166 offset:47616
	v_add_f32_e32 v92, v54, v92
	v_add_f32_e32 v92, v55, v92
	v_add_f32_e32 v92, v56, v92
	v_add_f32_e32 v105, v57, v92
	v_cvt_pk_bf16_f32 v142, v52, v53
	v_cvt_pk_bf16_f32 v143, v54, v55
	ds_read_b64_tr_b16 v[92:93], v166 offset:44032
	ds_read_b64_tr_b16 v[94:95], v166 offset:44544
	v_add_f32_e32 v52, v58, v105
	v_add_f32_e32 v52, v59, v52
	v_add_f32_e32 v52, v60, v52
	v_add_f32_e32 v105, v61, v52
	v_cvt_pk_bf16_f32 v136, v56, v57
	v_cvt_pk_bf16_f32 v137, v58, v59
	ds_read_b64_tr_b16 v[52:53], v166 offset:48128
	ds_read_b64_tr_b16 v[54:55], v166 offset:48640
	v_add_f32_e32 v56, v62, v105
	v_add_f32_e32 v56, v63, v56
	v_add_f32_e32 v56, 0, v56
	v_cvt_pk_bf16_f32 v138, v60, v61
	v_cvt_pk_bf16_f32 v139, v62, v63
	v_exp_f32_e32 v64, v64
	v_exp_f32_e32 v65, v65
	v_exp_f32_e32 v66, v66
	v_exp_f32_e32 v67, v67
	s_nop 0
	v_exp_f32_e32 v68, v68
	v_exp_f32_e32 v69, v69
	v_exp_f32_e32 v70, v70
	v_exp_f32_e32 v71, v71
	s_nop 0
	v_exp_f32_e32 v72, v72
	v_exp_f32_e32 v73, v73
	v_exp_f32_e32 v74, v74
	v_exp_f32_e32 v75, v75
	s_nop 0
	v_exp_f32_e32 v76, v76
	v_exp_f32_e32 v77, v77
	v_exp_f32_e32 v78, v78
	v_exp_f32_e32 v79, v79
	v_exp_f32_e32 v32, v32
	v_exp_f32_e32 v33, v33
	v_exp_f32_e32 v34, v34
	v_exp_f32_e32 v35, v35
	s_nop 0
	v_exp_f32_e32 v36, v36
	v_exp_f32_e32 v37, v37
	v_exp_f32_e32 v38, v38
	v_exp_f32_e32 v39, v39
	s_nop 0
	v_exp_f32_e32 v40, v40
	v_exp_f32_e32 v41, v41
	v_exp_f32_e32 v42, v42
	v_exp_f32_e32 v43, v43
	s_nop 0
	v_exp_f32_e32 v44, v44
	v_exp_f32_e32 v45, v45
	v_exp_f32_e32 v46, v46
	v_exp_f32_e32 v47, v47
	s_waitcnt lgkmcnt(14)
	v_mfma_f32_32x32x16_bf16 v[0:15], v[148:151], v[96:99], v[0:15]
	v_add_f32_e32 v57, v64, v65
	v_add_f32_e32 v57, v66, v57
	v_add_f32_e32 v57, v67, v57
	v_add_f32_e32 v57, v68, v57
	v_add_f32_e32 v57, v69, v57
	v_add_f32_e32 v57, v70, v57
	v_add_f32_e32 v57, v71, v57
	s_waitcnt lgkmcnt(12)
	v_mfma_f32_32x32x16_bf16 v[16:31], v[148:151], v[80:83], v[16:31]
	v_add_f32_e32 v57, v72, v57
	v_add_f32_e32 v57, v73, v57
	v_add_f32_e32 v57, v74, v57
	v_add_f32_e32 v57, v75, v57
	v_add_f32_e32 v57, v76, v57
	v_add_f32_e32 v57, v77, v57
	v_add_f32_e32 v57, v78, v57
	s_waitcnt lgkmcnt(10)
	v_mfma_f32_32x32x16_bf16 v[0:15], v[144:147], v[100:103], v[0:15]
	v_add_f32_e32 v57, v79, v57
	v_add_f32_e32 v57, v32, v57
	v_add_f32_e32 v57, v33, v57
	v_add_f32_e32 v57, v34, v57
	v_add_f32_e32 v57, v35, v57
	v_add_f32_e32 v57, v36, v57
	v_add_f32_e32 v57, v37, v57
	s_waitcnt lgkmcnt(8)
	v_mfma_f32_32x32x16_bf16 v[16:31], v[144:147], v[84:87], v[16:31]
	v_add_f32_e32 v57, v38, v57
	v_add_f32_e32 v57, v39, v57
	v_add_f32_e32 v57, v40, v57
	v_add_f32_e32 v57, v41, v57
	v_add_f32_e32 v57, v42, v57
	v_add_f32_e32 v57, v43, v57
	v_add_f32_e32 v57, v44, v57
	s_waitcnt lgkmcnt(6)
	v_mfma_f32_32x32x16_bf16 v[0:15], v[140:143], v[88:91], v[0:15]
	v_add_f32_e32 v57, v45, v57
	v_add_f32_e32 v57, v46, v57
	v_add_f32_e32 v57, v47, v57
	v_add_f32_e32 v56, v104, v56
	v_add_f32_e32 v56, v56, v57
	v_cvt_pk_bf16_f32 v32, v32, v33
	v_cvt_pk_bf16_f32 v58, v64, v65
	s_waitcnt lgkmcnt(4)
	v_mfma_f32_32x32x16_bf16 v[16:31], v[140:143], v[48:51], v[16:31]
	v_cvt_pk_bf16_f32 v59, v66, v67
	v_cvt_pk_bf16_f32 v60, v68, v69
	v_cvt_pk_bf16_f32 v61, v70, v71
	v_cvt_pk_bf16_f32 v62, v72, v73
	v_cvt_pk_bf16_f32 v63, v74, v75
	v_cvt_pk_bf16_f32 v64, v76, v77
	v_cvt_pk_bf16_f32 v65, v78, v79
	s_waitcnt lgkmcnt(2)
	v_mfma_f32_32x32x16_bf16 v[0:15], v[136:139], v[92:95], v[0:15]
	v_cvt_pk_bf16_f32 v33, v34, v35
	v_cvt_pk_bf16_f32 v34, v36, v37
	v_cvt_pk_bf16_f32 v35, v38, v39
	v_cvt_pk_bf16_f32 v36, v40, v41
	v_cvt_pk_bf16_f32 v37, v42, v43
	v_cvt_pk_bf16_f32 v38, v44, v45
	v_cvt_pk_bf16_f32 v39, v46, v47
	s_waitcnt lgkmcnt(0)
	v_mfma_f32_32x32x16_bf16 v[16:31], v[136:139], v[52:55], v[16:31]
	v_add_u32_e32 v40, s10, v163
	v_add3_u32 v57, v40, v162, v164
	ds_read_b64_tr_b16 v[40:41],v57 offset:0
	ds_read_b64_tr_b16 v[42:43],v57 offset:512
	ds_read_b64_tr_b16 v[44:45],v57 offset:1024
	ds_read_b64_tr_b16 v[46:47],v57 offset:1536
	ds_read_b64_tr_b16 v[48:49],v57 offset:2048
	ds_read_b64_tr_b16 v[50:51],v57 offset:2560
	ds_read_b64_tr_b16 v[52:53],v57 offset:3072
	ds_read_b64_tr_b16 v[54:55],v57 offset:3584
	s_waitcnt lgkmcnt(0)
	s_nop 0
	v_mfma_f32_32x32x16_bf16 v[0:15], v[58:61], v[40:43], v[0:15]
	ds_read_b64_tr_b16 v[40:41],v57 offset:4096
	ds_read_b64_tr_b16 v[42:43],v57 offset:4608
	v_mfma_f32_32x32x16_bf16 v[0:15], v[62:65], v[44:47], v[0:15]
	ds_read_b64_tr_b16 v[44:45],v57 offset:5120
	ds_read_b64_tr_b16 v[46:47],v57 offset:5632
	v_mfma_f32_32x32x16_bf16 v[0:15], v[32:35], v[48:51], v[0:15]
	ds_read_b64_tr_b16 v[48:49],v57 offset:6144
	ds_read_b64_tr_b16 v[50:51],v57 offset:6656
	v_mfma_f32_32x32x16_bf16 v[0:15], v[36:39], v[52:55], v[0:15]
	ds_read_b64_tr_b16 v[52:53],v57 offset:7168
	ds_read_b64_tr_b16 v[54:55],v57 offset:7680
	s_waitcnt lgkmcnt(0)
	v_mfma_f32_32x32x16_bf16 v[16:31], v[58:61], v[40:43], v[16:31]
	v_cmp_gt_u32_e32 vcc, 32, v156
	v_mfma_f32_32x32x16_bf16 v[16:31], v[62:65], v[44:47], v[16:31]
	v_mfma_f32_32x32x16_bf16 v[16:31], v[32:35], v[48:51], v[16:31]
	v_mov_b32_e32 v32, v56
	s_nop 1
	v_permlane32_swap_b32_e32 v56, v32
	v_mfma_f32_32x32x16_bf16 v[16:31], v[36:39], v[52:55], v[16:31]
	s_and_saveexec_b64 s[10:11], vcc
	s_cbranch_execz .LBB0_541
; template<int THRL,bool FIXED> __device__ __forceinline__ void attn_unit(int qb,const bf16*Qp,const unsigned char*__restrict__ K8h,const bf16*__restrict__ Vh,bf16*Op,int PO,char*shm){
;     ...
;   if(hi==0)wsf[32+r32]=l_reg;asm volatile("s_waitcnt lgkmcnt(0)":::"memory");
	v_lshl_add_u32 v33, v158, 2, s12
	v_add_f32_e32 v32, v56, v32
	ds_write_b32 v33, v32 offset:57472
	s_branch .LBB0_541

; #define WAIT_BAR(N) asm volatile("s_waitcnt vmcnt(" #N ") lgkmcnt(0)\n\ts_barrier":::"memory")
;   #define RESC() do{ if(resc){ asm volatile("s_waitcnt lgkmcnt(0)":::"memory"); \
;       _Pragma("unroll") for(int d_=0;d_<2;++d_) _Pragma("unroll") for(int r=0;r<16;++r)o[d_][r]*=wsf[crow(r,hi)]; } }while(0)
;   #define ROT() do{sl_prev=sl_cur;sl_cur=sl_next;sl_next=(sl_next==(NSLOT-1)*SLOTB)?0:sl_next+SLOTB;}while(0)
; #define WAIT_BAR(N) asm volatile("s_waitcnt vmcnt(" #N ") lgkmcnt(0)\n\ts_barrier":::"memory")
;   #define RESC() do{ if(resc){ asm volatile("s_waitcnt lgkmcnt(0)":::"memory"); \
;       _Pragma("unroll") for(int d_=0;d_<4;++d_) _Pragma("unroll") for(int r=0;r<16;++r)o[d_][r]*=wsf[crow(r,hi)]; } }while(0)
;   #define ROT() do{sl_prev=sl_cur;sl_cur=sl_next;sl_next=(sl_next==(NSLOT-1)*SLOTB)?0:sl_next+SLOTB;}while(0)
; #define WAIT_BAR(N) asm volatile("s_waitcnt vmcnt(" #N ") lgkmcnt(0)\n\ts_barrier":::"memory")
;   #define RESC() do{ if(resc){ asm volatile("s_waitcnt lgkmcnt(0)":::"memory"); \
;       _Pragma("unroll") for(int d_=0;d_<2;++d_) _Pragma("unroll") for(int r=0;r<16;++r)o[d_][r]*=wsf[crow(r,hi)]; } }while(0)
;   #define ROT() do{sl_prev=sl_cur;sl_cur=sl_next;sl_next=(sl_next==(NSLOT-1)*SLOTB)?0:sl_next+SLOTB;}while(0)
; template<int THRL,bool FIXED> __device__ __forceinline__ void attn_unit(int qb,const bf16*Qp,const bf16*__restrict__ Kh,const bf16*__restrict__ Vh,bf16*Op,int PO,char*shm,bool comb,float lam,const float*gsub,float gscale){
;     ...
;   for(;t+5<NT;t+=2){
;     STEP(pB0,pB1,pA0,pA1,t,true,true,true);     WAIT_BAR(5); RESC(); ROT();
;     STEP(pA0,pA1,pB0,pB1,t+1,true,true,true);   WAIT_BAR(5); RESC(); ROT();
.LBB0_550:
	s_and_b32 s22, s51, 0xc000
	v_add_u32_e32 v160, s22, v214
	v_add_u32_e32 v217, 0x8000, v160
	ds_read_b64_tr_b16 v[222:223], v160 offset:24576
	ds_read_b64_tr_b16 v[224:225], v160 offset:25088
	s_add_i32 s23, s51, 0xffff4000
	v_add_f32_e32 v116, v96, v97
	v_add_f32_e32 v116, v98, v116
	v_add_f32_e32 v116, v99, v116
	v_add_f32_e32 v116, v100, v116
	v_add_f32_e32 v116, v101, v116
	v_cvt_pk_bf16_f32 v182, v96, v97
	v_cvt_pk_bf16_f32 v183, v98, v99
	v_mfma_f32_32x32x16_bf16 v[128:143], v[112:115], v[190:193], v[64:79]
	ds_read_b64_tr_b16 v[96:97], v160 offset:28672
	ds_read_b64_tr_b16 v[98:99], v160 offset:29184
	v_add_f32_e32 v112, v102, v116
	v_add_f32_e32 v112, v103, v112
	v_add_f32_e32 v112, v104, v112
	v_add_f32_e32 v166, v105, v112
	v_mfma_f32_32x32x16_bf16 v[112:127], v[202:205], v[190:193], v[64:79]
	v_cvt_pk_bf16_f32 v184, v100, v101
	v_cvt_pk_bf16_f32 v185, v102, v103
	ds_read_b64_tr_b16 v[100:101], v160 offset:25600
	ds_read_b64_tr_b16 v[102:103], v160 offset:26112
	v_add_f32_e32 v166, v106, v166
	v_add_f32_e32 v166, v107, v166
	v_add_f32_e32 v166, v108, v166
	v_add_f32_e32 v166, v109, v166
	v_cvt_pk_bf16_f32 v178, v104, v105
	v_cvt_pk_bf16_f32 v179, v106, v107
	v_mfma_f32_32x32x16_bf16 v[128:143], v[198:201], v[186:189], v[128:143]
	ds_read_b64_tr_b16 v[104:105], v160 offset:29696
	ds_read_b64_tr_b16 v[106:107], v160 offset:30208
	v_mfma_f32_32x32x16_bf16 v[112:127], v[194:197], v[186:189], v[112:127]
	v_add_f32_e32 v166, v110, v166
	v_add_f32_e32 v166, v111, v166
	v_add_f32_e32 v166, v80, v166
	v_add_f32_e32 v166, v81, v166
	v_cvt_pk_bf16_f32 v180, v108, v109
	v_cvt_pk_bf16_f32 v181, v110, v111
	ds_read_b64_tr_b16 v[108:109], v160 offset:26624
	ds_read_b64_tr_b16 v[110:111], v160 offset:27136
	v_mfma_f32_32x32x16_bf16 v[128:143], v[156:159], v[174:177], v[128:143]
	v_add_f32_e32 v156, v82, v166
	v_add_f32_e32 v156, v83, v156
	v_add_f32_e32 v156, v84, v156
	v_add_f32_e32 v156, v85, v156
	v_cvt_pk_bf16_f32 v170, v80, v81
	v_cvt_pk_bf16_f32 v171, v82, v83
	ds_read_b64_tr_b16 v[80:81], v160 offset:30720
	ds_read_b64_tr_b16 v[82:83], v160 offset:31232
	v_mfma_f32_32x32x16_bf16 v[112:127], v[152:155], v[174:177], v[112:127]
	v_add_f32_e32 v152, v86, v156
	v_add_f32_e32 v152, v87, v152
	v_add_f32_e32 v152, v88, v152
	v_add_f32_e32 v152, v89, v152
	v_cvt_pk_bf16_f32 v172, v84, v85
	v_cvt_pk_bf16_f32 v173, v86, v87
	ds_read_b64_tr_b16 v[84:85], v160 offset:27648
	ds_read_b64_tr_b16 v[86:87], v160 offset:28160
	v_mfma_f32_32x32x16_bf16 v[128:143], v[148:151], v[162:165], v[128:143]
	v_add_f32_e32 v148, v90, v152
	v_add_f32_e32 v148, v91, v148
	v_add_f32_e32 v148, v92, v148
	v_add_f32_e32 v148, v93, v148
	v_cvt_pk_bf16_f32 v166, v88, v89
	v_cvt_pk_bf16_f32 v167, v90, v91
	ds_read_b64_tr_b16 v[88:89], v160 offset:31744
	ds_read_b64_tr_b16 v[90:91], v160 offset:32256
	v_mfma_f32_32x32x16_bf16 v[112:127], v[144:147], v[162:165], v[112:127]
	v_add_f32_e32 v144, v94, v148
	v_add_f32_e32 v144, v95, v144
	v_add_f32_e32 v160, 0, v144
	v_cvt_pk_bf16_f32 v168, v92, v93
	v_cvt_pk_bf16_f32 v169, v94, v95
	s_add_i32 s50, s50, s29
	s_mov_b32 m0, s50
	v_lshl_add_u64 v[92:93], v[212:213], 0, s[20:21]
	global_load_lds_dwordx4 v[92:93], off
	s_add_i32 s50, s51, 0xffffc000
	s_and_b32 s50, s50, 0xc000
	s_add_i32 s50, s50, s35
	s_mov_b32 m0, s50
	v_lshl_add_u64 v[92:93], v[210:211], 0, s[36:37]
	global_load_lds_dwordx4 v[92:93], off
	s_addk_i32 s50, 0x2000
	s_mov_b32 m0, s50
	v_lshl_add_u64 v[92:93], v[210:211], 0, s[26:27]
	global_load_lds_dwordx4 v[92:93], off
	s_waitcnt lgkmcnt(8)
	v_mfma_f32_32x32x16_bf16 v[0:15], v[182:185], v[222:225], v[0:15]
	v_exp_f32_e32 v128, v128
	v_exp_f32_e32 v129, v129
	ds_read_b64_tr_b16 v[92:93], v217
	ds_read_b64_tr_b16 v[94:95], v217 offset:512
	v_mfma_f32_32x32x16_bf16 v[16:31], v[182:185], v[96:99], v[16:31]
	v_exp_f32_e32 v130, v130
	v_exp_f32_e32 v131, v131
	ds_read_b64_tr_b16 v[96:97], v217 offset:4096
	ds_read_b64_tr_b16 v[98:99], v217 offset:4608
	v_mfma_f32_32x32x16_bf16 v[0:15], v[178:181], v[100:103], v[0:15]
	v_exp_f32_e32 v132, v132
	v_exp_f32_e32 v133, v133
	ds_read_b64_tr_b16 v[100:101], v217 offset:1024
	ds_read_b64_tr_b16 v[102:103], v217 offset:1536
	v_mfma_f32_32x32x16_bf16 v[16:31], v[178:181], v[104:107], v[16:31]
	v_exp_f32_e32 v134, v134
	v_exp_f32_e32 v135, v135
	ds_read_b64_tr_b16 v[104:105], v217 offset:5120
	ds_read_b64_tr_b16 v[106:107], v217 offset:5632
	s_waitcnt lgkmcnt(8)
	v_mfma_f32_32x32x16_bf16 v[0:15], v[170:173], v[108:111], v[0:15]
	v_exp_f32_e32 v136, v136
	v_exp_f32_e32 v137, v137
	ds_read_b64_tr_b16 v[108:109], v217 offset:2048
	ds_read_b64_tr_b16 v[110:111], v217 offset:2560
	v_mfma_f32_32x32x16_bf16 v[16:31], v[170:173], v[80:83], v[16:31]
	v_exp_f32_e32 v138, v138
	v_exp_f32_e32 v139, v139
	ds_read_b64_tr_b16 v[80:81], v217 offset:6144
	ds_read_b64_tr_b16 v[82:83], v217 offset:6656
	v_mfma_f32_32x32x16_bf16 v[0:15], v[166:169], v[84:87], v[0:15]
	v_exp_f32_e32 v140, v140
	v_exp_f32_e32 v141, v141
	ds_read_b64_tr_b16 v[84:85], v217 offset:3072
	ds_read_b64_tr_b16 v[86:87], v217 offset:3584
	v_mfma_f32_32x32x16_bf16 v[16:31], v[166:169], v[88:91], v[16:31]
	v_exp_f32_e32 v142, v142
	v_exp_f32_e32 v143, v143
	ds_read_b64_tr_b16 v[88:89], v217 offset:7168
	ds_read_b64_tr_b16 v[90:91], v217 offset:7680
	s_waitcnt lgkmcnt(8)
	v_mfma_f32_32x32x16_bf16 v[32:47], v[182:185], v[92:95], v[32:47]
	v_exp_f32_e32 v112, v112
	v_exp_f32_e32 v113, v113
	v_mfma_f32_32x32x16_bf16 v[48:63], v[182:185], v[96:99], v[48:63]
	v_exp_f32_e32 v114, v114
	v_exp_f32_e32 v115, v115
	v_add_u32_e32 v96, s34, v215
	ds_read_b128 v[92:95], v96
	ds_read_b128 v[144:147], v96 offset:512
	v_mfma_f32_32x32x16_bf16 v[32:47], v[178:181], v[100:103], v[32:47]
	v_exp_f32_e32 v116, v116
	v_exp_f32_e32 v117, v117
	ds_read_b128 v[148:151], v96 offset:2048
	ds_read_b128 v[152:155], v96 offset:2560
	v_mfma_f32_32x32x16_bf16 v[48:63], v[178:181], v[104:107], v[48:63]
	v_exp_f32_e32 v118, v118
	v_exp_f32_e32 v119, v119
	ds_read_b128 v[156:159], v96 offset:4096
	ds_read_b128 v[194:197], v96 offset:4608
	s_waitcnt lgkmcnt(6)
	v_mfma_f32_32x32x16_bf16 v[32:47], v[170:173], v[108:111], v[32:47]
	v_exp_f32_e32 v120, v120
	v_exp_f32_e32 v121, v121
	ds_read_b128 v[198:201], v96 offset:6144
	ds_read_b128 v[202:205], v96 offset:6656
	v_mfma_f32_32x32x16_bf16 v[48:63], v[170:173], v[80:83], v[48:63]
	v_exp_f32_e32 v122, v122
	v_exp_f32_e32 v123, v123
	v_mfma_f32_32x32x16_bf16 v[32:47], v[166:169], v[84:87], v[32:47]
	v_exp_f32_e32 v124, v124
	v_exp_f32_e32 v125, v125
	v_mfma_f32_32x32x16_bf16 v[48:63], v[166:169], v[88:91], v[48:63]
	v_exp_f32_e32 v126, v126
	v_exp_f32_e32 v127, v127
	s_add_i32 s50, s34, 0x2000
	s_cmpk_lg_i32 s34, 0x4000
	s_cselect_b32 s50, s50, 0
	s_and_b32 s23, s23, 0xc000
	v_add_u32_e32 v217, s23, v214
	v_add_u32_e32 v243, 0x8000, v217
	s_waitcnt vmcnt(5) lgkmcnt(0)
	s_barrier
; #define WAIT_BAR(N) asm volatile("s_waitcnt vmcnt(" #N ") lgkmcnt(0)\n\ts_barrier":::"memory")
;   #define RESC() do{ if(resc){ asm volatile("s_waitcnt lgkmcnt(0)":::"memory"); \
;       _Pragma("unroll") for(int d_=0;d_<2;++d_) _Pragma("unroll") for(int r=0;r<16;++r)o[d_][r]*=wsf[crow(r,hi)]; } }while(0)
;   #define ROT() do{sl_prev=sl_cur;sl_cur=sl_next;sl_next=(sl_next==(NSLOT-1)*SLOTB)?0:sl_next+SLOTB;}while(0)
; #define WAIT_BAR(N) asm volatile("s_waitcnt vmcnt(" #N ") lgkmcnt(0)\n\ts_barrier":::"memory")
;   #define RESC() do{ if(resc){ asm volatile("s_waitcnt lgkmcnt(0)":::"memory"); \
;       _Pragma("unroll") for(int d_=0;d_<4;++d_) _Pragma("unroll") for(int r=0;r<16;++r)o[d_][r]*=wsf[crow(r,hi)]; } }while(0)
;   #define ROT() do{sl_prev=sl_cur;sl_cur=sl_next;sl_next=(sl_next==(NSLOT-1)*SLOTB)?0:sl_next+SLOTB;}while(0)
; #define WAIT_BAR(N) asm volatile("s_waitcnt vmcnt(" #N ") lgkmcnt(0)\n\ts_barrier":::"memory")
;   #define RESC() do{ if(resc){ asm volatile("s_waitcnt lgkmcnt(0)":::"memory"); \
;       _Pragma("unroll") for(int d_=0;d_<2;++d_) _Pragma("unroll") for(int r=0;r<16;++r)o[d_][r]*=wsf[crow(r,hi)]; } }while(0)
;   #define ROT() do{sl_prev=sl_cur;sl_cur=sl_next;sl_next=(sl_next==(NSLOT-1)*SLOTB)?0:sl_next+SLOTB;}while(0)
; template<int THRL,bool FIXED> __device__ __forceinline__ void attn_unit(int qb,const bf16*Qp,const bf16*__restrict__ Kh,const bf16*__restrict__ Vh,bf16*Op,int PO,char*shm,bool comb,float lam,const float*gsub,float gscale){
;     ...
;   for(;t+5<NT;t+=2){
;     STEP(pB0,pB1,pA0,pA1,t,true,true,true);     WAIT_BAR(5); RESC(); ROT();
;     STEP(pA0,pA1,pB0,pB1,t+1,true,true,true);   WAIT_BAR(5); RESC(); ROT();
	ds_read_b64_tr_b16 v[222:223], v217 offset:24576
	ds_read_b64_tr_b16 v[224:225], v217 offset:25088
	v_mfma_f32_32x32x16_bf16 v[96:111], v[92:95], v[190:193], v[64:79]
	v_add_f32_e32 v80, v128, v129
	v_add_f32_e32 v80, v130, v80
	v_add_f32_e32 v80, v131, v80
	v_add_f32_e32 v80, v132, v80
	v_add_f32_e32 v80, v133, v80
	v_cvt_pk_bf16_f32 v182, v128, v129
	v_cvt_pk_bf16_f32 v183, v130, v131
	ds_read_b64_tr_b16 v[128:129], v217 offset:28672
	ds_read_b64_tr_b16 v[130:131], v217 offset:29184
	v_add_f32_e32 v80, v134, v80
	v_add_f32_e32 v80, v135, v80
	v_add_f32_e32 v80, v136, v80
	v_add_f32_e32 v166, v137, v80
	v_mfma_f32_32x32x16_bf16 v[80:95], v[144:147], v[190:193], v[64:79]
	v_cvt_pk_bf16_f32 v184, v132, v133
	v_cvt_pk_bf16_f32 v185, v134, v135
	ds_read_b64_tr_b16 v[132:133], v217 offset:25600
	ds_read_b64_tr_b16 v[134:135], v217 offset:26112
	v_mfma_f32_32x32x16_bf16 v[96:111], v[148:151], v[186:189], v[96:111]
	v_add_f32_e32 v144, v138, v166
	v_add_f32_e32 v144, v139, v144
	v_add_f32_e32 v144, v140, v144
	v_add_f32_e32 v144, v141, v144
	v_cvt_pk_bf16_f32 v178, v136, v137
	v_cvt_pk_bf16_f32 v179, v138, v139
	ds_read_b64_tr_b16 v[136:137], v217 offset:29696
	ds_read_b64_tr_b16 v[138:139], v217 offset:30208
	v_mfma_f32_32x32x16_bf16 v[80:95], v[152:155], v[186:189], v[80:95]
	v_add_f32_e32 v144, v142, v144
	v_add_f32_e32 v144, v143, v144
	v_add_f32_e32 v144, v112, v144
	v_add_f32_e32 v144, v113, v144
	v_cvt_pk_bf16_f32 v180, v140, v141
	v_cvt_pk_bf16_f32 v181, v142, v143
	ds_read_b64_tr_b16 v[140:141], v217 offset:26624
	ds_read_b64_tr_b16 v[142:143], v217 offset:27136
	v_mfma_f32_32x32x16_bf16 v[96:111], v[156:159], v[174:177], v[96:111]
	v_add_f32_e32 v144, v114, v144
	v_add_f32_e32 v144, v115, v144
	v_add_f32_e32 v144, v116, v144
	v_add_f32_e32 v144, v117, v144
	v_cvt_pk_bf16_f32 v170, v112, v113
	v_cvt_pk_bf16_f32 v171, v114, v115
	ds_read_b64_tr_b16 v[112:113], v217 offset:30720
	ds_read_b64_tr_b16 v[114:115], v217 offset:31232
	v_mfma_f32_32x32x16_bf16 v[80:95], v[194:197], v[174:177], v[80:95]
	v_add_f32_e32 v144, v118, v144
	v_add_f32_e32 v144, v119, v144
	v_add_f32_e32 v144, v120, v144
	v_add_f32_e32 v144, v121, v144
	v_cvt_pk_bf16_f32 v172, v116, v117
	v_cvt_pk_bf16_f32 v173, v118, v119
	ds_read_b64_tr_b16 v[116:117], v217 offset:27648
	ds_read_b64_tr_b16 v[118:119], v217 offset:28160
	v_mfma_f32_32x32x16_bf16 v[96:111], v[198:201], v[162:165], v[96:111]
	v_add_f32_e32 v144, v122, v144
	v_add_f32_e32 v144, v123, v144
	v_add_f32_e32 v144, v124, v144
	v_add_f32_e32 v144, v125, v144
	v_cvt_pk_bf16_f32 v166, v120, v121
	v_cvt_pk_bf16_f32 v167, v122, v123
	ds_read_b64_tr_b16 v[120:121], v217 offset:31744
	ds_read_b64_tr_b16 v[122:123], v217 offset:32256
	v_mfma_f32_32x32x16_bf16 v[80:95], v[202:205], v[162:165], v[80:95]
	v_add_f32_e32 v144, v126, v144
	v_add_f32_e32 v144, v127, v144
	v_add_f32_e32 v217, 0, v144
	v_cvt_pk_bf16_f32 v168, v124, v125
	v_cvt_pk_bf16_f32 v169, v126, v127
	s_add_i32 s23, s34, s29
	s_mov_b32 m0, s23
	v_lshl_add_u64 v[124:125], v[212:213], 0, s[38:39]
	global_load_lds_dwordx4 v[124:125], off
	s_add_i32 s22, s22, s35
	s_mov_b32 m0, s22
	s_nop 0
	global_load_lds_dwordx4 v[210:211], off
	s_addk_i32 s22, 0x2000
	s_mov_b32 m0, s22
	v_lshl_add_u64 v[124:125], v[210:211], 0, s[24:25]
	global_load_lds_dwordx4 v[124:125], off
	s_waitcnt lgkmcnt(8)
	v_mfma_f32_32x32x16_bf16 v[0:15], v[182:185], v[222:225], v[0:15]
	v_exp_f32_e32 v96, v96
	v_exp_f32_e32 v97, v97
	ds_read_b64_tr_b16 v[124:125], v243
	ds_read_b64_tr_b16 v[126:127], v243 offset:512
	v_mfma_f32_32x32x16_bf16 v[16:31], v[182:185], v[128:131], v[16:31]
	v_exp_f32_e32 v98, v98
	v_exp_f32_e32 v99, v99
	ds_read_b64_tr_b16 v[128:129], v243 offset:4096
	ds_read_b64_tr_b16 v[130:131], v243 offset:4608
	v_mfma_f32_32x32x16_bf16 v[0:15], v[178:181], v[132:135], v[0:15]
	v_exp_f32_e32 v100, v100
	v_exp_f32_e32 v101, v101
	ds_read_b64_tr_b16 v[132:133], v243 offset:1024
	ds_read_b64_tr_b16 v[134:135], v243 offset:1536
	v_mfma_f32_32x32x16_bf16 v[16:31], v[178:181], v[136:139], v[16:31]
	v_exp_f32_e32 v102, v102
	v_exp_f32_e32 v103, v103
	ds_read_b64_tr_b16 v[136:137], v243 offset:5120
	ds_read_b64_tr_b16 v[138:139], v243 offset:5632
	s_waitcnt lgkmcnt(8)
	v_mfma_f32_32x32x16_bf16 v[0:15], v[170:173], v[140:143], v[0:15]
	v_exp_f32_e32 v104, v104
	v_exp_f32_e32 v105, v105
	ds_read_b64_tr_b16 v[140:141], v243 offset:2048
	ds_read_b64_tr_b16 v[142:143], v243 offset:2560
	v_mfma_f32_32x32x16_bf16 v[16:31], v[170:173], v[112:115], v[16:31]
	v_exp_f32_e32 v106, v106
	v_exp_f32_e32 v107, v107
	ds_read_b64_tr_b16 v[222:223], v243 offset:6144
	ds_read_b64_tr_b16 v[224:225], v243 offset:6656
	v_mfma_f32_32x32x16_bf16 v[0:15], v[166:169], v[116:119], v[0:15]
	v_exp_f32_e32 v108, v108
	v_exp_f32_e32 v109, v109
	ds_read_b64_tr_b16 v[116:117], v243 offset:3072
	ds_read_b64_tr_b16 v[118:119], v243 offset:3584
	v_mfma_f32_32x32x16_bf16 v[16:31], v[166:169], v[120:123], v[16:31]
	v_exp_f32_e32 v110, v110
	v_exp_f32_e32 v111, v111
	ds_read_b64_tr_b16 v[120:121], v243 offset:7168
	ds_read_b64_tr_b16 v[122:123], v243 offset:7680
	s_waitcnt lgkmcnt(8)
	v_mfma_f32_32x32x16_bf16 v[32:47], v[182:185], v[124:127], v[32:47]
	v_exp_f32_e32 v80, v80
	v_exp_f32_e32 v81, v81
	v_mfma_f32_32x32x16_bf16 v[48:63], v[182:185], v[128:131], v[48:63]
	v_exp_f32_e32 v82, v82
	v_exp_f32_e32 v83, v83
	v_add_u32_e32 v124, s50, v215
	ds_read_b128 v[112:115], v124
	ds_read_b128 v[202:205], v124 offset:512
	v_mfma_f32_32x32x16_bf16 v[32:47], v[178:181], v[132:135], v[32:47]
	v_exp_f32_e32 v84, v84
	v_exp_f32_e32 v85, v85
	ds_read_b128 v[198:201], v124 offset:2048
	ds_read_b128 v[194:197], v124 offset:2560
	v_mfma_f32_32x32x16_bf16 v[48:63], v[178:181], v[136:139], v[48:63]
	v_exp_f32_e32 v86, v86
	v_exp_f32_e32 v87, v87
	ds_read_b128 v[156:159], v124 offset:4096
	ds_read_b128 v[152:155], v124 offset:4608
	s_waitcnt lgkmcnt(6)
	v_mfma_f32_32x32x16_bf16 v[32:47], v[170:173], v[140:143], v[32:47]
	v_exp_f32_e32 v88, v88
	v_exp_f32_e32 v89, v89
	ds_read_b128 v[148:151], v124 offset:6144
	ds_read_b128 v[144:147], v124 offset:6656
	v_mfma_f32_32x32x16_bf16 v[48:63], v[170:173], v[222:225], v[48:63]
	v_exp_f32_e32 v90, v90
	v_exp_f32_e32 v91, v91
	v_mfma_f32_32x32x16_bf16 v[32:47], v[166:169], v[116:119], v[32:47]
	v_exp_f32_e32 v92, v92
	v_exp_f32_e32 v93, v93
	v_mfma_f32_32x32x16_bf16 v[48:63], v[166:169], v[120:123], v[48:63]
	v_exp_f32_e32 v94, v94
	v_exp_f32_e32 v95, v95
	s_add_i32 s22, s50, 0x2000
	s_cmpk_lg_i32 s50, 0x4000
	v_add_f32_e32 v116, v216, v160
	s_cselect_b32 s34, s22, 0
	s_add_i32 s44, s44, 2
	s_add_i32 s51, s51, 0x8000
	v_lshl_add_u64 v[210:211], v[210:211], 0, s[40:41]
	v_lshl_add_u64 v[212:213], v[212:213], 0, s[40:41]
	s_cmpk_gt_u32 s44, 0xf8
	v_add_f32_e32 v216, v116, v217
	s_waitcnt vmcnt(5) lgkmcnt(0)
	s_barrier
;   #define RESC() do{ if(resc){ asm volatile("s_waitcnt lgkmcnt(0)":::"memory"); \
;       _Pragma("unroll") for(int d_=0;d_<2;++d_) _Pragma("unroll") for(int r=0;r<16;++r)o[d_][r]*=wsf[crow(r,hi)]; } }while(0)
;   #define ROT() do{sl_prev=sl_cur;sl_cur=sl_next;sl_next=(sl_next==(NSLOT-1)*SLOTB)?0:sl_next+SLOTB;}while(0)
;   #define ENDW(tt) do{ if((tt)+3<NT){WAIT_BAR(3);} else if((tt)+2<NT){WAIT_BAR(2);} else {WAIT_BAR(0);} }while(0)
;   #define RESC() do{ if(resc){ asm volatile("s_waitcnt lgkmcnt(0)":::"memory"); \
;       _Pragma("unroll") for(int d_=0;d_<4;++d_) _Pragma("unroll") for(int r=0;r<16;++r)o[d_][r]*=wsf[crow(r,hi)]; } }while(0)
;   #define ROT() do{sl_prev=sl_cur;sl_cur=sl_next;sl_next=(sl_next==(NSLOT-1)*SLOTB)?0:sl_next+SLOTB;}while(0)
;   #define ENDW(tt) do{ if((tt)+3<NT){WAIT_BAR(5);} else if((tt)+2<NT){WAIT_BAR(4);} else {WAIT_BAR(0);} }while(0)
;   #define RESC() do{ if(resc){ asm volatile("s_waitcnt lgkmcnt(0)":::"memory"); \
;       _Pragma("unroll") for(int d_=0;d_<2;++d_) _Pragma("unroll") for(int r=0;r<16;++r)o[d_][r]*=wsf[crow(r,hi)]; } }while(0)
;   #define ROT() do{sl_prev=sl_cur;sl_cur=sl_next;sl_next=(sl_next==(NSLOT-1)*SLOTB)?0:sl_next+SLOTB;}while(0)
;   #define ENDW(tt) do{ if((tt)+3<NT){WAIT_BAR(3);} else if((tt)+2<NT){WAIT_BAR(2);} else {WAIT_BAR(0);} }while(0)
; template<int THRL,bool FIXED> __device__ __forceinline__ void attn_unit(int qb,const bf16*Qp,const bf16*__restrict__ Kh,const bf16*__restrict__ Vh,bf16*Op,int PO,char*shm,bool comb,float lam,const float*gsub,float gscale){
;     ...
;   for(;t+1<NT;t+=2){
;     STEP(pB0,pB1,pA0,pA1,t,(t+3<NT),(t+2<NT),(t+1<NT));       ENDW(t);   RESC(); ROT();
;     STEP(pA0,pA1,pB0,pB1,t+1,(t+4<NT),(t+3<NT),(t+2<NT));     ENDW(t+1); RESC(); ROT();
	s_cbranch_scc0 .LBB0_550
	s_mov_b32 m0, s101
	s_and_b32 s22, s28, 0x3fffffc0
	s_lshl_b32 s22, s22, 2
	s_add_i32 s28, s22, 0
	s_add_i32 s28, s28, 0x16000
	v_add_u32_e32 v210, 0x6000, v214
	v_add_u32_e32 v160, 0x10000, v214
	v_mov_b32_e32 v211, v160
	ds_read_b64_tr_b16 v[244:245], v214 offset:57344
	ds_read_b64_tr_b16 v[246:247], v214 offset:57856
	v_add_f32_e32 v116, v96, v97
	v_add_f32_e32 v116, v98, v116
	v_add_f32_e32 v116, v99, v116
	v_add_f32_e32 v116, v100, v116
	v_add_f32_e32 v116, v101, v116
	v_cvt_pk_bf16_f32 v182, v96, v97
	v_cvt_pk_bf16_f32 v183, v98, v99
	s_waitcnt lgkmcnt(9)
	v_mfma_f32_32x32x16_bf16 v[128:143], v[112:115], v[190:193], v[64:79]
	ds_read_b64_tr_b16 v[248:249], v214 offset:61440
	ds_read_b64_tr_b16 v[250:251], v214 offset:61952
	v_add_f32_e32 v96, v102, v116
	v_add_f32_e32 v96, v103, v96
	v_add_f32_e32 v96, v104, v96
	v_add_f32_e32 v96, v105, v96
	v_cvt_pk_bf16_f32 v184, v100, v101
	v_cvt_pk_bf16_f32 v185, v102, v103
	s_waitcnt lgkmcnt(10)
	v_mfma_f32_32x32x16_bf16 v[112:127], v[202:205], v[190:193], v[64:79]
	ds_read_b64_tr_b16 v[98:99], v214 offset:58368
	ds_read_b64_tr_b16 v[100:101], v214 offset:58880
	v_add_f32_e32 v96, v106, v96
	v_add_f32_e32 v96, v107, v96
	v_add_f32_e32 v96, v108, v96
	v_add_f32_e32 v96, v109, v96
	v_cvt_pk_bf16_f32 v178, v104, v105
	v_cvt_pk_bf16_f32 v179, v106, v107
	s_waitcnt lgkmcnt(11)
	v_mfma_f32_32x32x16_bf16 v[128:143], v[198:201], v[186:189], v[128:143]
	ds_read_b64_tr_b16 v[102:103], v214 offset:62464
	ds_read_b64_tr_b16 v[104:105], v214 offset:62976
	v_add_f32_e32 v96, v110, v96
	v_add_f32_e32 v96, v111, v96
	v_add_f32_e32 v96, v80, v96
	v_add_f32_e32 v96, v81, v96
	v_cvt_pk_bf16_f32 v180, v108, v109
	v_cvt_pk_bf16_f32 v181, v110, v111
	s_waitcnt lgkmcnt(12)
	v_mfma_f32_32x32x16_bf16 v[112:127], v[194:197], v[186:189], v[112:127]
	ds_read_b64_tr_b16 v[106:107], v214 offset:59392
	ds_read_b64_tr_b16 v[108:109], v214 offset:59904
	v_add_f32_e32 v96, v82, v96
	v_add_f32_e32 v96, v83, v96
	v_add_f32_e32 v96, v84, v96
	v_add_f32_e32 v96, v85, v96
	v_cvt_pk_bf16_f32 v170, v80, v81
	v_cvt_pk_bf16_f32 v171, v82, v83
	s_waitcnt lgkmcnt(13)
	v_mfma_f32_32x32x16_bf16 v[128:143], v[156:159], v[174:177], v[128:143]
	ds_read_b64_tr_b16 v[80:81], v214 offset:63488
	ds_read_b64_tr_b16 v[82:83], v214 offset:64000
	v_add_f32_e32 v96, v86, v96
	v_add_f32_e32 v96, v87, v96
	v_add_f32_e32 v96, v88, v96
	v_add_f32_e32 v96, v89, v96
	v_cvt_pk_bf16_f32 v172, v84, v85
	v_cvt_pk_bf16_f32 v173, v86, v87
	s_waitcnt lgkmcnt(14)
	v_mfma_f32_32x32x16_bf16 v[112:127], v[152:155], v[174:177], v[112:127]
	ds_read_b64_tr_b16 v[84:85], v214 offset:60416
	ds_read_b64_tr_b16 v[86:87], v214 offset:60928
	v_add_f32_e32 v96, v90, v96
	v_add_f32_e32 v96, v91, v96
	v_add_f32_e32 v96, v92, v96
	v_add_f32_e32 v96, v93, v96
	v_cvt_pk_bf16_f32 v166, v88, v89
	v_cvt_pk_bf16_f32 v167, v90, v91
	s_waitcnt lgkmcnt(14)
	v_mfma_f32_32x32x16_bf16 v[128:143], v[148:151], v[162:165], v[128:143]
	ds_read_b64_tr_b16 v[88:89], v214 offset:64512
	ds_read_b64_tr_b16 v[90:91], v214 offset:65024
	v_add_f32_e32 v96, v94, v96
	v_add_f32_e32 v96, v95, v96
	v_add_f32_e32 v96, 0, v96
	v_cvt_pk_bf16_f32 v168, v92, v93
	v_cvt_pk_bf16_f32 v169, v94, v95
	v_mfma_f32_32x32x16_bf16 v[112:127], v[144:147], v[162:165], v[112:127]
	s_add_i32 s22, s50, s29
	s_cmp_lg_u32 0, -1
	v_lshl_add_u64 v[92:93], v[208:209], 0, s[42:43]
	s_mov_b32 s23, m0
	s_mov_b32 m0, s22
	s_nop 0
	global_load_lds_dwordx4 v[92:93], off
	s_mov_b32 m0, s23
	s_cselect_b32 s44, 0, 0
	s_mov_b64 s[22:23], 0x4728000
	s_add_i32 s35, s44, s3
	v_lshl_add_u64 v[92:93], v[206:207], 0, s[22:23]
	s_add_i32 s22, s35, 0xa000
	s_mov_b32 s23, m0
	s_mov_b32 m0, s22
	s_nop 0
	global_load_lds_dwordx4 v[92:93], off
	s_mov_b32 m0, s23
	s_mov_b64 s[22:23], 0x4728080
	v_lshl_add_u64 v[92:93], v[206:207], 0, s[22:23]
	s_add_i32 s22, s35, 0xc000
	s_mov_b32 s23, m0
	s_mov_b32 m0, s22
	s_nop 0
	global_load_lds_dwordx4 v[92:93], off
	s_mov_b32 m0, s23
	v_add_f32_e32 v96, v216, v96
	s_waitcnt lgkmcnt(14)
	v_mfma_f32_32x32x16_bf16 v[0:15], v[182:185], v[244:247], v[0:15]
	v_exp_f32_e32 v128, v128
	v_exp_f32_e32 v129, v129
	ds_read_b64_tr_b16 v[92:93], v211
	ds_read_b64_tr_b16 v[94:95], v211 offset:512
	s_waitcnt lgkmcnt(14)
	v_mfma_f32_32x32x16_bf16 v[16:31], v[182:185], v[248:251], v[16:31]
	v_exp_f32_e32 v130, v130
	v_exp_f32_e32 v131, v131
	ds_read_b64_tr_b16 v[144:145], v211 offset:4096
	ds_read_b64_tr_b16 v[146:147], v211 offset:4608
	s_waitcnt lgkmcnt(14)
	v_mfma_f32_32x32x16_bf16 v[0:15], v[178:181], v[98:101], v[0:15]
	v_exp_f32_e32 v132, v132
	v_exp_f32_e32 v133, v133
	ds_read_b64_tr_b16 v[98:99], v211 offset:1024
	ds_read_b64_tr_b16 v[100:101], v211 offset:1536
	s_waitcnt lgkmcnt(14)
	v_mfma_f32_32x32x16_bf16 v[16:31], v[178:181], v[102:105], v[16:31]
	v_exp_f32_e32 v134, v134
	v_exp_f32_e32 v135, v135
	ds_read_b64_tr_b16 v[102:103], v211 offset:5120
	ds_read_b64_tr_b16 v[104:105], v211 offset:5632
	s_waitcnt lgkmcnt(14)
	v_mfma_f32_32x32x16_bf16 v[0:15], v[170:173], v[106:109], v[0:15]
	v_exp_f32_e32 v136, v136
	v_exp_f32_e32 v137, v137
	ds_read_b64_tr_b16 v[106:107], v211 offset:2048
	ds_read_b64_tr_b16 v[108:109], v211 offset:2560
	s_waitcnt lgkmcnt(14)
	v_mfma_f32_32x32x16_bf16 v[16:31], v[170:173], v[80:83], v[16:31]
	v_exp_f32_e32 v138, v138
	v_exp_f32_e32 v139, v139
	ds_read_b64_tr_b16 v[80:81], v211 offset:6144
	ds_read_b64_tr_b16 v[82:83], v211 offset:6656
	s_waitcnt lgkmcnt(14)
	v_mfma_f32_32x32x16_bf16 v[0:15], v[166:169], v[84:87], v[0:15]
	v_exp_f32_e32 v140, v140
	v_exp_f32_e32 v141, v141
	ds_read_b64_tr_b16 v[84:85], v211 offset:3072
	ds_read_b64_tr_b16 v[86:87], v211 offset:3584
	s_waitcnt lgkmcnt(14)
;   #define RESC() do{ if(resc){ asm volatile("s_waitcnt lgkmcnt(0)":::"memory"); \
;       _Pragma("unroll") for(int d_=0;d_<2;++d_) _Pragma("unroll") for(int r=0;r<16;++r)o[d_][r]*=wsf[crow(r,hi)]; } }while(0)
;   #define ROT() do{sl_prev=sl_cur;sl_cur=sl_next;sl_next=(sl_next==(NSLOT-1)*SLOTB)?0:sl_next+SLOTB;}while(0)
;   #define ENDW(tt) do{ if((tt)+3<NT){WAIT_BAR(3);} else if((tt)+2<NT){WAIT_BAR(2);} else {WAIT_BAR(0);} }while(0)
;   #define RESC() do{ if(resc){ asm volatile("s_waitcnt lgkmcnt(0)":::"memory"); \
;       _Pragma("unroll") for(int d_=0;d_<4;++d_) _Pragma("unroll") for(int r=0;r<16;++r)o[d_][r]*=wsf[crow(r,hi)]; } }while(0)
;   #define ROT() do{sl_prev=sl_cur;sl_cur=sl_next;sl_next=(sl_next==(NSLOT-1)*SLOTB)?0:sl_next+SLOTB;}while(0)
;   #define ENDW(tt) do{ if((tt)+3<NT){WAIT_BAR(5);} else if((tt)+2<NT){WAIT_BAR(4);} else {WAIT_BAR(0);} }while(0)
;   #define RESC() do{ if(resc){ asm volatile("s_waitcnt lgkmcnt(0)":::"memory"); \
;       _Pragma("unroll") for(int d_=0;d_<2;++d_) _Pragma("unroll") for(int r=0;r<16;++r)o[d_][r]*=wsf[crow(r,hi)]; } }while(0)
;   #define ROT() do{sl_prev=sl_cur;sl_cur=sl_next;sl_next=(sl_next==(NSLOT-1)*SLOTB)?0:sl_next+SLOTB;}while(0)
;   #define ENDW(tt) do{ if((tt)+3<NT){WAIT_BAR(3);} else if((tt)+2<NT){WAIT_BAR(2);} else {WAIT_BAR(0);} }while(0)
; template<int THRL,bool FIXED> __device__ __forceinline__ void attn_unit(int qb,const bf16*Qp,const bf16*__restrict__ Kh,const bf16*__restrict__ Vh,bf16*Op,int PO,char*shm,bool comb,float lam,const float*gsub,float gscale){
;     ...
;   for(;t+1<NT;t+=2){
;     STEP(pB0,pB1,pA0,pA1,t,(t+3<NT),(t+2<NT),(t+1<NT));       ENDW(t);   RESC(); ROT();
;     STEP(pA0,pA1,pB0,pB1,t+1,(t+4<NT),(t+3<NT),(t+2<NT));     ENDW(t+1); RESC(); ROT();
	v_mfma_f32_32x32x16_bf16 v[16:31], v[166:169], v[88:91], v[16:31]
	v_exp_f32_e32 v142, v142
	v_exp_f32_e32 v143, v143
	ds_read_b64_tr_b16 v[88:89], v211 offset:7168
	ds_read_b64_tr_b16 v[90:91], v211 offset:7680
	s_waitcnt lgkmcnt(14)
	v_mfma_f32_32x32x16_bf16 v[32:47], v[182:185], v[92:95], v[32:47]
	v_exp_f32_e32 v112, v112
	v_exp_f32_e32 v113, v113
	s_waitcnt lgkmcnt(12)
	v_mfma_f32_32x32x16_bf16 v[48:63], v[182:185], v[144:147], v[48:63]
	v_exp_f32_e32 v114, v114
	v_exp_f32_e32 v115, v115
	v_add_u32_e32 v97, s34, v215
	ds_read_b128 v[92:95], v97
	ds_read_b128 v[194:197], v97 offset:512
	s_waitcnt lgkmcnt(12)
	v_mfma_f32_32x32x16_bf16 v[32:47], v[178:181], v[98:101], v[32:47]
	v_exp_f32_e32 v116, v116
	v_exp_f32_e32 v117, v117
	ds_read_b128 v[98:101], v97 offset:2048
	ds_read_b128 v[198:201], v97 offset:2560
	s_waitcnt lgkmcnt(12)
	v_mfma_f32_32x32x16_bf16 v[48:63], v[178:181], v[102:105], v[48:63]
	v_exp_f32_e32 v118, v118
	v_exp_f32_e32 v119, v119
	ds_read_b128 v[102:105], v97 offset:4096
	ds_read_b128 v[202:205], v97 offset:4608
	s_waitcnt lgkmcnt(12)
	v_mfma_f32_32x32x16_bf16 v[32:47], v[170:173], v[106:109], v[32:47]
	v_exp_f32_e32 v120, v120
	v_exp_f32_e32 v121, v121
	ds_read_b128 v[106:109], v97 offset:6144
	ds_read_b128 v[244:247], v97 offset:6656
	s_waitcnt lgkmcnt(12)
	v_mfma_f32_32x32x16_bf16 v[48:63], v[170:173], v[80:83], v[48:63]
	v_exp_f32_e32 v122, v122
	v_exp_f32_e32 v123, v123
	s_waitcnt lgkmcnt(10)
	v_mfma_f32_32x32x16_bf16 v[32:47], v[166:169], v[84:87], v[32:47]
	v_exp_f32_e32 v124, v124
	v_exp_f32_e32 v125, v125
	s_waitcnt lgkmcnt(8)
	v_mfma_f32_32x32x16_bf16 v[48:63], v[166:169], v[88:91], v[48:63]
	v_exp_f32_e32 v126, v126
	v_exp_f32_e32 v127, v127
	s_waitcnt vmcnt(5) lgkmcnt(0)
	s_barrier
	s_add_i32 s22, s34, 0x2000
	s_cmpk_lg_i32 s34, 0x4000
	s_cselect_b32 s22, s22, 0
	v_add_u32_e32 v211, 0x14000, v214
	ds_read_b64_tr_b16 v[248:249], v210 offset:49152
	ds_read_b64_tr_b16 v[250:251], v210 offset:49664
	v_add_f32_e32 v80, v128, v129
	v_add_f32_e32 v80, v130, v80
	v_add_f32_e32 v80, v131, v80
	v_add_f32_e32 v80, v132, v80
	v_add_f32_e32 v80, v133, v80
	v_cvt_pk_bf16_f32 v182, v128, v129
	v_cvt_pk_bf16_f32 v183, v130, v131
	s_waitcnt lgkmcnt(9)
	v_mfma_f32_32x32x16_bf16 v[144:159], v[92:95], v[190:193], v[64:79]
	ds_read_b64_tr_b16 v[222:223], v210 offset:53248
	ds_read_b64_tr_b16 v[224:225], v210 offset:53760
	v_add_f32_e32 v80, v134, v80
	v_add_f32_e32 v80, v135, v80
	v_add_f32_e32 v80, v136, v80
	v_add_f32_e32 v97, v137, v80
	s_waitcnt lgkmcnt(10)
	v_mfma_f32_32x32x16_bf16 v[80:95], v[194:197], v[190:193], v[64:79]
	v_cvt_pk_bf16_f32 v184, v132, v133
	v_cvt_pk_bf16_f32 v185, v134, v135
	ds_read_b64_tr_b16 v[130:131], v210 offset:50176
	ds_read_b64_tr_b16 v[132:133], v210 offset:50688
	v_add_f32_e32 v97, v138, v97
	v_add_f32_e32 v97, v139, v97
	v_add_f32_e32 v97, v140, v97
	v_add_f32_e32 v97, v141, v97
	v_cvt_pk_bf16_f32 v178, v136, v137
	v_cvt_pk_bf16_f32 v179, v138, v139
	s_waitcnt lgkmcnt(11)
	v_mfma_f32_32x32x16_bf16 v[144:159], v[98:101], v[186:189], v[144:159]
	ds_read_b64_tr_b16 v[98:99], v210 offset:54272
	ds_read_b64_tr_b16 v[100:101], v210 offset:54784
	s_waitcnt lgkmcnt(12)
	v_mfma_f32_32x32x16_bf16 v[80:95], v[198:201], v[186:189], v[80:95]
	v_add_f32_e32 v97, v142, v97
	v_add_f32_e32 v97, v143, v97
	v_add_f32_e32 v97, v112, v97
	v_add_f32_e32 v97, v113, v97
	v_cvt_pk_bf16_f32 v180, v140, v141
	v_cvt_pk_bf16_f32 v181, v142, v143
	ds_read_b64_tr_b16 v[134:135], v210 offset:51200
	ds_read_b64_tr_b16 v[136:137], v210 offset:51712
	v_add_f32_e32 v97, v114, v97
	v_add_f32_e32 v97, v115, v97
	v_add_f32_e32 v97, v116, v97
	v_add_f32_e32 v97, v117, v97
	v_cvt_pk_bf16_f32 v170, v112, v113
	v_cvt_pk_bf16_f32 v171, v114, v115
	s_waitcnt lgkmcnt(13)
	v_mfma_f32_32x32x16_bf16 v[144:159], v[102:105], v[174:177], v[144:159]
	ds_read_b64_tr_b16 v[102:103], v210 offset:55296
	ds_read_b64_tr_b16 v[104:105], v210 offset:55808
	s_waitcnt lgkmcnt(14)
	v_mfma_f32_32x32x16_bf16 v[80:95], v[202:205], v[174:177], v[80:95]
	v_add_f32_e32 v97, v118, v97
	v_add_f32_e32 v97, v119, v97
	v_add_f32_e32 v97, v120, v97
	v_add_f32_e32 v97, v121, v97
	v_cvt_pk_bf16_f32 v172, v116, v117
	v_cvt_pk_bf16_f32 v173, v118, v119
	ds_read_b64_tr_b16 v[110:111], v210 offset:52224
	ds_read_b64_tr_b16 v[112:113], v210 offset:52736
	v_add_f32_e32 v97, v122, v97
	v_add_f32_e32 v97, v123, v97
	v_add_f32_e32 v97, v124, v97
	v_add_f32_e32 v97, v125, v97
	v_cvt_pk_bf16_f32 v166, v120, v121
	v_cvt_pk_bf16_f32 v167, v122, v123
	s_waitcnt lgkmcnt(14)
	v_mfma_f32_32x32x16_bf16 v[144:159], v[106:109], v[162:165], v[144:159]
	ds_read_b64_tr_b16 v[106:107], v210 offset:56320
	ds_read_b64_tr_b16 v[108:109], v210 offset:56832
	v_mfma_f32_32x32x16_bf16 v[80:95], v[244:247], v[162:165], v[80:95]
	v_add_f32_e32 v97, v126, v97
	v_add_f32_e32 v97, v127, v97
	v_add_f32_e32 v97, 0, v97
	v_cvt_pk_bf16_f32 v168, v124, v125
	v_cvt_pk_bf16_f32 v169, v126, v127
	s_nop 0
	v_add_f32_e32 v128, v96, v97
	s_add_i32 s23, s34, s29
	v_lshl_add_u64 v[96:97], v[208:209], 0, s[46:47]
	s_mov_b32 s29, m0
	s_mov_b32 m0, s23
	s_nop 0
	global_load_lds_dwordx4 v[96:97], off
	s_mov_b32 m0, s29
	v_lshl_add_u64 v[96:97], v[206:207], 0, s[42:43]
	s_add_i32 s23, s35, 0xe000
	s_mov_b32 s29, m0
	s_mov_b32 m0, s23
	s_nop 0
	global_load_lds_dwordx4 v[96:97], off
	s_mov_b32 m0, s29
	s_mov_b64 s[50:51], 0x4770080
	v_lshl_add_u64 v[96:97], v[206:207], 0, s[50:51]
	s_add_i32 s23, s35, 0x10000
	s_mov_b32 s29, m0
	s_mov_b32 m0, s23
	s_nop 0
	global_load_lds_dwordx4 v[96:97], off
	s_mov_b32 m0, s29
	s_waitcnt lgkmcnt(14)
;   #define RESC() do{ if(resc){ asm volatile("s_waitcnt lgkmcnt(0)":::"memory"); \
;       _Pragma("unroll") for(int d_=0;d_<2;++d_) _Pragma("unroll") for(int r=0;r<16;++r)o[d_][r]*=wsf[crow(r,hi)]; } }while(0)
;   #define ROT() do{sl_prev=sl_cur;sl_cur=sl_next;sl_next=(sl_next==(NSLOT-1)*SLOTB)?0:sl_next+SLOTB;}while(0)
;   #define ENDW(tt) do{ if((tt)+3<NT){WAIT_BAR(3);} else if((tt)+2<NT){WAIT_BAR(2);} else {WAIT_BAR(0);} }while(0)
;   #define RESC() do{ if(resc){ asm volatile("s_waitcnt lgkmcnt(0)":::"memory"); \
;       _Pragma("unroll") for(int d_=0;d_<4;++d_) _Pragma("unroll") for(int r=0;r<16;++r)o[d_][r]*=wsf[crow(r,hi)]; } }while(0)
;   #define ROT() do{sl_prev=sl_cur;sl_cur=sl_next;sl_next=(sl_next==(NSLOT-1)*SLOTB)?0:sl_next+SLOTB;}while(0)
;   #define ENDW(tt) do{ if((tt)+3<NT){WAIT_BAR(5);} else if((tt)+2<NT){WAIT_BAR(4);} else {WAIT_BAR(0);} }while(0)
;   #define RESC() do{ if(resc){ asm volatile("s_waitcnt lgkmcnt(0)":::"memory"); \
;       _Pragma("unroll") for(int d_=0;d_<2;++d_) _Pragma("unroll") for(int r=0;r<16;++r)o[d_][r]*=wsf[crow(r,hi)]; } }while(0)
;   #define ROT() do{sl_prev=sl_cur;sl_cur=sl_next;sl_next=(sl_next==(NSLOT-1)*SLOTB)?0:sl_next+SLOTB;}while(0)
;   #define ENDW(tt) do{ if((tt)+3<NT){WAIT_BAR(3);} else if((tt)+2<NT){WAIT_BAR(2);} else {WAIT_BAR(0);} }while(0)
; template<int THRL,bool FIXED> __device__ __forceinline__ void attn_unit(int qb,const bf16*Qp,const bf16*__restrict__ Kh,const bf16*__restrict__ Vh,bf16*Op,int PO,char*shm,bool comb,float lam,const float*gsub,float gscale){
;     ...
;   for(;t+1<NT;t+=2){
;     STEP(pB0,pB1,pA0,pA1,t,(t+3<NT),(t+2<NT),(t+1<NT));       ENDW(t);   RESC(); ROT();
;     STEP(pA0,pA1,pB0,pB1,t+1,(t+4<NT),(t+3<NT),(t+2<NT));     ENDW(t+1); RESC(); ROT();
	v_mfma_f32_32x32x16_bf16 v[0:15], v[182:185], v[248:251], v[0:15]
	v_exp_f32_e32 v144, v144
	v_exp_f32_e32 v145, v145
	ds_read_b64_tr_b16 v[114:115], v211
	ds_read_b64_tr_b16 v[116:117], v211 offset:512
	s_waitcnt lgkmcnt(14)
	v_mfma_f32_32x32x16_bf16 v[16:31], v[182:185], v[222:225], v[16:31]
	v_exp_f32_e32 v146, v146
	v_exp_f32_e32 v147, v147
	ds_read_b64_tr_b16 v[118:119], v211 offset:4096
	ds_read_b64_tr_b16 v[120:121], v211 offset:4608
	s_waitcnt lgkmcnt(14)
	v_mfma_f32_32x32x16_bf16 v[0:15], v[178:181], v[130:133], v[0:15]
	v_exp_f32_e32 v148, v148
	v_exp_f32_e32 v149, v149
	ds_read_b64_tr_b16 v[122:123], v211 offset:1024
	ds_read_b64_tr_b16 v[124:125], v211 offset:1536
	s_waitcnt lgkmcnt(14)
	v_mfma_f32_32x32x16_bf16 v[16:31], v[178:181], v[98:101], v[16:31]
	v_exp_f32_e32 v150, v150
	v_exp_f32_e32 v151, v151
	ds_read_b64_tr_b16 v[96:97], v211 offset:5120
	ds_read_b64_tr_b16 v[98:99], v211 offset:5632
	s_waitcnt lgkmcnt(14)
	v_mfma_f32_32x32x16_bf16 v[0:15], v[170:173], v[134:137], v[0:15]
	v_exp_f32_e32 v152, v152
	v_exp_f32_e32 v153, v153
	ds_read_b64_tr_b16 v[130:131], v211 offset:2048
	ds_read_b64_tr_b16 v[132:133], v211 offset:2560
	s_waitcnt lgkmcnt(14)
	v_mfma_f32_32x32x16_bf16 v[16:31], v[170:173], v[102:105], v[16:31]
	v_exp_f32_e32 v154, v154
	v_exp_f32_e32 v155, v155
	ds_read_b64_tr_b16 v[100:101], v211 offset:6144
	ds_read_b64_tr_b16 v[102:103], v211 offset:6656
	s_waitcnt lgkmcnt(14)
	v_mfma_f32_32x32x16_bf16 v[0:15], v[166:169], v[110:113], v[0:15]
	v_exp_f32_e32 v156, v156
	v_exp_f32_e32 v157, v157
	ds_read_b64_tr_b16 v[110:111], v211 offset:3072
	ds_read_b64_tr_b16 v[112:113], v211 offset:3584
	s_waitcnt lgkmcnt(14)
	v_mfma_f32_32x32x16_bf16 v[16:31], v[166:169], v[106:109], v[16:31]
	v_exp_f32_e32 v158, v158
	v_exp_f32_e32 v159, v159
	ds_read_b64_tr_b16 v[104:105], v211 offset:7168
	ds_read_b64_tr_b16 v[106:107], v211 offset:7680
	s_waitcnt lgkmcnt(14)
	v_mfma_f32_32x32x16_bf16 v[32:47], v[182:185], v[114:117], v[32:47]
	v_exp_f32_e32 v80, v80
	v_exp_f32_e32 v81, v81
	s_waitcnt lgkmcnt(12)
	v_mfma_f32_32x32x16_bf16 v[48:63], v[182:185], v[118:121], v[48:63]
	v_exp_f32_e32 v82, v82
	v_exp_f32_e32 v83, v83
	v_add_u32_e32 v108, s22, v215
	ds_read_b128 v[134:137], v108
	ds_read_b128 v[138:141], v108 offset:512
	s_waitcnt lgkmcnt(12)
	v_mfma_f32_32x32x16_bf16 v[32:47], v[178:181], v[122:125], v[32:47]
	v_exp_f32_e32 v84, v84
	v_exp_f32_e32 v85, v85
	ds_read_b128 v[194:197], v108 offset:2048
	ds_read_b128 v[198:201], v108 offset:2560
	s_waitcnt lgkmcnt(12)
	v_mfma_f32_32x32x16_bf16 v[48:63], v[178:181], v[96:99], v[48:63]
	v_exp_f32_e32 v86, v86
	v_exp_f32_e32 v87, v87
	ds_read_b128 v[202:205], v108 offset:4096
	ds_read_b128 v[208:211], v108 offset:4608
	s_waitcnt lgkmcnt(12)
	v_mfma_f32_32x32x16_bf16 v[32:47], v[170:173], v[130:133], v[32:47]
	v_exp_f32_e32 v88, v88
	v_exp_f32_e32 v89, v89
	ds_read_b128 v[130:133], v108 offset:6144
	ds_read_b128 v[222:225], v108 offset:6656
	s_waitcnt lgkmcnt(12)
	v_mfma_f32_32x32x16_bf16 v[48:63], v[170:173], v[100:103], v[48:63]
	v_exp_f32_e32 v90, v90
	v_exp_f32_e32 v91, v91
	s_waitcnt lgkmcnt(10)
	v_mfma_f32_32x32x16_bf16 v[32:47], v[166:169], v[110:113], v[32:47]
	v_exp_f32_e32 v92, v92
	v_exp_f32_e32 v93, v93
	s_waitcnt lgkmcnt(8)
	v_mfma_f32_32x32x16_bf16 v[48:63], v[166:169], v[104:107], v[48:63]
	v_exp_f32_e32 v94, v94
	v_exp_f32_e32 v95, v95
	s_waitcnt vmcnt(5) lgkmcnt(0)
	s_barrier
	s_add_i32 s23, s22, 0x2000
	s_cmpk_lg_i32 s22, 0x4000
	s_cselect_b32 s22, s23, 0
	v_add_u32_e32 v212, 0x8000, v214
	ds_read_b64_tr_b16 v[244:245], v214 offset:24576
	ds_read_b64_tr_b16 v[246:247], v214 offset:25088
	v_add_f32_e32 v96, v144, v145
	v_add_f32_e32 v96, v146, v96
	v_add_f32_e32 v96, v147, v96
	v_add_f32_e32 v96, v148, v96
	v_add_f32_e32 v96, v149, v96
	v_cvt_pk_bf16_f32 v182, v144, v145
	v_cvt_pk_bf16_f32 v183, v146, v147
	s_waitcnt lgkmcnt(9)
	v_mfma_f32_32x32x16_bf16 v[112:127], v[134:137], v[190:193], v[64:79]
	ds_read_b64_tr_b16 v[134:135], v214 offset:28672
	ds_read_b64_tr_b16 v[136:137], v214 offset:29184
	v_add_f32_e32 v96, v150, v96
	v_add_f32_e32 v96, v151, v96
	v_add_f32_e32 v96, v152, v96
	v_add_f32_e32 v129, v153, v96
	v_cvt_pk_bf16_f32 v184, v148, v149
	v_cvt_pk_bf16_f32 v185, v150, v151
	s_waitcnt lgkmcnt(10)
	v_mfma_f32_32x32x16_bf16 v[96:111], v[138:141], v[190:193], v[64:79]
	ds_read_b64_tr_b16 v[138:139], v214 offset:25600
	ds_read_b64_tr_b16 v[140:141], v214 offset:26112
	v_add_f32_e32 v129, v154, v129
	v_add_f32_e32 v129, v155, v129
	v_add_f32_e32 v129, v156, v129
	v_add_f32_e32 v129, v157, v129
	v_cvt_pk_bf16_f32 v178, v152, v153
	v_cvt_pk_bf16_f32 v179, v154, v155
	s_waitcnt lgkmcnt(11)
	v_mfma_f32_32x32x16_bf16 v[112:127], v[194:197], v[186:189], v[112:127]
	ds_read_b64_tr_b16 v[146:147], v214 offset:29696
	ds_read_b64_tr_b16 v[148:149], v214 offset:30208
	v_add_f32_e32 v129, v158, v129
	v_add_f32_e32 v129, v159, v129
	v_add_f32_e32 v129, v80, v129
	v_add_f32_e32 v129, v81, v129
	v_cvt_pk_bf16_f32 v180, v156, v157
	v_cvt_pk_bf16_f32 v181, v158, v159
	s_waitcnt lgkmcnt(12)
	v_mfma_f32_32x32x16_bf16 v[96:111], v[198:201], v[186:189], v[96:111]
	ds_read_b64_tr_b16 v[150:151], v214 offset:26624
	ds_read_b64_tr_b16 v[152:153], v214 offset:27136
	v_add_f32_e32 v129, v82, v129
	v_add_f32_e32 v129, v83, v129
	v_add_f32_e32 v129, v84, v129
	v_add_f32_e32 v129, v85, v129
	v_cvt_pk_bf16_f32 v170, v80, v81
	v_cvt_pk_bf16_f32 v171, v82, v83
	s_waitcnt lgkmcnt(13)
	v_mfma_f32_32x32x16_bf16 v[112:127], v[202:205], v[174:177], v[112:127]
	ds_read_b64_tr_b16 v[80:81], v214 offset:30720
	ds_read_b64_tr_b16 v[82:83], v214 offset:31232
	v_add_f32_e32 v129, v86, v129
	v_add_f32_e32 v129, v87, v129
	v_add_f32_e32 v129, v88, v129
	v_add_f32_e32 v129, v89, v129
	v_cvt_pk_bf16_f32 v172, v84, v85
	v_cvt_pk_bf16_f32 v173, v86, v87
	s_waitcnt lgkmcnt(14)
;   #define RESC() do{ if(resc){ asm volatile("s_waitcnt lgkmcnt(0)":::"memory"); \
;       _Pragma("unroll") for(int d_=0;d_<2;++d_) _Pragma("unroll") for(int r=0;r<16;++r)o[d_][r]*=wsf[crow(r,hi)]; } }while(0)
;   #define ROT() do{sl_prev=sl_cur;sl_cur=sl_next;sl_next=(sl_next==(NSLOT-1)*SLOTB)?0:sl_next+SLOTB;}while(0)
;   #define ENDW(tt) do{ if((tt)+3<NT){WAIT_BAR(3);} else if((tt)+2<NT){WAIT_BAR(2);} else {WAIT_BAR(0);} }while(0)
;   #define RESC() do{ if(resc){ asm volatile("s_waitcnt lgkmcnt(0)":::"memory"); \
;       _Pragma("unroll") for(int d_=0;d_<4;++d_) _Pragma("unroll") for(int r=0;r<16;++r)o[d_][r]*=wsf[crow(r,hi)]; } }while(0)
;   #define ROT() do{sl_prev=sl_cur;sl_cur=sl_next;sl_next=(sl_next==(NSLOT-1)*SLOTB)?0:sl_next+SLOTB;}while(0)
;   #define ENDW(tt) do{ if((tt)+3<NT){WAIT_BAR(5);} else if((tt)+2<NT){WAIT_BAR(4);} else {WAIT_BAR(0);} }while(0)
;   #define RESC() do{ if(resc){ asm volatile("s_waitcnt lgkmcnt(0)":::"memory"); \
;       _Pragma("unroll") for(int d_=0;d_<2;++d_) _Pragma("unroll") for(int r=0;r<16;++r)o[d_][r]*=wsf[crow(r,hi)]; } }while(0)
;   #define ROT() do{sl_prev=sl_cur;sl_cur=sl_next;sl_next=(sl_next==(NSLOT-1)*SLOTB)?0:sl_next+SLOTB;}while(0)
;   #define ENDW(tt) do{ if((tt)+3<NT){WAIT_BAR(3);} else if((tt)+2<NT){WAIT_BAR(2);} else {WAIT_BAR(0);} }while(0)
; template<int THRL,bool FIXED> __device__ __forceinline__ void attn_unit(int qb,const bf16*Qp,const bf16*__restrict__ Kh,const bf16*__restrict__ Vh,bf16*Op,int PO,char*shm,bool comb,float lam,const float*gsub,float gscale){
;     ...
;   for(;t+1<NT;t+=2){
;     STEP(pB0,pB1,pA0,pA1,t,(t+3<NT),(t+2<NT),(t+1<NT));       ENDW(t);   RESC(); ROT();
;     STEP(pA0,pA1,pB0,pB1,t+1,(t+4<NT),(t+3<NT),(t+2<NT));     ENDW(t+1); RESC(); ROT();
	v_mfma_f32_32x32x16_bf16 v[96:111], v[208:211], v[174:177], v[96:111]
	ds_read_b64_tr_b16 v[84:85], v214 offset:27648
	ds_read_b64_tr_b16 v[86:87], v214 offset:28160
	v_add_f32_e32 v129, v90, v129
	v_add_f32_e32 v129, v91, v129
	v_add_f32_e32 v129, v92, v129
	v_add_f32_e32 v129, v93, v129
	v_cvt_pk_bf16_f32 v166, v88, v89
	v_cvt_pk_bf16_f32 v167, v90, v91
	s_waitcnt lgkmcnt(14)
	v_mfma_f32_32x32x16_bf16 v[112:127], v[130:133], v[162:165], v[112:127]
	ds_read_b64_tr_b16 v[88:89], v214 offset:31744
	ds_read_b64_tr_b16 v[90:91], v214 offset:32256
	v_add_f32_e32 v129, v94, v129
	v_add_f32_e32 v129, v95, v129
	v_add_f32_e32 v129, 0, v129
	v_cvt_pk_bf16_f32 v168, v92, v93
	v_cvt_pk_bf16_f32 v169, v94, v95
	v_mfma_f32_32x32x16_bf16 v[96:111], v[222:225], v[162:165], v[96:111]
	s_add_i32 s29, s44, 0x12000
	v_lshl_add_u64 v[92:93], v[206:207], 0, s[46:47]
	s_add_i32 s3, s3, s29
	s_mov_b32 s23, m0
	s_mov_b32 m0, s3
	s_nop 0
	global_load_lds_dwordx4 v[92:93], off
	s_mov_b32 m0, s23
	s_mov_b64 s[50:51], 0x47b8080
	v_lshl_add_u64 v[92:93], v[206:207], 0, s[50:51]
	s_add_i32 s35, s35, 0x14000
	s_mov_b32 s3, m0
	s_mov_b32 m0, s35
	s_nop 0
	global_load_lds_dwordx4 v[92:93], off
	s_mov_b32 m0, s3
	v_add_f32_e32 v144, v128, v129
	s_waitcnt lgkmcnt(14)
	v_mfma_f32_32x32x16_bf16 v[0:15], v[182:185], v[244:247], v[0:15]
	v_exp_f32_e32 v112, v112
	v_exp_f32_e32 v113, v113
	ds_read_b64_tr_b16 v[92:93], v212
	ds_read_b64_tr_b16 v[94:95], v212 offset:512
	s_waitcnt lgkmcnt(14)
	v_mfma_f32_32x32x16_bf16 v[16:31], v[182:185], v[134:137], v[16:31]
	v_exp_f32_e32 v114, v114
	v_exp_f32_e32 v115, v115
	ds_read_b64_tr_b16 v[128:129], v212 offset:4096
	ds_read_b64_tr_b16 v[130:131], v212 offset:4608
	s_waitcnt lgkmcnt(14)
	v_mfma_f32_32x32x16_bf16 v[0:15], v[178:181], v[138:141], v[0:15]
	v_exp_f32_e32 v116, v116
	v_exp_f32_e32 v117, v117
	ds_read_b64_tr_b16 v[132:133], v212 offset:1024
	ds_read_b64_tr_b16 v[134:135], v212 offset:1536
	s_waitcnt lgkmcnt(14)
	v_mfma_f32_32x32x16_bf16 v[16:31], v[178:181], v[146:149], v[16:31]
	v_exp_f32_e32 v118, v118
	v_exp_f32_e32 v119, v119
	ds_read_b64_tr_b16 v[136:137], v212 offset:5120
	ds_read_b64_tr_b16 v[138:139], v212 offset:5632
	s_waitcnt lgkmcnt(14)
	v_mfma_f32_32x32x16_bf16 v[0:15], v[170:173], v[150:153], v[0:15]
	v_exp_f32_e32 v120, v120
	v_exp_f32_e32 v121, v121
	ds_read_b64_tr_b16 v[140:141], v212 offset:2048
	ds_read_b64_tr_b16 v[142:143], v212 offset:2560
	s_waitcnt lgkmcnt(14)
	v_mfma_f32_32x32x16_bf16 v[16:31], v[170:173], v[80:83], v[16:31]
	v_exp_f32_e32 v122, v122
	v_exp_f32_e32 v123, v123
	ds_read_b64_tr_b16 v[80:81], v212 offset:6144
	ds_read_b64_tr_b16 v[82:83], v212 offset:6656
	s_waitcnt lgkmcnt(14)
	v_mfma_f32_32x32x16_bf16 v[0:15], v[166:169], v[84:87], v[0:15]
	v_exp_f32_e32 v124, v124
	v_exp_f32_e32 v125, v125
	ds_read_b64_tr_b16 v[84:85], v212 offset:3072
	ds_read_b64_tr_b16 v[86:87], v212 offset:3584
	s_waitcnt lgkmcnt(14)
	v_mfma_f32_32x32x16_bf16 v[16:31], v[166:169], v[88:91], v[16:31]
	v_exp_f32_e32 v126, v126
	v_exp_f32_e32 v127, v127
	ds_read_b64_tr_b16 v[88:89], v212 offset:7168
	ds_read_b64_tr_b16 v[90:91], v212 offset:7680
	s_waitcnt lgkmcnt(14)
	v_mfma_f32_32x32x16_bf16 v[32:47], v[182:185], v[92:95], v[32:47]
	v_exp_f32_e32 v96, v96
	v_exp_f32_e32 v97, v97
	s_waitcnt lgkmcnt(12)
	v_mfma_f32_32x32x16_bf16 v[48:63], v[182:185], v[128:131], v[48:63]
	v_exp_f32_e32 v98, v98
	v_exp_f32_e32 v99, v99
	v_add_u32_e32 v128, s22, v215
	ds_read_b128 v[92:95], v128
	ds_read_b128 v[146:149], v128 offset:512
	s_waitcnt lgkmcnt(12)
	v_mfma_f32_32x32x16_bf16 v[32:47], v[178:181], v[132:135], v[32:47]
	v_exp_f32_e32 v100, v100
	v_exp_f32_e32 v101, v101
	ds_read_b128 v[150:153], v128 offset:2048
	ds_read_b128 v[154:157], v128 offset:2560
	s_waitcnt lgkmcnt(12)
	v_mfma_f32_32x32x16_bf16 v[48:63], v[178:181], v[136:139], v[48:63]
	v_exp_f32_e32 v102, v102
	v_exp_f32_e32 v103, v103
	ds_read_b128 v[194:197], v128 offset:4096
	ds_read_b128 v[198:201], v128 offset:4608
	s_waitcnt lgkmcnt(12)
	v_mfma_f32_32x32x16_bf16 v[32:47], v[170:173], v[140:143], v[32:47]
	v_exp_f32_e32 v104, v104
	v_exp_f32_e32 v105, v105
	ds_read_b128 v[202:205], v128 offset:6144
	ds_read_b128 v[206:209], v128 offset:6656
	s_waitcnt lgkmcnt(12)
	v_mfma_f32_32x32x16_bf16 v[48:63], v[170:173], v[80:83], v[48:63]
	v_exp_f32_e32 v106, v106
	v_exp_f32_e32 v107, v107
	s_waitcnt lgkmcnt(10)
	v_mfma_f32_32x32x16_bf16 v[32:47], v[166:169], v[84:87], v[32:47]
	v_exp_f32_e32 v108, v108
	v_exp_f32_e32 v109, v109
	s_waitcnt lgkmcnt(8)
	v_mfma_f32_32x32x16_bf16 v[48:63], v[166:169], v[88:91], v[48:63]
	v_exp_f32_e32 v110, v110
	v_exp_f32_e32 v111, v111
	s_waitcnt vmcnt(4) lgkmcnt(0)
	s_barrier
;   #define RESC() do{ if(resc){ asm volatile("s_waitcnt lgkmcnt(0)":::"memory"); \
;       _Pragma("unroll") for(int d_=0;d_<2;++d_) _Pragma("unroll") for(int r=0;r<16;++r)o[d_][r]*=wsf[crow(r,hi)]; } }while(0)
;   #define ROT() do{sl_prev=sl_cur;sl_cur=sl_next;sl_next=(sl_next==(NSLOT-1)*SLOTB)?0:sl_next+SLOTB;}while(0)
;   #define ENDW(tt) do{ if((tt)+3<NT){WAIT_BAR(3);} else if((tt)+2<NT){WAIT_BAR(2);} else {WAIT_BAR(0);} }while(0)
;   #define RESC() do{ if(resc){ asm volatile("s_waitcnt lgkmcnt(0)":::"memory"); \
;       _Pragma("unroll") for(int d_=0;d_<4;++d_) _Pragma("unroll") for(int r=0;r<16;++r)o[d_][r]*=wsf[crow(r,hi)]; } }while(0)
;   #define ROT() do{sl_prev=sl_cur;sl_cur=sl_next;sl_next=(sl_next==(NSLOT-1)*SLOTB)?0:sl_next+SLOTB;}while(0)
;   #define ENDW(tt) do{ if((tt)+3<NT){WAIT_BAR(5);} else if((tt)+2<NT){WAIT_BAR(4);} else {WAIT_BAR(0);} }while(0)
;   #define RESC() do{ if(resc){ asm volatile("s_waitcnt lgkmcnt(0)":::"memory"); \
;       _Pragma("unroll") for(int d_=0;d_<2;++d_) _Pragma("unroll") for(int r=0;r<16;++r)o[d_][r]*=wsf[crow(r,hi)]; } }while(0)
;   #define ROT() do{sl_prev=sl_cur;sl_cur=sl_next;sl_next=(sl_next==(NSLOT-1)*SLOTB)?0:sl_next+SLOTB;}while(0)
;   #define ENDW(tt) do{ if((tt)+3<NT){WAIT_BAR(3);} else if((tt)+2<NT){WAIT_BAR(2);} else {WAIT_BAR(0);} }while(0)
; template<int THRL,bool FIXED> __device__ __forceinline__ void attn_unit(int qb,const bf16*Qp,const bf16*__restrict__ Kh,const bf16*__restrict__ Vh,bf16*Op,int PO,char*shm,bool comb,float lam,const float*gsub,float gscale){
;     ...
;   for(;t+1<NT;t+=2){
;     STEP(pB0,pB1,pA0,pA1,t,(t+3<NT),(t+2<NT),(t+1<NT));       ENDW(t);   RESC(); ROT();
;     STEP(pA0,pA1,pB0,pB1,t+1,(t+4<NT),(t+3<NT),(t+2<NT));     ENDW(t+1); RESC(); ROT();
	s_add_i32 s3, s22, 0x2000
	s_cmpk_lg_i32 s22, 0x4000
	s_cselect_b32 s3, s3, 0
	v_add_u32_e32 v158, 0xc000, v214
	ds_read_b64_tr_b16 v[210:211], v214 offset:40960
	ds_read_b64_tr_b16 v[212:213], v214 offset:41472
	v_add_f32_e32 v80, v112, v113
	v_add_f32_e32 v80, v114, v80
	v_add_f32_e32 v80, v115, v80
	v_add_f32_e32 v80, v116, v80
	v_add_f32_e32 v80, v117, v80
	v_cvt_pk_bf16_f32 v182, v112, v113
	v_cvt_pk_bf16_f32 v183, v114, v115
	s_waitcnt lgkmcnt(9)
	v_mfma_f32_32x32x16_bf16 v[128:143], v[92:95], v[190:193], v[64:79]
	ds_read_b64_tr_b16 v[222:223], v214 offset:45056
	ds_read_b64_tr_b16 v[224:225], v214 offset:45568
	v_add_f32_e32 v80, v118, v80
	v_add_f32_e32 v80, v119, v80
	v_add_f32_e32 v80, v120, v80
	v_add_f32_e32 v112, v121, v80
	s_waitcnt lgkmcnt(10)
	v_mfma_f32_32x32x16_bf16 v[80:95], v[146:149], v[190:193], v[64:79]
	v_cvt_pk_bf16_f32 v184, v116, v117
	v_cvt_pk_bf16_f32 v185, v118, v119
	ds_read_b64_tr_b16 v[114:115], v214 offset:41984
	ds_read_b64_tr_b16 v[116:117], v214 offset:42496
	v_add_f32_e32 v112, v122, v112
	v_add_f32_e32 v112, v123, v112
	v_add_f32_e32 v112, v124, v112
	v_add_f32_e32 v112, v125, v112
	v_cvt_pk_bf16_f32 v178, v120, v121
	v_cvt_pk_bf16_f32 v179, v122, v123
	s_waitcnt lgkmcnt(11)
	v_mfma_f32_32x32x16_bf16 v[128:143], v[150:153], v[186:189], v[128:143]
	ds_read_b64_tr_b16 v[118:119], v214 offset:46080
	ds_read_b64_tr_b16 v[120:121], v214 offset:46592
	s_waitcnt lgkmcnt(12)
	v_mfma_f32_32x32x16_bf16 v[80:95], v[154:157], v[186:189], v[80:95]
	v_add_f32_e32 v112, v126, v112
	v_add_f32_e32 v112, v127, v112
	v_add_f32_e32 v112, v96, v112
	v_add_f32_e32 v112, v97, v112
	v_cvt_pk_bf16_f32 v180, v124, v125
	v_cvt_pk_bf16_f32 v181, v126, v127
	ds_read_b64_tr_b16 v[122:123], v214 offset:43008
	ds_read_b64_tr_b16 v[124:125], v214 offset:43520
	v_add_f32_e32 v112, v98, v112
	v_add_f32_e32 v112, v99, v112
	v_add_f32_e32 v112, v100, v112
	v_add_f32_e32 v112, v101, v112
	v_cvt_pk_bf16_f32 v170, v96, v97
	v_cvt_pk_bf16_f32 v171, v98, v99
	s_waitcnt lgkmcnt(13)
	v_mfma_f32_32x32x16_bf16 v[128:143], v[194:197], v[174:177], v[128:143]
	ds_read_b64_tr_b16 v[96:97], v214 offset:47104
	ds_read_b64_tr_b16 v[98:99], v214 offset:47616
	s_waitcnt lgkmcnt(14)
	v_mfma_f32_32x32x16_bf16 v[80:95], v[198:201], v[174:177], v[80:95]
	v_add_f32_e32 v112, v102, v112
	v_add_f32_e32 v112, v103, v112
	v_add_f32_e32 v112, v104, v112
	v_add_f32_e32 v112, v105, v112
	v_cvt_pk_bf16_f32 v172, v100, v101
	v_cvt_pk_bf16_f32 v173, v102, v103
	ds_read_b64_tr_b16 v[100:101], v214 offset:44032
	ds_read_b64_tr_b16 v[102:103], v214 offset:44544
	v_add_f32_e32 v112, v106, v112
	v_add_f32_e32 v112, v107, v112
	v_add_f32_e32 v112, v108, v112
	v_add_f32_e32 v112, v109, v112
	v_cvt_pk_bf16_f32 v166, v104, v105
	v_cvt_pk_bf16_f32 v167, v106, v107
	s_waitcnt lgkmcnt(14)
	v_mfma_f32_32x32x16_bf16 v[128:143], v[202:205], v[162:165], v[128:143]
	ds_read_b64_tr_b16 v[104:105], v214 offset:48128
	ds_read_b64_tr_b16 v[106:107], v214 offset:48640
	v_mfma_f32_32x32x16_bf16 v[80:95], v[206:209], v[162:165], v[80:95]
	v_add_f32_e32 v112, v110, v112
	v_add_f32_e32 v112, v111, v112
	v_add_f32_e32 v112, 0, v112
	v_cvt_pk_bf16_f32 v168, v108, v109
	v_cvt_pk_bf16_f32 v169, v110, v111
	s_nop 0
	v_add_f32_e32 v112, v144, v112
	s_waitcnt lgkmcnt(14)
	v_mfma_f32_32x32x16_bf16 v[0:15], v[182:185], v[210:213], v[0:15]
	v_exp_f32_e32 v128, v128
	v_exp_f32_e32 v129, v129
	ds_read_b64_tr_b16 v[108:109], v158
	ds_read_b64_tr_b16 v[110:111], v158 offset:512
	s_waitcnt lgkmcnt(14)
	v_mfma_f32_32x32x16_bf16 v[16:31], v[182:185], v[222:225], v[16:31]
	v_exp_f32_e32 v130, v130
	v_exp_f32_e32 v131, v131
	ds_read_b64_tr_b16 v[144:145], v158 offset:4096
	ds_read_b64_tr_b16 v[146:147], v158 offset:4608
	s_waitcnt lgkmcnt(14)
	v_mfma_f32_32x32x16_bf16 v[0:15], v[178:181], v[114:117], v[0:15]
	v_exp_f32_e32 v132, v132
	v_exp_f32_e32 v133, v133
	ds_read_b64_tr_b16 v[114:115], v158 offset:1024
	ds_read_b64_tr_b16 v[116:117], v158 offset:1536
	s_waitcnt lgkmcnt(14)
	v_mfma_f32_32x32x16_bf16 v[16:31], v[178:181], v[118:121], v[16:31]
	v_exp_f32_e32 v134, v134
	v_exp_f32_e32 v135, v135
	ds_read_b64_tr_b16 v[118:119], v158 offset:5120
	ds_read_b64_tr_b16 v[120:121], v158 offset:5632
	s_waitcnt lgkmcnt(14)
	v_mfma_f32_32x32x16_bf16 v[0:15], v[170:173], v[122:125], v[0:15]
	v_exp_f32_e32 v136, v136
	v_exp_f32_e32 v137, v137
	ds_read_b64_tr_b16 v[122:123], v158 offset:2048
	ds_read_b64_tr_b16 v[124:125], v158 offset:2560
	s_waitcnt lgkmcnt(14)
	v_mfma_f32_32x32x16_bf16 v[16:31], v[170:173], v[96:99], v[16:31]
	v_exp_f32_e32 v138, v138
	v_exp_f32_e32 v139, v139
	ds_read_b64_tr_b16 v[96:97], v158 offset:6144
	ds_read_b64_tr_b16 v[98:99], v158 offset:6656
	s_waitcnt lgkmcnt(14)
	v_mfma_f32_32x32x16_bf16 v[0:15], v[166:169], v[100:103], v[0:15]
	v_exp_f32_e32 v140, v140
	v_exp_f32_e32 v141, v141
	ds_read_b64_tr_b16 v[100:101], v158 offset:3072
	ds_read_b64_tr_b16 v[102:103], v158 offset:3584
	s_waitcnt lgkmcnt(14)
	v_mfma_f32_32x32x16_bf16 v[16:31], v[166:169], v[104:107], v[16:31]
	v_exp_f32_e32 v142, v142
	v_exp_f32_e32 v143, v143
	ds_read_b64_tr_b16 v[104:105], v158 offset:7168
	ds_read_b64_tr_b16 v[106:107], v158 offset:7680
	s_waitcnt lgkmcnt(14)
	v_mfma_f32_32x32x16_bf16 v[32:47], v[182:185], v[108:111], v[32:47]
	v_exp_f32_e32 v80, v80
	v_exp_f32_e32 v81, v81
	s_waitcnt lgkmcnt(12)
	v_mfma_f32_32x32x16_bf16 v[48:63], v[182:185], v[144:147], v[48:63]
	v_exp_f32_e32 v82, v82
	v_exp_f32_e32 v83, v83
	v_add_u32_e32 v108, s3, v215
	ds_read_b128 v[144:147], v108
	ds_read_b128 v[148:151], v108 offset:512
	s_waitcnt lgkmcnt(12)
	v_mfma_f32_32x32x16_bf16 v[32:47], v[178:181], v[114:117], v[32:47]
	v_exp_f32_e32 v84, v84
	v_exp_f32_e32 v85, v85
	ds_read_b128 v[114:117], v108 offset:2048
	ds_read_b128 v[152:155], v108 offset:2560
	s_waitcnt lgkmcnt(12)
	v_mfma_f32_32x32x16_bf16 v[48:63], v[178:181], v[118:121], v[48:63]
	v_exp_f32_e32 v86, v86
	v_exp_f32_e32 v87, v87
	ds_read_b128 v[118:121], v108 offset:4096
	ds_read_b128 v[156:159], v108 offset:4608
	s_waitcnt lgkmcnt(12)
	v_mfma_f32_32x32x16_bf16 v[32:47], v[170:173], v[122:125], v[32:47]
	v_exp_f32_e32 v88, v88
	v_exp_f32_e32 v89, v89
	ds_read_b128 v[122:125], v108 offset:6144
	ds_read_b128 v[194:197], v108 offset:6656
	s_waitcnt lgkmcnt(12)
	v_mfma_f32_32x32x16_bf16 v[48:63], v[170:173], v[96:99], v[48:63]
	v_exp_f32_e32 v90, v90
	v_exp_f32_e32 v91, v91
	s_waitcnt lgkmcnt(10)
	v_mfma_f32_32x32x16_bf16 v[32:47], v[166:169], v[100:103], v[32:47]
	v_exp_f32_e32 v92, v92
	v_exp_f32_e32 v93, v93
	s_waitcnt lgkmcnt(8)
	v_mfma_f32_32x32x16_bf16 v[48:63], v[166:169], v[104:107], v[48:63]
	v_exp_f32_e32 v94, v94
	v_exp_f32_e32 v95, v95
	s_waitcnt vmcnt(0) lgkmcnt(0)
	s_barrier
;   #define RESC() do{ if(resc){ asm volatile("s_waitcnt lgkmcnt(0)":::"memory"); \
;       _Pragma("unroll") for(int d_=0;d_<2;++d_) _Pragma("unroll") for(int r=0;r<16;++r)o[d_][r]*=wsf[crow(r,hi)]; } }while(0)
;   #define RESC() do{ if(resc){ asm volatile("s_waitcnt lgkmcnt(0)":::"memory"); \
;       _Pragma("unroll") for(int d_=0;d_<4;++d_) _Pragma("unroll") for(int r=0;r<16;++r)o[d_][r]*=wsf[crow(r,hi)]; } }while(0)
;   #define RESC() do{ if(resc){ asm volatile("s_waitcnt lgkmcnt(0)":::"memory"); \
;       _Pragma("unroll") for(int d_=0;d_<2;++d_) _Pragma("unroll") for(int r=0;r<16;++r)o[d_][r]*=wsf[crow(r,hi)]; } }while(0)
; template<int THRL,bool FIXED> __device__ __forceinline__ void attn_unit(int qb,const bf16*Qp,const bf16*__restrict__ Kh,const bf16*__restrict__ Vh,bf16*Op,int PO,char*shm,bool comb,float lam,const float*gsub,float gscale){
;     ...
;   STEP(pB0,pB1,pA0,pA1,NT-1,false,false,false); RESC();
	ds_read_b64_tr_b16 v[198:199], v214 offset:57344
	ds_read_b64_tr_b16 v[200:201], v214 offset:57856
	v_add_f32_e32 v96, v128, v129
	v_add_f32_e32 v96, v130, v96
	v_add_f32_e32 v96, v131, v96
	v_add_f32_e32 v96, v132, v96
	v_add_f32_e32 v113, v133, v96
	v_cvt_pk_bf16_f32 v182, v128, v129
	v_cvt_pk_bf16_f32 v183, v130, v131
	s_waitcnt lgkmcnt(9)
	v_mfma_f32_32x32x16_bf16 v[96:111], v[144:147], v[190:193], v[64:79]
	ds_read_b64_tr_b16 v[126:127], v214 offset:61440
	ds_read_b64_tr_b16 v[128:129], v214 offset:61952
	s_waitcnt lgkmcnt(10)
	v_mfma_f32_32x32x16_bf16 v[64:79], v[148:151], v[190:193], v[64:79]
	v_add_f32_e32 v113, v134, v113
	v_add_f32_e32 v113, v135, v113
	v_add_f32_e32 v113, v136, v113
	v_add_f32_e32 v113, v137, v113
	v_cvt_pk_bf16_f32 v184, v132, v133
	v_cvt_pk_bf16_f32 v185, v134, v135
	ds_read_b64_tr_b16 v[130:131], v214 offset:58368
	ds_read_b64_tr_b16 v[132:133], v214 offset:58880
	v_add_f32_e32 v113, v138, v113
	v_add_f32_e32 v113, v139, v113
	v_add_f32_e32 v113, v140, v113
	v_add_f32_e32 v113, v141, v113
	v_cvt_pk_bf16_f32 v178, v136, v137
	v_cvt_pk_bf16_f32 v179, v138, v139
	s_waitcnt lgkmcnt(11)
	v_mfma_f32_32x32x16_bf16 v[96:111], v[114:117], v[186:189], v[96:111]
	ds_read_b64_tr_b16 v[114:115], v214 offset:62464
	ds_read_b64_tr_b16 v[116:117], v214 offset:62976
	s_waitcnt lgkmcnt(12)
	v_mfma_f32_32x32x16_bf16 v[64:79], v[152:155], v[186:189], v[64:79]
	v_add_f32_e32 v113, v142, v113
	v_add_f32_e32 v113, v143, v113
	v_add_f32_e32 v113, v80, v113
	v_add_f32_e32 v113, v81, v113
	v_cvt_pk_bf16_f32 v180, v140, v141
	v_cvt_pk_bf16_f32 v181, v142, v143
	ds_read_b64_tr_b16 v[134:135], v214 offset:59392
	ds_read_b64_tr_b16 v[136:137], v214 offset:59904
	v_add_f32_e32 v113, v82, v113
	v_add_f32_e32 v113, v83, v113
	v_add_f32_e32 v113, v84, v113
	v_add_f32_e32 v113, v85, v113
	v_cvt_pk_bf16_f32 v170, v80, v81
	v_cvt_pk_bf16_f32 v171, v82, v83
	s_waitcnt lgkmcnt(13)
	v_mfma_f32_32x32x16_bf16 v[96:111], v[118:121], v[174:177], v[96:111]
	ds_read_b64_tr_b16 v[80:81], v214 offset:63488
	ds_read_b64_tr_b16 v[82:83], v214 offset:64000
	s_waitcnt lgkmcnt(14)
	v_mfma_f32_32x32x16_bf16 v[64:79], v[156:159], v[174:177], v[64:79]
	v_add_f32_e32 v113, v86, v113
	v_add_f32_e32 v113, v87, v113
	v_add_f32_e32 v113, v88, v113
	v_add_f32_e32 v113, v89, v113
	v_cvt_pk_bf16_f32 v172, v84, v85
	v_cvt_pk_bf16_f32 v173, v86, v87
	ds_read_b64_tr_b16 v[84:85], v214 offset:60416
	ds_read_b64_tr_b16 v[86:87], v214 offset:60928
	v_add_f32_e32 v113, v90, v113
	v_add_f32_e32 v113, v91, v113
	v_add_f32_e32 v113, v92, v113
	v_add_f32_e32 v113, v93, v113
	v_cvt_pk_bf16_f32 v166, v88, v89
	v_cvt_pk_bf16_f32 v167, v90, v91
	s_waitcnt lgkmcnt(14)
	v_mfma_f32_32x32x16_bf16 v[96:111], v[122:125], v[162:165], v[96:111]
	ds_read_b64_tr_b16 v[88:89], v214 offset:64512
	ds_read_b64_tr_b16 v[90:91], v214 offset:65024
	v_mfma_f32_32x32x16_bf16 v[64:79], v[194:197], v[162:165], v[64:79]
	v_add_f32_e32 v113, v94, v113
	v_add_f32_e32 v113, v95, v113
	v_add_f32_e32 v113, 0, v113
	v_cvt_pk_bf16_f32 v168, v92, v93
	v_cvt_pk_bf16_f32 v169, v94, v95
	s_waitcnt lgkmcnt(14)
	v_mfma_f32_32x32x16_bf16 v[0:15], v[182:185], v[198:201], v[0:15]
	s_nop 1
	v_exp_f32_e32 v96, v96
	v_exp_f32_e32 v97, v97
	ds_read_b64_tr_b16 v[92:93], v160
	ds_read_b64_tr_b16 v[94:95], v160 offset:512
	s_waitcnt lgkmcnt(14)
	v_mfma_f32_32x32x16_bf16 v[16:31], v[182:185], v[126:129], v[16:31]
	v_exp_f32_e32 v98, v98
	v_exp_f32_e32 v99, v99
	ds_read_b64_tr_b16 v[118:119], v160 offset:4096
	ds_read_b64_tr_b16 v[120:121], v160 offset:4608
	s_waitcnt lgkmcnt(14)
	v_mfma_f32_32x32x16_bf16 v[0:15], v[178:181], v[130:133], v[0:15]
	v_exp_f32_e32 v100, v100
	v_exp_f32_e32 v101, v101
	ds_read_b64_tr_b16 v[122:123], v160 offset:1024
	ds_read_b64_tr_b16 v[124:125], v160 offset:1536
	s_waitcnt lgkmcnt(14)
	v_mfma_f32_32x32x16_bf16 v[16:31], v[178:181], v[114:117], v[16:31]
	v_exp_f32_e32 v102, v102
	v_exp_f32_e32 v103, v103
	ds_read_b64_tr_b16 v[114:115], v160 offset:5120
	ds_read_b64_tr_b16 v[116:117], v160 offset:5632
	s_waitcnt lgkmcnt(14)
	v_mfma_f32_32x32x16_bf16 v[0:15], v[170:173], v[134:137], v[0:15]
	v_exp_f32_e32 v104, v104
	v_exp_f32_e32 v105, v105
	ds_read_b64_tr_b16 v[126:127], v160 offset:2048
	ds_read_b64_tr_b16 v[128:129], v160 offset:2560
	s_waitcnt lgkmcnt(14)
	v_mfma_f32_32x32x16_bf16 v[16:31], v[170:173], v[80:83], v[16:31]
	v_exp_f32_e32 v106, v106
	v_exp_f32_e32 v107, v107
	ds_read_b64_tr_b16 v[80:81], v160 offset:6144
	ds_read_b64_tr_b16 v[82:83], v160 offset:6656
	s_waitcnt lgkmcnt(14)
	v_mfma_f32_32x32x16_bf16 v[0:15], v[166:169], v[84:87], v[0:15]
	v_exp_f32_e32 v108, v108
	v_exp_f32_e32 v109, v109
	ds_read_b64_tr_b16 v[84:85], v160 offset:3072
	ds_read_b64_tr_b16 v[86:87], v160 offset:3584
	s_waitcnt lgkmcnt(14)
	v_mfma_f32_32x32x16_bf16 v[16:31], v[166:169], v[88:91], v[16:31]
	v_exp_f32_e32 v110, v110
	v_exp_f32_e32 v111, v111
	ds_read_b64_tr_b16 v[88:89], v160 offset:7168
	ds_read_b64_tr_b16 v[90:91], v160 offset:7680
	s_waitcnt lgkmcnt(14)
	v_mfma_f32_32x32x16_bf16 v[32:47], v[182:185], v[92:95], v[32:47]
	v_exp_f32_e32 v64, v64
	v_exp_f32_e32 v65, v65
	s_waitcnt lgkmcnt(12)
	v_mfma_f32_32x32x16_bf16 v[48:63], v[182:185], v[118:121], v[48:63]
	v_exp_f32_e32 v66, v66
	v_exp_f32_e32 v67, v67
	s_waitcnt lgkmcnt(10)
	v_mfma_f32_32x32x16_bf16 v[32:47], v[178:181], v[122:125], v[32:47]
	v_exp_f32_e32 v68, v68
	v_exp_f32_e32 v69, v69
	s_waitcnt lgkmcnt(8)
	v_mfma_f32_32x32x16_bf16 v[48:63], v[178:181], v[114:117], v[48:63]
	v_exp_f32_e32 v70, v70
	v_exp_f32_e32 v71, v71
	s_waitcnt lgkmcnt(6)
	v_mfma_f32_32x32x16_bf16 v[32:47], v[170:173], v[126:129], v[32:47]
	v_exp_f32_e32 v72, v72
	v_exp_f32_e32 v73, v73
	s_waitcnt lgkmcnt(4)
; #define SBAR() __builtin_amdgcn_sched_barrier(0)
;   #define PKW(P,B) cvtpk_s(P[B],P[B+1])
; #define SBAR() __builtin_amdgcn_sched_barrier(0)
;   #define PKW(P,B) cvtpk_s(P[B],P[B+1])
; #define SBAR() __builtin_amdgcn_sched_barrier(0)
;   #define PKW(P,B) cvtpk_s(P[B],P[B+1])
; __device__ __forceinline__ void pv(f32x16*o,int vb,bf16x8 pa0,bf16x8 pa1,bf16x8 pa2,bf16x8 pa3){
;   #pragma unroll
;   for(int d0=0;d0<4;++d0){s16x4 lo[4],hi[4];
;     #pragma unroll
;     for(int ks=0;ks<4;++ks){
;       asm volatile("ds_read_b64_tr_b16 %0,%1 offset:%c2":"=&v"(lo[ks]):"v"(vb),"i"(d0*4096+ks*1024):"memory");
;       asm volatile("ds_read_b64_tr_b16 %0,%1 offset:%c2":"=&v"(hi[ks]):"v"(vb),"i"(d0*4096+ks*1024+512):"memory");}
;     asm volatile("s_waitcnt lgkmcnt(0)":::"memory");SBAR();
;     ...
;     o[d0]=__builtin_amdgcn_mfma_f32_32x32x16_bf16(pa0,PK(0),o[d0],0,0,0);
;     o[d0]=__builtin_amdgcn_mfma_f32_32x32x16_bf16(pa1,PK(1),o[d0],0,0,0);
;     o[d0]=__builtin_amdgcn_mfma_f32_32x32x16_bf16(pa2,PK(2),o[d0],0,0,0);
;     o[d0]=__builtin_amdgcn_mfma_f32_32x32x16_bf16(pa3,PK(3),o[d0],0,0,0);
;     ...
;   }
; template<int THRL,bool FIXED> __device__ __forceinline__ void attn_unit(int qb,const bf16*Qp,const bf16*__restrict__ Kh,const bf16*__restrict__ Vh,bf16*Op,int PO,char*shm,bool comb,float lam,const float*gsub,float gscale){
;     ...
;   { float sacc=pB0[0]+pB0[1]; _Pragma("unroll") for(int r=2;r<16;++r)sacc+=pB0[r]; _Pragma("unroll") for(int r=0;r<16;++r)sacc+=pB1[r]; l_reg+=sacc;
;     pw0=(u32x4){PKW(pB0,0),PKW(pB0,2),PKW(pB0,4),PKW(pB0,6)};pw1=(u32x4){PKW(pB0,8),PKW(pB0,10),PKW(pB0,12),PKW(pB0,14)};pw2=(u32x4){PKW(pB1,0),PKW(pB1,2),PKW(pB1,4),PKW(pB1,6)};pw3=(u32x4){PKW(pB1,8),PKW(pB1,10),PKW(pB1,12),PKW(pB1,14)};
;     SBAR(); pv(o,vb0+VSL(NT-1),PAF(0),PAF(1),PAF(2),PAF(3)); }
;   asm volatile("s_waitcnt lgkmcnt(0)\n\ts_barrier":::"memory");
	v_mfma_f32_32x32x16_bf16 v[48:63], v[170:173], v[80:83], v[48:63]
	v_exp_f32_e32 v74, v74
	v_exp_f32_e32 v75, v75
	s_waitcnt lgkmcnt(2)
	v_mfma_f32_32x32x16_bf16 v[32:47], v[166:169], v[84:87], v[32:47]
	v_exp_f32_e32 v76, v76
	v_exp_f32_e32 v77, v77
	s_waitcnt lgkmcnt(0)
	v_mfma_f32_32x32x16_bf16 v[48:63], v[166:169], v[88:91], v[48:63]
	v_exp_f32_e32 v78, v78
	v_exp_f32_e32 v79, v79
	v_add_f32_e32 v80, v96, v97
	v_add_f32_e32 v80, v98, v80
	v_add_f32_e32 v80, v99, v80
	v_add_f32_e32 v80, v100, v80
	v_add_f32_e32 v80, v101, v80
	v_add_f32_e32 v80, v102, v80
	v_add_f32_e32 v80, v103, v80
	v_add_f32_e32 v80, v104, v80
	v_add_f32_e32 v80, v105, v80
	v_add_f32_e32 v80, v106, v80
	v_add_f32_e32 v80, v107, v80
	v_add_f32_e32 v80, v108, v80
	v_add_f32_e32 v80, v109, v80
	v_add_f32_e32 v80, v110, v80
	v_add_f32_e32 v80, v111, v80
	v_add_f32_e32 v80, v80, v64
	v_add_f32_e32 v80, v65, v80
	v_add_f32_e32 v80, v66, v80
	v_add_f32_e32 v80, v67, v80
	v_add_f32_e32 v80, v68, v80
	v_add_f32_e32 v80, v69, v80
	v_add_f32_e32 v80, v70, v80
	v_add_f32_e32 v80, v71, v80
	v_add_f32_e32 v80, v72, v80
	v_add_f32_e32 v80, v73, v80
	v_add_f32_e32 v80, v74, v80
	v_add_f32_e32 v80, v75, v80
	v_add_f32_e32 v80, v76, v80
	v_add_f32_e32 v80, v77, v80
	v_add_f32_e32 v80, v78, v80
	v_add_f32_e32 v80, v79, v80
	v_add_f32_e32 v81, v112, v113
	v_add_f32_e32 v80, v81, v80
	v_cvt_pk_bf16_f32 v64, v64, v65
	v_cvt_pk_bf16_f32 v82, v96, v97
	v_cvt_pk_bf16_f32 v83, v98, v99
	v_cvt_pk_bf16_f32 v84, v100, v101
	v_cvt_pk_bf16_f32 v85, v102, v103
	v_cvt_pk_bf16_f32 v86, v104, v105
	v_cvt_pk_bf16_f32 v87, v106, v107
	v_cvt_pk_bf16_f32 v88, v108, v109
	v_cvt_pk_bf16_f32 v89, v110, v111
	v_cvt_pk_bf16_f32 v65, v66, v67
	v_cvt_pk_bf16_f32 v66, v68, v69
	v_cvt_pk_bf16_f32 v67, v70, v71
	v_cvt_pk_bf16_f32 v68, v72, v73
	v_cvt_pk_bf16_f32 v69, v74, v75
	v_cvt_pk_bf16_f32 v70, v76, v77
	v_cvt_pk_bf16_f32 v71, v78, v79
	v_add_u32_e32 v72, s29, v236
	v_add3_u32 v81, v72, v237, v240
	ds_read_b64_tr_b16 v[72:73],v81 offset:0
	ds_read_b64_tr_b16 v[74:75],v81 offset:512
	ds_read_b64_tr_b16 v[76:77],v81 offset:1024
	ds_read_b64_tr_b16 v[78:79],v81 offset:1536
	ds_read_b64_tr_b16 v[90:91],v81 offset:2048
	ds_read_b64_tr_b16 v[92:93],v81 offset:2560
	ds_read_b64_tr_b16 v[94:95],v81 offset:3072
	ds_read_b64_tr_b16 v[96:97],v81 offset:3584
	s_waitcnt lgkmcnt(0)
	s_nop 0
	v_mfma_f32_32x32x16_bf16 v[0:15], v[82:85], v[72:75], v[0:15]
	ds_read_b64_tr_b16 v[72:73],v81 offset:4096
	ds_read_b64_tr_b16 v[74:75],v81 offset:4608
	v_mfma_f32_32x32x16_bf16 v[0:15], v[86:89], v[76:79], v[0:15]
	ds_read_b64_tr_b16 v[76:77],v81 offset:5120
	ds_read_b64_tr_b16 v[78:79],v81 offset:5632
	v_mfma_f32_32x32x16_bf16 v[0:15], v[64:67], v[90:93], v[0:15]
	ds_read_b64_tr_b16 v[90:91],v81 offset:6144
	ds_read_b64_tr_b16 v[92:93],v81 offset:6656
	v_mfma_f32_32x32x16_bf16 v[0:15], v[68:71], v[94:97], v[0:15]
	ds_read_b64_tr_b16 v[94:95],v81 offset:7168
	ds_read_b64_tr_b16 v[96:97],v81 offset:7680
	s_waitcnt lgkmcnt(0)
	v_mfma_f32_32x32x16_bf16 v[16:31], v[82:85], v[72:75], v[16:31]
	ds_read_b64_tr_b16 v[72:73],v81 offset:8192
	ds_read_b64_tr_b16 v[74:75],v81 offset:8704
	v_mfma_f32_32x32x16_bf16 v[16:31], v[86:89], v[76:79], v[16:31]
	ds_read_b64_tr_b16 v[76:77],v81 offset:9216
	ds_read_b64_tr_b16 v[78:79],v81 offset:9728
	v_mfma_f32_32x32x16_bf16 v[16:31], v[64:67], v[90:93], v[16:31]
	ds_read_b64_tr_b16 v[90:91],v81 offset:10240
	ds_read_b64_tr_b16 v[92:93],v81 offset:10752
	v_mfma_f32_32x32x16_bf16 v[16:31], v[68:71], v[94:97], v[16:31]
	ds_read_b64_tr_b16 v[94:95],v81 offset:11264
	ds_read_b64_tr_b16 v[96:97],v81 offset:11776
	s_waitcnt lgkmcnt(0)
	v_mfma_f32_32x32x16_bf16 v[32:47], v[82:85], v[72:75], v[32:47]
	ds_read_b64_tr_b16 v[72:73],v81 offset:12288
	ds_read_b64_tr_b16 v[74:75],v81 offset:12800
	v_mfma_f32_32x32x16_bf16 v[32:47], v[86:89], v[76:79], v[32:47]
	ds_read_b64_tr_b16 v[76:77],v81 offset:13312
	ds_read_b64_tr_b16 v[78:79],v81 offset:13824
	v_mfma_f32_32x32x16_bf16 v[32:47], v[64:67], v[90:93], v[32:47]
	ds_read_b64_tr_b16 v[90:91],v81 offset:14336
	ds_read_b64_tr_b16 v[92:93],v81 offset:14848
	v_mfma_f32_32x32x16_bf16 v[32:47], v[68:71], v[94:97], v[32:47]
	ds_read_b64_tr_b16 v[94:95],v81 offset:15360
	ds_read_b64_tr_b16 v[96:97],v81 offset:15872
	s_waitcnt lgkmcnt(0)
	v_mfma_f32_32x32x16_bf16 v[48:63], v[82:85], v[72:75], v[48:63]
	s_waitcnt lgkmcnt(0)
	s_barrier
; __device__ __forceinline__ int crow(int r,int hi){return (r&3)+8*(r>>2)+4*hi;}
; __device__ __forceinline__ int crow(int r,int hi){return (r&3)+8*(r>>2)+4*hi;}
; template<int THRL,bool FIXED> __device__ __forceinline__ void attn_unit(int qb,const bf16*Qp,const bf16*__restrict__ Kh,const bf16*__restrict__ Vh,bf16*Op,int PO,char*shm,bool comb,float lam,const float*gsub,float gscale){
;     ...
;   {auto rr=__builtin_amdgcn_permlane32_swap(__float_as_uint(l_reg),__float_as_uint(l_reg),false,false);l_reg=__uint_as_float(rr[0])+__uint_as_float(rr[1]);}
;   if(hi==0)wsf[32+r32]=l_reg;asm volatile("s_waitcnt lgkmcnt(0)":::"memory");
;   float rli[16];
;   #pragma unroll
;   for(int r=0;r<16;++r)rli[r]=__builtin_amdgcn_rcpf(wsf[32+crow(r,hi)]);
;   bf16*Ow=Op+(long)(q0+wid*QBLK)*PO;
;   { bf16*stg=(bf16*)(shm+LDS_OST)+wid*4096;
;     #pragma unroll
;     for(int r=0;r<16;++r){const int orow=crow(r,hi);
;       #pragma unroll
;       for(int d0=0;d0<4;++d0)stg[orow*128+d0*32+r32]=__float2bfloat16(o[d0][r]*rli[r]);}
	v_cmp_gt_u32_e32 vcc, 32, v234
	v_mfma_f32_32x32x16_bf16 v[48:63], v[86:89], v[76:79], v[48:63]
	v_mfma_f32_32x32x16_bf16 v[48:63], v[64:67], v[90:93], v[48:63]
	v_mov_b32_e32 v64, v80
	s_nop 1
	v_permlane32_swap_b32_e32 v80, v64
	v_mfma_f32_32x32x16_bf16 v[48:63], v[68:71], v[94:97], v[48:63]
	s_and_saveexec_b64 s[66:67], vcc
	v_lshl_add_u32 v65, v232, 2, s28
	v_add_f32_e32 v64, v80, v64
	ds_write_b32 v65, v64 offset:128
	s_or_b64 exec, exec, s[66:67]
	s_waitcnt lgkmcnt(0)
	v_lshl_add_u32 v72, v233, 4, s28
	ds_read_b128 v[64:67], v72 offset:128
	ds_read_b128 v[68:71], v72 offset:160
	s_lshl_b32 s3, s77, 13
	s_add_i32 s3, s3, 0
	s_lshl_b64 s[64:65], s[64:65], 11
	s_waitcnt lgkmcnt(1)
	v_rcp_f32_e32 v73, v64
	v_rcp_f32_e32 v74, v65
	v_rcp_f32_e32 v75, v66
	v_rcp_f32_e32 v76, v67
	s_waitcnt lgkmcnt(0)
	v_rcp_f32_e32 v77, v68
	ds_read_b128 v[64:67], v72 offset:192
	v_rcp_f32_e32 v78, v69
	v_rcp_f32_e32 v79, v70
	v_rcp_f32_e32 v80, v71
	ds_read_b128 v[68:71], v72 offset:224
	v_lshlrev_b32_e32 v72, 1, v232
	v_mul_f32_e32 v0, v0, v73
	v_add3_u32 v72, s3, v235, v72
	v_cvt_pk_bf16_f32 v0, v0, s0
	ds_write_b16 v72, v0
	v_mul_f32_e32 v0, v16, v73
	v_cvt_pk_bf16_f32 v0, v0, s0
	ds_write_b16 v72, v0 offset:64
	v_mul_f32_e32 v0, v32, v73
	v_cvt_pk_bf16_f32 v0, v0, s0
	ds_write_b16 v72, v0 offset:128
	v_mul_f32_e32 v0, v48, v73
	v_cvt_pk_bf16_f32 v0, v0, s0
	ds_write_b16 v72, v0 offset:192
	v_mul_f32_e32 v0, v1, v74
	v_cvt_pk_bf16_f32 v0, v0, s0
	ds_write_b16 v72, v0 offset:256
	v_mul_f32_e32 v0, v17, v74
	v_cvt_pk_bf16_f32 v0, v0, s0
	ds_write_b16 v72, v0 offset:320
	v_mul_f32_e32 v0, v33, v74
	v_cvt_pk_bf16_f32 v0, v0, s0
	ds_write_b16 v72, v0 offset:384
	v_mul_f32_e32 v0, v49, v74
	v_cvt_pk_bf16_f32 v0, v0, s0
	ds_write_b16 v72, v0 offset:448
	v_mul_f32_e32 v0, v2, v75
	v_cvt_pk_bf16_f32 v0, v0, s0
	ds_write_b16 v72, v0 offset:512
	v_mul_f32_e32 v0, v18, v75
	v_cvt_pk_bf16_f32 v0, v0, s0
	ds_write_b16 v72, v0 offset:576
	v_mul_f32_e32 v0, v34, v75
	v_cvt_pk_bf16_f32 v0, v0, s0
	ds_write_b16 v72, v0 offset:640
	v_mul_f32_e32 v0, v50, v75
	v_cvt_pk_bf16_f32 v0, v0, s0
	ds_write_b16 v72, v0 offset:704
	v_mul_f32_e32 v0, v3, v76
	v_cvt_pk_bf16_f32 v0, v0, s0
	ds_write_b16 v72, v0 offset:768
	v_mul_f32_e32 v0, v19, v76
	v_cvt_pk_bf16_f32 v0, v0, s0
	ds_write_b16 v72, v0 offset:832
	v_mul_f32_e32 v0, v35, v76
	v_cvt_pk_bf16_f32 v0, v0, s0
	ds_write_b16 v72, v0 offset:896
	v_mul_f32_e32 v0, v51, v76
	v_cvt_pk_bf16_f32 v0, v0, s0
	ds_write_b16 v72, v0 offset:960
	v_mul_f32_e32 v0, v4, v77
	v_cvt_pk_bf16_f32 v0, v0, s0
	ds_write_b16 v72, v0 offset:2048
	v_mul_f32_e32 v0, v20, v77
	v_cvt_pk_bf16_f32 v0, v0, s0
	ds_write_b16 v72, v0 offset:2112
	v_mul_f32_e32 v0, v36, v77
	v_cvt_pk_bf16_f32 v0, v0, s0
	ds_write_b16 v72, v0 offset:2176
	v_mul_f32_e32 v0, v52, v77
	v_cvt_pk_bf16_f32 v0, v0, s0
	ds_write_b16 v72, v0 offset:2240
	v_mul_f32_e32 v0, v5, v78
	v_cvt_pk_bf16_f32 v0, v0, s0
	ds_write_b16 v72, v0 offset:2304
	v_mul_f32_e32 v0, v21, v78
	v_cvt_pk_bf16_f32 v0, v0, s0
	ds_write_b16 v72, v0 offset:2368
	v_mul_f32_e32 v0, v37, v78
	v_cvt_pk_bf16_f32 v0, v0, s0
	ds_write_b16 v72, v0 offset:2432
	v_mul_f32_e32 v0, v53, v78
	v_cvt_pk_bf16_f32 v0, v0, s0
	ds_write_b16 v72, v0 offset:2496
	v_mul_f32_e32 v0, v6, v79
	v_cvt_pk_bf16_f32 v0, v0, s0
	ds_write_b16 v72, v0 offset:2560
	v_mul_f32_e32 v0, v22, v79
	v_cvt_pk_bf16_f32 v0, v0, s0
	ds_write_b16 v72, v0 offset:2624
	v_mul_f32_e32 v0, v38, v79
	v_cvt_pk_bf16_f32 v0, v0, s0
	ds_write_b16 v72, v0 offset:2688
	v_mul_f32_e32 v0, v54, v79
	v_cvt_pk_bf16_f32 v0, v0, s0
	ds_write_b16 v72, v0 offset:2752
	v_mul_f32_e32 v0, v7, v80
	v_cvt_pk_bf16_f32 v0, v0, s0
	ds_write_b16 v72, v0 offset:2816
	v_mul_f32_e32 v0, v23, v80
	v_cvt_pk_bf16_f32 v0, v0, s0
	s_waitcnt lgkmcnt(14)
; __device__ __forceinline__ int crow(int r,int hi){return (r&3)+8*(r>>2)+4*hi;}
; __device__ __forceinline__ int crow(int r,int hi){return (r&3)+8*(r>>2)+4*hi;}
; template<int THRL,bool FIXED> __device__ __forceinline__ void attn_unit(int qb,const bf16*Qp,const bf16*__restrict__ Kh,const bf16*__restrict__ Vh,bf16*Op,int PO,char*shm,bool comb,float lam,const float*gsub,float gscale){
;     ...
;     for(int r=0;r<16;++r){const int orow=crow(r,hi);
;       #pragma unroll
;       for(int d0=0;d0<4;++d0)stg[orow*128+d0*32+r32]=__float2bfloat16(o[d0][r]*rli[r]);}
;     asm volatile("s_waitcnt lgkmcnt(0)":::"memory");
;     if(!comb){
;       #pragma unroll
;       for(int i=0;i<8;++i){const int row=i*4+(lane>>4),ch=lane&15; const u32x4 v=*(const u32x4*)(stg+row*128+ch*8); ATTN_STORE16(Ow+(long)row*PO+ch*8,v);}
	v_rcp_f32_e32 v64, v64
	ds_write_b16 v72, v0 offset:2880
	v_mul_f32_e32 v0, v39, v80
	v_cvt_pk_bf16_f32 v0, v0, s0
	ds_write_b16 v72, v0 offset:2944
	v_mul_f32_e32 v0, v55, v80
	v_cvt_pk_bf16_f32 v0, v0, s0
	ds_write_b16 v72, v0 offset:3008
	v_mul_f32_e32 v0, v8, v64
	v_cvt_pk_bf16_f32 v0, v0, s0
	ds_write_b16 v72, v0 offset:4096
	v_mul_f32_e32 v0, v24, v64
	v_cvt_pk_bf16_f32 v0, v0, s0
	v_rcp_f32_e32 v65, v65
	ds_write_b16 v72, v0 offset:4160
	v_mul_f32_e32 v0, v40, v64
	v_cvt_pk_bf16_f32 v0, v0, s0
	ds_write_b16 v72, v0 offset:4224
	v_mul_f32_e32 v0, v56, v64
	v_cvt_pk_bf16_f32 v0, v0, s0
	ds_write_b16 v72, v0 offset:4288
	v_mul_f32_e32 v0, v9, v65
	v_cvt_pk_bf16_f32 v0, v0, s0
	ds_write_b16 v72, v0 offset:4352
	v_mul_f32_e32 v0, v25, v65
	v_cvt_pk_bf16_f32 v0, v0, s0
	v_rcp_f32_e32 v66, v66
	ds_write_b16 v72, v0 offset:4416
	v_mul_f32_e32 v0, v41, v65
	v_cvt_pk_bf16_f32 v0, v0, s0
	ds_write_b16 v72, v0 offset:4480
	v_mul_f32_e32 v0, v57, v65
	v_cvt_pk_bf16_f32 v0, v0, s0
	ds_write_b16 v72, v0 offset:4544
	v_mul_f32_e32 v0, v10, v66
	v_cvt_pk_bf16_f32 v0, v0, s0
	ds_write_b16 v72, v0 offset:4608
	v_mul_f32_e32 v0, v26, v66
	v_cvt_pk_bf16_f32 v0, v0, s0
	v_rcp_f32_e32 v67, v67
	ds_write_b16 v72, v0 offset:4672
	v_mul_f32_e32 v0, v42, v66
	v_cvt_pk_bf16_f32 v0, v0, s0
	ds_write_b16 v72, v0 offset:4736
	v_mul_f32_e32 v0, v58, v66
	v_cvt_pk_bf16_f32 v0, v0, s0
	ds_write_b16 v72, v0 offset:4800
	v_mul_f32_e32 v0, v11, v67
	v_cvt_pk_bf16_f32 v0, v0, s0
	ds_write_b16 v72, v0 offset:4864
	v_mul_f32_e32 v0, v27, v67
	v_cvt_pk_bf16_f32 v0, v0, s0
	v_rcp_f32_e32 v68, v68
	ds_write_b16 v72, v0 offset:4928
	v_mul_f32_e32 v0, v43, v67
	v_cvt_pk_bf16_f32 v0, v0, s0
	ds_write_b16 v72, v0 offset:4992
	v_mul_f32_e32 v0, v59, v67
	v_cvt_pk_bf16_f32 v0, v0, s0
	ds_write_b16 v72, v0 offset:5056
	v_mul_f32_e32 v0, v12, v68
	v_cvt_pk_bf16_f32 v0, v0, s0
	ds_write_b16 v72, v0 offset:6144
	v_mul_f32_e32 v0, v28, v68
	v_cvt_pk_bf16_f32 v0, v0, s0
	v_rcp_f32_e32 v69, v69
	ds_write_b16 v72, v0 offset:6208
	v_mul_f32_e32 v0, v44, v68
	v_cvt_pk_bf16_f32 v0, v0, s0
	ds_write_b16 v72, v0 offset:6272
	v_mul_f32_e32 v0, v60, v68
	v_cvt_pk_bf16_f32 v0, v0, s0
	ds_write_b16 v72, v0 offset:6336
	v_mul_f32_e32 v0, v13, v69
	v_cvt_pk_bf16_f32 v0, v0, s0
	ds_write_b16 v72, v0 offset:6400
	v_mul_f32_e32 v0, v29, v69
	v_cvt_pk_bf16_f32 v0, v0, s0
	v_rcp_f32_e32 v70, v70
	ds_write_b16 v72, v0 offset:6464
	v_mul_f32_e32 v0, v45, v69
	v_cvt_pk_bf16_f32 v0, v0, s0
	ds_write_b16 v72, v0 offset:6528
	v_mul_f32_e32 v0, v61, v69
	v_cvt_pk_bf16_f32 v0, v0, s0
	ds_write_b16 v72, v0 offset:6592
	v_mul_f32_e32 v0, v14, v70
	v_cvt_pk_bf16_f32 v0, v0, s0
	ds_write_b16 v72, v0 offset:6656
	v_mul_f32_e32 v0, v30, v70
	v_cvt_pk_bf16_f32 v0, v0, s0
	v_rcp_f32_e32 v71, v71
	ds_write_b16 v72, v0 offset:6720
	v_mul_f32_e32 v0, v46, v70
	v_cvt_pk_bf16_f32 v0, v0, s0
	ds_write_b16 v72, v0 offset:6784
	v_mul_f32_e32 v0, v62, v70
	v_cvt_pk_bf16_f32 v0, v0, s0
	ds_write_b16 v72, v0 offset:6848
	v_mul_f32_e32 v0, v15, v71
	v_cvt_pk_bf16_f32 v0, v0, s0
	ds_write_b16 v72, v0 offset:6912
	v_mul_f32_e32 v0, v31, v71
	v_cvt_pk_bf16_f32 v0, v0, s0
	ds_write_b16 v72, v0 offset:6976
	v_mul_f32_e32 v0, v47, v71
	v_cvt_pk_bf16_f32 v0, v0, s0
	ds_write_b16 v72, v0 offset:7040
	v_mul_f32_e32 v0, v63, v71
	v_cvt_pk_bf16_f32 v0, v0, s0
	ds_write_b16 v72, v0 offset:7104
	s_waitcnt lgkmcnt(0)
	s_add_u32 s64, s72, s64
	v_lshlrev_b32_e32 v6, 3, v231
	v_or_b32_e32 v28, 4, v230
	v_or_b32_e32 v60, 8, v230
	v_or_b32_e32 v59, 12, v230
	v_or_b32_e32 v58, 16, v230
	v_or_b32_e32 v57, 20, v230
	v_or_b32_e32 v56, 24, v230
	s_addc_u32 s65, s73, s65
	s_mov_b64 s[66:67], -1
	s_andn2_b64 vcc, exec, s[12:13]
	v_lshlrev_b32_e32 v4, 11, v230
	v_lshlrev_b32_e32 v160, 1, v6
	v_lshlrev_b32_e32 v52, 11, v28
	v_lshlrev_b32_e32 v50, 11, v60
	v_lshlrev_b32_e32 v48, 11, v59
	v_lshlrev_b32_e32 v46, 11, v58
	v_lshlrev_b32_e32 v42, 11, v57
	v_lshlrev_b32_e32 v40, 11, v56
	v_or_b32_e32 v54, 28, v230
	s_cbranch_vccnz .LBB0_555
	v_add_u32_e32 v7, s3, v160
	v_lshl_add_u32 v0, v230, 8, v7
	ds_read_b128 v[0:3], v0
	v_lshl_add_u64 v[8:9], s[64:65], 0, v[160:161]
	v_mov_b32_e32 v5, v161
	v_lshl_add_u64 v[10:11], v[8:9], 0, v[4:5]
	v_mov_b32_e32 v53, v161
	s_waitcnt lgkmcnt(0)
	global_store_dwordx4 v[10:11], v[0:3], off offset:1024
	v_lshl_add_u64 v[10:11], v[8:9], 0, v[52:53]
	v_mov_b32_e32 v51, v161
	v_lshl_add_u32 v0, v28, 8, v7
	ds_read_b128 v[0:3], v0
	v_mov_b32_e32 v49, v161
	v_mov_b32_e32 v47, v161
	v_mov_b32_e32 v43, v161
	v_mov_b32_e32 v41, v161
	s_waitcnt lgkmcnt(0)
	global_store_dwordx4 v[10:11], v[0:3], off offset:1024
	v_lshl_add_u64 v[10:11], v[8:9], 0, v[50:51]
	v_or_b32_e32 v5, 28, v230
	v_lshl_add_u32 v0, v60, 8, v7
	ds_read_b128 v[0:3], v0
	s_mov_b64 s[66:67], 0
	s_waitcnt lgkmcnt(0)
	global_store_dwordx4 v[10:11], v[0:3], off offset:1024
	s_nop 1
	v_lshl_add_u32 v0, v59, 8, v7
	ds_read_b128 v[0:3], v0
	v_lshl_add_u64 v[10:11], v[8:9], 0, v[48:49]
	s_waitcnt lgkmcnt(0)
	global_store_dwordx4 v[10:11], v[0:3], off offset:1024
	s_nop 1
	v_lshl_add_u32 v0, v58, 8, v7
	ds_read_b128 v[0:3], v0
	v_lshl_add_u64 v[10:11], v[8:9], 0, v[46:47]
	s_waitcnt lgkmcnt(0)
	global_store_dwordx4 v[10:11], v[0:3], off offset:1024
	s_nop 1
	v_lshl_add_u32 v0, v57, 8, v7
	ds_read_b128 v[0:3], v0
	v_lshl_add_u64 v[10:11], v[8:9], 0, v[42:43]
	v_lshl_add_u64 v[8:9], v[8:9], 0, v[40:41]
	s_waitcnt lgkmcnt(0)
	global_store_dwordx4 v[10:11], v[0:3], off offset:1024
	s_nop 1
	v_lshl_add_u32 v0, v56, 8, v7
	ds_read_b128 v[0:3], v0
	s_waitcnt lgkmcnt(0)
	global_store_dwordx4 v[8:9], v[0:3], off offset:1024
	s_nop 1
	v_lshl_add_u32 v0, v5, 8, v7
	ds_read_b128 v[0:3], v0
